# mix/xo/down GEMM epilogues: stats+src loads prefetched 2 row-blocks ahead, LN gamma/beta staged in wave-private LDS
# speedup vs baseline: 1.0332x; 1.0173x over previous
;     __device__ __forceinline__ void operator()(int row, int col, f32x4 v, int, float&, float&) const { *(u32x2*)(O + (size_t)row * ldc + col) = pk4(v * s); }
; __device__ __forceinline__ void stats_main(const float* stm, int row, int fq, float& mu, float& rs) {
;     const f32x4* p = (const f32x4*)(stm + (size_t)row * 32 + fq * 8);
;     const f32x4 a = p[0], b = p[1];
;     float s1 = (a.x + a.z) + (b.x + b.z), s2 = (a.y + a.w) + (b.y + b.w);
;     s1 += __shfl_xor(s1, 16); s2 += __shfl_xor(s2, 16); s1 += __shfl_xor(s1, 32); s2 += __shfl_xor(s2, 32);
;     mu = s1 * (1.f / DM); rs = __builtin_amdgcn_rsqf(fmaxf(s2 * (1.f / DM) - mu * mu, 0.f) + LN_EPS);
; }
;     __device__ __forceinline__ void operator()(const f32x4 (&acc)[2][2][4][2], const pg8::Unit& u, int wr, int wc, int fr, int fq) const {
; #pragma unroll
;         for (int ai = 0; ai < 2; ++ai)
; #pragma unroll
;             for (int m = 0; m < 4; ++m) {
;                 const int row = u.pm * 256 + ai * 128 + wr * 64 + m * 16 + fr;
;                 float mu = 0.f, rs = 1.f; if (ln) stats_main(stm_p, row, fq, mu, rs);
.LBB0_1836:
	v_readlane_b32 s80, v251, 34
	v_readlane_b32 s81, v251, 35
	v_readlane_b32 s98, v251, 36
	v_readlane_b32 s99, v251, 37
	v_and_b32_e32 v244, 0xfffffff0, v162
	v_lshl_add_u32 v244, s23, 8, v244
	v_and_b32_e32 v245, 31, v219
	v_add_u32_e32 v244, v244, v245
	v_lshrrev_b32_e32 v245, 5, v219
	v_lshl_add_u32 v244, v245, 7, v244
	v_lshlrev_b32_e32 v244, 2, v244
	global_load_dword v214, v244, s[80:81]
	global_load_dword v215, v244, s[98:99]
	v_lshl_add_u32 v245, s29, 8, v160
	v_lshl_add_u32 v244, s23, 8, v162
	v_lshlrev_b32_e32 v242, 11, v245
	v_lshl_add_u32 v242, v244, 1, v242
	v_lshlrev_b32_e32 v246, 7, v245
	v_mov_b32_e32 v247, 0
	v_lshlrev_b32_e32 v248, 7, v245
	v_mov_b32_e32 v249, 0
	v_add_u32_e32 v246, 0x1000, v246
	v_add_u32_e32 v248, 0x5000, v248
	v_lshl_add_u64 v[246:247], v[246:247], 0, v[134:135]
	v_lshl_add_u64 v[248:249], v[248:249], 0, v[134:135]
	global_load_dwordx4 v[190:193], v[246:247], off offset:-4080
	global_load_dwordx4 v[194:197], v[246:247], off offset:-4096
	global_load_dwordx2 v[198:199], v242, s[46:47]
	global_load_dwordx2 v[200:201], v242, s[46:47] offset:32
	global_load_dwordx2 v[202:203], v242, s[46:47] offset:256
	global_load_dwordx2 v[204:205], v242, s[46:47] offset:288
	v_lshrrev_b32_e32 v245, 6, v160
	v_lshrrev_b32_e32 v244, 5, v162
	v_lshl_add_u32 v245, v245, 2, v244
	v_lshlrev_b32_e32 v245, 9, v245
	v_and_b32_e32 v244, 12, v162
	v_lshl_add_u32 v244, v244, 2, v245
	v_add_u32_e32 v244, 0x20000, v244
	v_lshl_add_u32 v245, v219, 2, v245
	v_add_u32_e32 v245, 0x20000, v245
	s_waitcnt vmcnt(7)
	ds_write_b32 v245, v214
	s_waitcnt vmcnt(6)
	ds_write_b32 v245, v215 offset:256
	v_add_u32_e32 v243, 0x8000, v242
	global_load_dwordx4 v[206:209], v[246:247], off offset:-2032
	global_load_dwordx4 v[214:217], v[246:247], off offset:-2048
	global_load_dwordx2 v[234:235], v243, s[46:47]
	global_load_dwordx2 v[236:237], v243, s[46:47] offset:32
	global_load_dwordx2 v[238:239], v243, s[46:47] offset:256
	global_load_dwordx2 v[240:241], v243, s[46:47] offset:288
	s_waitcnt lgkmcnt(0)
	v_and_b32_e32 v140, 64, v219
	v_xor_b32_e32 v3, 16, v219
	v_add_u32_e32 v140, 64, v140
	v_cmp_lt_i32_e32 vcc, v3, v140
	v_lshl_add_u32 v146, s29, 8, v160
	v_ashrrev_i32_e32 v147, 31, v146
	v_cndmask_b32_e32 v3, v219, v3, vcc
	v_lshlrev_b32_e32 v165, 2, v3
	v_xor_b32_e32 v3, 32, v219
	v_cmp_lt_i32_e32 vcc, v3, v140
	v_lshlrev_b64 v[148:149], 7, v[146:147]
	s_nop 0
	v_cndmask_b32_e32 v3, v219, v3, vcc
	v_lshlrev_b32_e32 v164, 2, v3
	v_cndmask_b32_e64 v3, 0, 1, s[96:97]
	v_cmp_ne_u32_e64 s[44:45], 1, v3
	s_andn2_b64 vcc, exec, s[96:97]
	s_cbranch_vccnz .LBB0_1838
	v_lshl_add_u64 v[144:145], v[134:135], 0, v[148:149]
	s_waitcnt vmcnt(10)
	v_mov_b64_e32 v[140:141], v[194:195]
	v_mov_b64_e32 v[142:143], v[196:197]
	s_waitcnt vmcnt(11)
	v_mov_b64_e32 v[150:151], v[190:191]
	v_mov_b64_e32 v[152:153], v[192:193]
	s_waitcnt lgkmcnt(0)
	v_mov_b32_e32 v144, v140
	v_mov_b32_e32 v145, v150
	v_mov_b32_e32 v154, v142
	v_mov_b32_e32 v155, v152
	v_pk_add_f32 v[144:145], v[144:145], v[154:155]
	v_add_f32_e32 v140, v141, v143
	v_add_f32_e32 v142, v151, v153
	v_mov_b32_e32 v141, v144
	v_mov_b32_e32 v143, v145
	v_pk_add_f32 v[140:141], v[140:141], v[142:143]
	ds_bpermute_b32 v143, v165, v141
	ds_bpermute_b32 v142, v165, v140
	s_waitcnt lgkmcnt(0)
	v_pk_add_f32 v[140:141], v[140:141], v[142:143]
	ds_bpermute_b32 v143, v164, v141
	ds_bpermute_b32 v142, v164, v140
	s_waitcnt lgkmcnt(0)
	v_pk_add_f32 v[140:141], v[140:141], v[142:143]
	s_nop 0
	v_pk_mul_f32 v[150:151], v[140:141], s[82:83] op_sel_hi:[1,0]
	s_nop 0
	v_fma_f32 v3, -v151, v151, v150
	v_max_f32_e32 v3, 0, v3
	v_add_f32_e32 v3, 0x3727c5ac, v3
	v_rsq_f32_e32 v152, v3
	s_branch .LBB0_1839

; __device__ __forceinline__ u32x2 pk4(f32x4 v) { u32x2 r; r.x = pk2(v.x, v.y); r.y = pk2(v.z, v.w); return r; }
;     __device__ __forceinline__ void operator()(const f32x4 (&acc)[2][2][4][2], const pg8::Unit& u, int wr, int wc, int fr, int fq) const {
;     ...
;                 for (int bj = 0; bj < 2; ++bj)
; #pragma unroll
;                     for (int n = 0; n < 2; ++n) {
;                         const int col = u.pn * 256 + bj * 128 + wc * 32 + n * 16 + fq * 4;
;                         const u32x2 raw = *(const u32x2*)(src + (size_t)row * DM + col);
;                         f32x4 x = (f32x4){bflo(raw.x), bfhi(raw.x), bflo(raw.y), bfhi(raw.y)};
;                         if (ln) x = (x - mu) * rs * *(const f32x4*)(g + col) + *(const f32x4*)(b + col);
;                         const u32x2 pz = pk4(x * ALPHA + acc[ai][bj][m][n]);
;                         *(u32x2*)(dst + (size_t)row * DM + col) = pz;
;                         const float z0 = bflo(pz.x), z1 = bfhi(pz.x), z2 = bflo(pz.y), z3 = bfhi(pz.y);
;                         s1 += (z0 + z1) + (z2 + z3); s2 += (z0 * z0 + z1 * z1) + (z2 * z2 + z3 * z3);
;                     }
.LBB0_1839:
	v_lshl_add_u32 v144, s23, 8, v162
	v_lshlrev_b64 v[140:141], 11, v[146:147]
	v_lshl_add_u64 v[140:141], s[46:47], 0, v[140:141]
	v_ashrrev_i32_e32 v145, 31, v144
	v_lshl_add_u64 v[154:155], v[144:145], 1, v[140:141]
	v_add_u32_e32 v243, 0x10000, v242
	s_waitcnt vmcnt(9)
	v_mov_b64_e32 v[142:143], v[198:199]
	global_load_dwordx4 v[190:193], v[246:247], off offset:16
	global_load_dwordx4 v[194:197], v[246:247], off
	global_load_dwordx2 v[198:199], v243, s[46:47]
	v_readlane_b32 s56, v251, 22
	v_lshlrev_b64 v[166:167], 2, v[144:145]
	v_readlane_b32 s68, v251, 34
	v_readlane_b32 s69, v251, 35
	v_readlane_b32 s70, v251, 36
	v_readlane_b32 s71, v251, 37
	v_readlane_b32 s24, v251, 0
	v_mov_b32_e32 v153, v152
	s_and_b64 vcc, exec, s[44:45]
	v_lshl_add_u64 v[140:141], s[70:71], 0, v[166:167]
	v_readlane_b32 s25, v251, 1
	v_readlane_b32 s26, v251, 2
	v_readlane_b32 s27, v251, 3
	v_readlane_b32 s57, v251, 23
	v_readlane_b32 s58, v251, 24
	v_readlane_b32 s59, v251, 25
	v_readlane_b32 s60, v251, 26
	v_readlane_b32 s61, v251, 27
	v_readlane_b32 s62, v251, 28
	v_readlane_b32 s63, v251, 29
	v_readlane_b32 s64, v251, 30
	v_readlane_b32 s65, v251, 31
	v_readlane_b32 s66, v251, 32
	v_readlane_b32 s67, v251, 33
	s_waitcnt lgkmcnt(0)
	v_lshlrev_b32_e32 v156, 16, v142
	v_and_b32_e32 v157, 0xffff0000, v142
	v_lshlrev_b32_e32 v158, 16, v143
	v_and_b32_e32 v159, 0xffff0000, v143
	v_lshl_add_u64 v[142:143], s[68:69], 0, v[166:167]
	s_cbranch_vccnz .LBB0_1841
	v_sub_f32_e32 v157, v157, v151
	v_sub_f32_e32 v156, v156, v151
	v_sub_f32_e32 v159, v159, v151
	v_sub_f32_e32 v158, v158, v151
	v_pk_mul_f32 v[166:167], v[152:153], v[156:157]
	v_mov_b32_e32 v156, v152
	v_mov_b32_e32 v157, v152
	v_pk_mul_f32 v[168:169], v[156:157], v[158:159]
	ds_read_b128 v[156:159], v244
	ds_read_b128 v[180:183], v244 offset:256
	s_waitcnt lgkmcnt(0)
	v_pk_fma_f32 v[158:159], v[168:169], v[158:159], v[182:183]
	v_pk_fma_f32 v[156:157], v[166:167], v[156:157], v[180:181]
.LBB0_1841:
	v_readlane_b32 s70, v250, 30
	v_lshlrev_b64 v[166:167], 10, v[146:147]
	v_pk_fma_f32 v[128:129], v[156:157], s[72:73], v[128:129] op_sel_hi:[1,0,1]
	v_readlane_b32 s71, v250, 31
	v_pk_fma_f32 v[158:159], v[158:159], s[72:73], v[130:131] op_sel_hi:[1,0,1]
	v_cvt_pk_bf16_f32 v130, v128, v129
	v_lshl_add_u64 v[128:129], v[166:167], 1, s[70:71]
	v_cvt_pk_bf16_f32 v131, v158, v159
	v_lshl_add_u64 v[128:129], v[144:145], 1, v[128:129]
	global_store_dwordx2 v[128:129], v[130:131], off
	s_waitcnt vmcnt(12)
	v_mov_b64_e32 v[158:159], v[200:201]
	global_load_dwordx2 v[200:201], v243, s[46:47] offset:32
	s_and_b64 vcc, exec, s[44:45]
	s_waitcnt lgkmcnt(0)
	v_lshlrev_b32_e32 v156, 16, v158
	v_and_b32_e32 v157, 0xffff0000, v158
	v_lshlrev_b32_e32 v158, 16, v159
	v_and_b32_e32 v159, 0xffff0000, v159
	s_cbranch_vccnz .LBB0_1843
	v_sub_f32_e32 v157, v157, v151
	v_sub_f32_e32 v156, v156, v151
	v_sub_f32_e32 v159, v159, v151
	v_sub_f32_e32 v158, v158, v151
	v_pk_mul_f32 v[166:167], v[152:153], v[156:157]
	v_mov_b32_e32 v156, v152
	v_mov_b32_e32 v157, v152
	v_pk_mul_f32 v[168:169], v[156:157], v[158:159]
	ds_read_b128 v[156:159], v244 offset:64
	ds_read_b128 v[180:183], v244 offset:320
	s_waitcnt lgkmcnt(0)
	v_pk_fma_f32 v[158:159], v[168:169], v[158:159], v[182:183]
	v_pk_fma_f32 v[156:157], v[166:167], v[156:157], v[180:181]
.LBB0_1843:
	v_pk_fma_f32 v[126:127], v[158:159], s[72:73], v[126:127] op_sel_hi:[1,0,1]
	v_pk_fma_f32 v[124:125], v[156:157], s[72:73], v[124:125] op_sel_hi:[1,0,1]
	s_and_b64 vcc, exec, s[44:45]
	v_cvt_pk_bf16_f32 v124, v124, v125
	v_cvt_pk_bf16_f32 v125, v126, v127
	global_store_dwordx2 v[128:129], v[124:125], off offset:32
	s_waitcnt vmcnt(13)
	v_mov_b64_e32 v[156:157], v[202:203]
	global_load_dwordx2 v[202:203], v243, s[46:47] offset:256
	s_waitcnt lgkmcnt(0)
	v_lshlrev_b32_e32 v126, 16, v156
	v_and_b32_e32 v127, 0xffff0000, v156
	v_lshlrev_b32_e32 v156, 16, v157
	v_and_b32_e32 v157, 0xffff0000, v157
	s_cbranch_vccnz .LBB0_1845
	ds_read_b128 v[180:183], v244 offset:128
	ds_read_b128 v[184:187], v244 offset:384
	v_sub_f32_e32 v157, v157, v151
	v_sub_f32_e32 v156, v156, v151
	v_sub_f32_e32 v127, v127, v151
	v_sub_f32_e32 v126, v126, v151
	v_mov_b32_e32 v158, v152
	v_mov_b32_e32 v159, v152
	v_pk_mul_f32 v[126:127], v[152:153], v[126:127]
	v_pk_mul_f32 v[156:157], v[158:159], v[156:157]
	s_waitcnt lgkmcnt(0)
	v_pk_fma_f32 v[126:127], v[126:127], v[180:181], v[184:185]
	v_pk_fma_f32 v[156:157], v[156:157], v[182:183], v[186:187]
.LBB0_1845:
	s_nop 0
	v_pk_fma_f32 v[122:123], v[156:157], s[72:73], v[122:123] op_sel_hi:[1,0,1]
	v_pk_fma_f32 v[120:121], v[126:127], s[72:73], v[120:121] op_sel_hi:[1,0,1]
	s_and_b64 vcc, exec, s[44:45]
	v_cvt_pk_bf16_f32 v120, v120, v121
	v_cvt_pk_bf16_f32 v121, v122, v123
	global_store_dwordx2 v[128:129], v[120:121], off offset:256
	s_waitcnt vmcnt(14)
	v_mov_b64_e32 v[126:127], v[204:205]
	global_load_dwordx2 v[204:205], v243, s[46:47] offset:288
	s_waitcnt lgkmcnt(0)
	v_lshlrev_b32_e32 v122, 16, v126
	v_and_b32_e32 v123, 0xffff0000, v126
	v_lshlrev_b32_e32 v126, 16, v127
	v_and_b32_e32 v127, 0xffff0000, v127
	s_cbranch_vccnz .LBB0_1847
	v_sub_f32_e32 v123, v123, v151
	v_sub_f32_e32 v122, v122, v151
	v_sub_f32_e32 v127, v127, v151
	v_sub_f32_e32 v126, v126, v151
	v_pk_mul_f32 v[122:123], v[152:153], v[122:123]
	v_mov_b32_e32 v153, v152
	v_pk_mul_f32 v[126:127], v[152:153], v[126:127]
	ds_read_b128 v[150:153], v244 offset:192
	ds_read_b128 v[154:157], v244 offset:448
	s_waitcnt lgkmcnt(0)
	v_pk_fma_f32 v[126:127], v[126:127], v[152:153], v[156:157]
	v_pk_fma_f32 v[122:123], v[122:123], v[150:151], v[154:155]

; __device__ __forceinline__ void stats_main(const float* stm, int row, int fq, float& mu, float& rs) {
;     const f32x4* p = (const f32x4*)(stm + (size_t)row * 32 + fq * 8);
;     const f32x4 a = p[0], b = p[1];
;     float s1 = (a.x + a.z) + (b.x + b.z), s2 = (a.y + a.w) + (b.y + b.w);
;     s1 += __shfl_xor(s1, 16); s2 += __shfl_xor(s2, 16); s1 += __shfl_xor(s1, 32); s2 += __shfl_xor(s2, 32);
;     mu = s1 * (1.f / DM); rs = __builtin_amdgcn_rsqf(fmaxf(s2 * (1.f / DM) - mu * mu, 0.f) + LN_EPS);
; }
.LBB0_1849:
	s_or_b64 exec, exec, s[0:1]
	v_or_b32_e32 v124, 16, v146
	v_ashrrev_i32_e32 v125, 31, v124
	s_and_b64 vcc, exec, s[44:45]
	v_lshlrev_b64 v[116:117], 7, v[124:125]
	s_cbranch_vccnz .LBB0_1851
	v_lshl_add_u64 v[122:123], v[134:135], 0, v[116:117]
	s_waitcnt lgkmcnt(0)
	s_waitcnt vmcnt(15)
	v_mov_b64_e32 v[118:119], v[214:215]
	v_mov_b64_e32 v[120:121], v[216:217]
	s_waitcnt vmcnt(16)
	v_mov_b64_e32 v[126:127], v[206:207]
	v_mov_b64_e32 v[128:129], v[208:209]
	s_waitcnt lgkmcnt(0)
	v_mov_b32_e32 v122, v118
	s_waitcnt lgkmcnt(0)
	v_mov_b32_e32 v123, v126
	v_mov_b32_e32 v130, v120
	v_mov_b32_e32 v131, v128
	v_pk_add_f32 v[122:123], v[122:123], v[130:131]
	v_add_f32_e32 v118, v119, v121
	v_add_f32_e32 v120, v127, v129
	v_mov_b32_e32 v119, v122
	v_mov_b32_e32 v121, v123
	v_pk_add_f32 v[118:119], v[118:119], v[120:121]
	ds_bpermute_b32 v121, v165, v119
	ds_bpermute_b32 v120, v165, v118
	s_waitcnt lgkmcnt(0)
	v_pk_add_f32 v[118:119], v[118:119], v[120:121]
	ds_bpermute_b32 v121, v164, v119
	ds_bpermute_b32 v120, v164, v118
	s_waitcnt lgkmcnt(0)
	v_pk_add_f32 v[118:119], v[118:119], v[120:121]
	s_nop 0
	v_pk_mul_f32 v[118:119], v[118:119], s[82:83] op_sel_hi:[1,0]
	s_nop 0
	v_fma_f32 v3, -v119, v119, v118
	v_max_f32_e32 v3, 0, v3
	v_add_f32_e32 v3, 0x3727c5ac, v3
	v_rsq_f32_e32 v120, v3
	s_branch .LBB0_1852

; __device__ __forceinline__ u32x2 pk4(f32x4 v) { u32x2 r; r.x = pk2(v.x, v.y); r.y = pk2(v.z, v.w); return r; }
;     __device__ __forceinline__ void operator()(const f32x4 (&acc)[2][2][4][2], const pg8::Unit& u, int wr, int wc, int fr, int fq) const {
;     ...
;                 for (int bj = 0; bj < 2; ++bj)
; #pragma unroll
;                     for (int n = 0; n < 2; ++n) {
;                         const int col = u.pn * 256 + bj * 128 + wc * 32 + n * 16 + fq * 4;
;                         const u32x2 raw = *(const u32x2*)(src + (size_t)row * DM + col);
;                         f32x4 x = (f32x4){bflo(raw.x), bfhi(raw.x), bflo(raw.y), bfhi(raw.y)};
;                         if (ln) x = (x - mu) * rs * *(const f32x4*)(g + col) + *(const f32x4*)(b + col);
;                         const u32x2 pz = pk4(x * ALPHA + acc[ai][bj][m][n]);
;                         *(u32x2*)(dst + (size_t)row * DM + col) = pz;
;                         const float z0 = bflo(pz.x), z1 = bfhi(pz.x), z2 = bflo(pz.y), z3 = bfhi(pz.y);
;                         s1 += (z0 + z1) + (z2 + z3); s2 += (z0 * z0 + z1 * z1) + (z2 * z2 + z3 * z3);
;                     }
.LBB0_1852:
	v_lshlrev_b64 v[122:123], 11, v[124:125]
	v_lshl_add_u64 v[122:123], s[46:47], 0, v[122:123]
	v_lshl_add_u64 v[122:123], v[144:145], 1, v[122:123]
	v_add_u32_e32 v243, 0x18000, v242
	s_waitcnt vmcnt(14)
	v_mov_b64_e32 v[128:129], v[234:235]
	global_load_dwordx4 v[206:209], v[246:247], off offset:2064
	global_load_dwordx4 v[214:217], v[246:247], off offset:2048
	global_load_dwordx2 v[234:235], v243, s[46:47]
	v_mov_b32_e32 v121, v120
	s_and_b64 vcc, exec, s[44:45]
	s_waitcnt lgkmcnt(0)
	v_lshlrev_b32_e32 v126, 16, v128
	v_and_b32_e32 v127, 0xffff0000, v128
	v_lshlrev_b32_e32 v128, 16, v129
	v_and_b32_e32 v129, 0xffff0000, v129
	s_cbranch_vccnz .LBB0_1854
	v_sub_f32_e32 v127, v127, v119
	v_sub_f32_e32 v126, v126, v119
	v_sub_f32_e32 v129, v129, v119
	v_sub_f32_e32 v128, v128, v119
	v_pk_mul_f32 v[130:131], v[120:121], v[126:127]
	v_mov_b32_e32 v126, v120
	v_mov_b32_e32 v127, v120
	v_pk_mul_f32 v[152:153], v[126:127], v[128:129]
	ds_read_b128 v[126:129], v244
	ds_read_b128 v[148:151], v244 offset:256
	s_waitcnt lgkmcnt(0)
	v_pk_fma_f32 v[128:129], v[152:153], v[128:129], v[150:151]
	v_pk_fma_f32 v[126:127], v[130:131], v[126:127], v[148:149]
.LBB0_1854:
	v_lshlrev_b64 v[124:125], 10, v[124:125]
	v_pk_fma_f32 v[112:113], v[126:127], s[72:73], v[112:113] op_sel_hi:[1,0,1]
	v_pk_fma_f32 v[128:129], v[128:129], s[72:73], v[114:115] op_sel_hi:[1,0,1]
	v_cvt_pk_bf16_f32 v114, v112, v113
	v_lshl_add_u64 v[112:113], v[124:125], 1, s[70:71]
	v_cvt_pk_bf16_f32 v115, v128, v129
	v_lshl_add_u64 v[112:113], v[144:145], 1, v[112:113]
	global_store_dwordx2 v[112:113], v[114:115], off
	s_waitcnt vmcnt(17)
	v_mov_b64_e32 v[126:127], v[236:237]
	global_load_dwordx2 v[236:237], v243, s[46:47] offset:32
	s_and_b64 vcc, exec, s[44:45]
	s_waitcnt lgkmcnt(0)
	v_lshlrev_b32_e32 v124, 16, v126
	v_and_b32_e32 v125, 0xffff0000, v126
	v_lshlrev_b32_e32 v126, 16, v127
	v_and_b32_e32 v127, 0xffff0000, v127
	s_cbranch_vccnz .LBB0_1856
	v_sub_f32_e32 v125, v125, v119
	v_sub_f32_e32 v124, v124, v119
	v_sub_f32_e32 v127, v127, v119
	v_sub_f32_e32 v126, v126, v119
	v_pk_mul_f32 v[148:149], v[120:121], v[124:125]
	v_mov_b32_e32 v124, v120
	v_mov_b32_e32 v125, v120
	v_pk_mul_f32 v[150:151], v[124:125], v[126:127]
	ds_read_b128 v[124:127], v244 offset:64
	ds_read_b128 v[128:131], v244 offset:320
	s_waitcnt lgkmcnt(0)
	v_pk_fma_f32 v[126:127], v[150:151], v[126:127], v[130:131]
	v_pk_fma_f32 v[124:125], v[148:149], v[124:125], v[128:129]
.LBB0_1856:
	v_pk_fma_f32 v[110:111], v[126:127], s[72:73], v[110:111] op_sel_hi:[1,0,1]
	v_pk_fma_f32 v[108:109], v[124:125], s[72:73], v[108:109] op_sel_hi:[1,0,1]
	s_and_b64 vcc, exec, s[44:45]
	v_cvt_pk_bf16_f32 v108, v108, v109
	v_cvt_pk_bf16_f32 v109, v110, v111
	global_store_dwordx2 v[112:113], v[108:109], off offset:32
	s_waitcnt vmcnt(18)
	v_mov_b64_e32 v[124:125], v[238:239]
	global_load_dwordx2 v[238:239], v243, s[46:47] offset:256
	s_waitcnt lgkmcnt(0)
	v_lshlrev_b32_e32 v110, 16, v124
	v_and_b32_e32 v111, 0xffff0000, v124
	v_lshlrev_b32_e32 v124, 16, v125
	v_and_b32_e32 v125, 0xffff0000, v125
	s_cbranch_vccnz .LBB0_1858
	v_sub_f32_e32 v125, v125, v119
	v_sub_f32_e32 v124, v124, v119
	v_mov_b32_e32 v126, v120
	v_mov_b32_e32 v127, v120
	v_pk_mul_f32 v[124:125], v[126:127], v[124:125]
	ds_read_b128 v[126:129], v244 offset:128
	ds_read_b128 v[148:151], v244 offset:384
	v_sub_f32_e32 v111, v111, v119
	v_sub_f32_e32 v110, v110, v119
	v_pk_mul_f32 v[110:111], v[120:121], v[110:111]
	s_waitcnt lgkmcnt(0)
	v_pk_fma_f32 v[124:125], v[124:125], v[128:129], v[150:151]
	v_pk_fma_f32 v[110:111], v[110:111], v[126:127], v[148:149]
.LBB0_1858:
	v_pk_fma_f32 v[106:107], v[124:125], s[72:73], v[106:107] op_sel_hi:[1,0,1]
	v_pk_fma_f32 v[104:105], v[110:111], s[72:73], v[104:105] op_sel_hi:[1,0,1]
	s_and_b64 vcc, exec, s[44:45]
	v_cvt_pk_bf16_f32 v104, v104, v105
	v_cvt_pk_bf16_f32 v105, v106, v107
	global_store_dwordx2 v[112:113], v[104:105], off offset:256
	s_waitcnt vmcnt(19)
	v_mov_b64_e32 v[110:111], v[240:241]
	global_load_dwordx2 v[240:241], v243, s[46:47] offset:288
	s_waitcnt lgkmcnt(0)
	v_lshlrev_b32_e32 v106, 16, v110
	v_and_b32_e32 v107, 0xffff0000, v110
	v_lshlrev_b32_e32 v110, 16, v111
	v_and_b32_e32 v111, 0xffff0000, v111
	s_cbranch_vccnz .LBB0_1860
	v_sub_f32_e32 v107, v107, v119
	v_sub_f32_e32 v106, v106, v119
	v_sub_f32_e32 v111, v111, v119
	v_sub_f32_e32 v110, v110, v119
	v_pk_mul_f32 v[106:107], v[120:121], v[106:107]
	v_mov_b32_e32 v121, v120
	v_pk_mul_f32 v[110:111], v[120:121], v[110:111]
	ds_read_b128 v[118:121], v244 offset:192
	ds_read_b128 v[122:125], v244 offset:448
	s_waitcnt lgkmcnt(0)
	v_pk_fma_f32 v[110:111], v[110:111], v[120:121], v[124:125]
	v_pk_fma_f32 v[106:107], v[106:107], v[118:119], v[122:123]

; __device__ __forceinline__ void stats_main(const float* stm, int row, int fq, float& mu, float& rs) {
;     const f32x4* p = (const f32x4*)(stm + (size_t)row * 32 + fq * 8);
;     const f32x4 a = p[0], b = p[1];
;     float s1 = (a.x + a.z) + (b.x + b.z), s2 = (a.y + a.w) + (b.y + b.w);
;     s1 += __shfl_xor(s1, 16); s2 += __shfl_xor(s2, 16); s1 += __shfl_xor(s1, 32); s2 += __shfl_xor(s2, 32);
;     mu = s1 * (1.f / DM); rs = __builtin_amdgcn_rsqf(fmaxf(s2 * (1.f / DM) - mu * mu, 0.f) + LN_EPS);
; }
.LBB0_1862:
	s_or_b64 exec, exec, s[0:1]
	v_or_b32_e32 v108, 32, v146
	v_ashrrev_i32_e32 v109, 31, v108
	s_and_b64 vcc, exec, s[44:45]
	v_lshlrev_b64 v[100:101], 7, v[108:109]
	s_cbranch_vccnz .LBB0_1864
	v_lshl_add_u64 v[106:107], v[134:135], 0, v[100:101]
	s_waitcnt lgkmcnt(0)
	s_waitcnt vmcnt(20)
	v_mov_b64_e32 v[102:103], v[194:195]
	v_mov_b64_e32 v[104:105], v[196:197]
	s_waitcnt vmcnt(21)
	v_mov_b64_e32 v[110:111], v[190:191]
	v_mov_b64_e32 v[112:113], v[192:193]
	s_waitcnt lgkmcnt(0)
	v_mov_b32_e32 v106, v102
	s_waitcnt lgkmcnt(0)
	v_mov_b32_e32 v107, v110
	v_mov_b32_e32 v114, v104
	v_mov_b32_e32 v115, v112
	v_pk_add_f32 v[106:107], v[106:107], v[114:115]
	v_add_f32_e32 v102, v103, v105
	v_add_f32_e32 v104, v111, v113
	v_mov_b32_e32 v103, v106
	v_mov_b32_e32 v105, v107
	v_pk_add_f32 v[102:103], v[102:103], v[104:105]
	ds_bpermute_b32 v105, v165, v103
	ds_bpermute_b32 v104, v165, v102
	s_waitcnt lgkmcnt(0)
	v_pk_add_f32 v[102:103], v[102:103], v[104:105]
	ds_bpermute_b32 v105, v164, v103
	ds_bpermute_b32 v104, v164, v102
	s_waitcnt lgkmcnt(0)
	v_pk_add_f32 v[102:103], v[102:103], v[104:105]
	s_nop 0
	v_pk_mul_f32 v[102:103], v[102:103], s[82:83] op_sel_hi:[1,0]
	s_nop 0
	v_fma_f32 v3, -v103, v103, v102
	v_max_f32_e32 v3, 0, v3
	v_add_f32_e32 v3, 0x3727c5ac, v3
	v_rsq_f32_e32 v104, v3
	s_branch .LBB0_1865

; __device__ __forceinline__ u32x2 pk4(f32x4 v) { u32x2 r; r.x = pk2(v.x, v.y); r.y = pk2(v.z, v.w); return r; }
;     __device__ __forceinline__ void operator()(const f32x4 (&acc)[2][2][4][2], const pg8::Unit& u, int wr, int wc, int fr, int fq) const {
;     ...
;                 for (int bj = 0; bj < 2; ++bj)
; #pragma unroll
;                     for (int n = 0; n < 2; ++n) {
;                         const int col = u.pn * 256 + bj * 128 + wc * 32 + n * 16 + fq * 4;
;                         const u32x2 raw = *(const u32x2*)(src + (size_t)row * DM + col);
;                         f32x4 x = (f32x4){bflo(raw.x), bfhi(raw.x), bflo(raw.y), bfhi(raw.y)};
;                         if (ln) x = (x - mu) * rs * *(const f32x4*)(g + col) + *(const f32x4*)(b + col);
;                         const u32x2 pz = pk4(x * ALPHA + acc[ai][bj][m][n]);
;                         *(u32x2*)(dst + (size_t)row * DM + col) = pz;
;                         const float z0 = bflo(pz.x), z1 = bfhi(pz.x), z2 = bflo(pz.y), z3 = bfhi(pz.y);
;                         s1 += (z0 + z1) + (z2 + z3); s2 += (z0 * z0 + z1 * z1) + (z2 * z2 + z3 * z3);
;                     }
.LBB0_1865:
	v_lshlrev_b64 v[106:107], 11, v[108:109]
	v_lshl_add_u64 v[106:107], s[46:47], 0, v[106:107]
	v_lshl_add_u64 v[106:107], v[144:145], 1, v[106:107]
	v_add_u32_e32 v243, 0x40000, v242
	s_waitcnt vmcnt(19)
	v_mov_b64_e32 v[112:113], v[198:199]
	global_load_dwordx4 v[190:193], v[248:249], off offset:-4080
	global_load_dwordx4 v[194:197], v[248:249], off offset:-4096
	global_load_dwordx2 v[198:199], v243, s[46:47]
	v_mov_b32_e32 v105, v104
	s_and_b64 vcc, exec, s[44:45]
	s_waitcnt lgkmcnt(0)
	v_lshlrev_b32_e32 v110, 16, v112
	v_and_b32_e32 v111, 0xffff0000, v112
	v_lshlrev_b32_e32 v112, 16, v113
	v_and_b32_e32 v113, 0xffff0000, v113
	s_cbranch_vccnz .LBB0_1867
	v_sub_f32_e32 v111, v111, v103
	v_sub_f32_e32 v110, v110, v103
	v_sub_f32_e32 v113, v113, v103
	v_sub_f32_e32 v112, v112, v103
	v_pk_mul_f32 v[118:119], v[104:105], v[110:111]
	v_mov_b32_e32 v110, v104
	v_mov_b32_e32 v111, v104
	v_pk_mul_f32 v[120:121], v[110:111], v[112:113]
	ds_read_b128 v[110:113], v244
	ds_read_b128 v[114:117], v244 offset:256
	s_waitcnt lgkmcnt(0)
	v_pk_fma_f32 v[112:113], v[120:121], v[112:113], v[116:117]
	v_pk_fma_f32 v[110:111], v[118:119], v[110:111], v[114:115]
.LBB0_1867:
	v_lshlrev_b64 v[108:109], 10, v[108:109]
	v_pk_fma_f32 v[96:97], v[110:111], s[72:73], v[96:97] op_sel_hi:[1,0,1]
	v_pk_fma_f32 v[112:113], v[112:113], s[72:73], v[98:99] op_sel_hi:[1,0,1]
	v_cvt_pk_bf16_f32 v98, v96, v97
	v_lshl_add_u64 v[96:97], v[108:109], 1, s[70:71]
	v_cvt_pk_bf16_f32 v99, v112, v113
	v_lshl_add_u64 v[96:97], v[144:145], 1, v[96:97]
	global_store_dwordx2 v[96:97], v[98:99], off
	s_waitcnt vmcnt(21)
	v_mov_b64_e32 v[110:111], v[200:201]
	global_load_dwordx2 v[200:201], v243, s[46:47] offset:32
	s_and_b64 vcc, exec, s[44:45]
	s_waitcnt lgkmcnt(0)
	v_lshlrev_b32_e32 v108, 16, v110
	v_and_b32_e32 v109, 0xffff0000, v110
	v_lshlrev_b32_e32 v110, 16, v111
	v_and_b32_e32 v111, 0xffff0000, v111
	s_cbranch_vccnz .LBB0_1869
	v_sub_f32_e32 v109, v109, v103
	v_sub_f32_e32 v108, v108, v103
	v_sub_f32_e32 v111, v111, v103
	v_sub_f32_e32 v110, v110, v103
	v_pk_mul_f32 v[116:117], v[104:105], v[108:109]
	v_mov_b32_e32 v108, v104
	v_mov_b32_e32 v109, v104
	v_pk_mul_f32 v[118:119], v[108:109], v[110:111]
	ds_read_b128 v[108:111], v244 offset:64
	ds_read_b128 v[112:115], v244 offset:320
	s_waitcnt lgkmcnt(0)
	v_pk_fma_f32 v[110:111], v[118:119], v[110:111], v[114:115]
	v_pk_fma_f32 v[108:109], v[116:117], v[108:109], v[112:113]
.LBB0_1869:
	v_pk_fma_f32 v[94:95], v[110:111], s[72:73], v[94:95] op_sel_hi:[1,0,1]
	v_pk_fma_f32 v[92:93], v[108:109], s[72:73], v[92:93] op_sel_hi:[1,0,1]
	s_and_b64 vcc, exec, s[44:45]
	v_cvt_pk_bf16_f32 v92, v92, v93
	v_cvt_pk_bf16_f32 v93, v94, v95
	global_store_dwordx2 v[96:97], v[92:93], off offset:32
	s_waitcnt vmcnt(21)
	v_mov_b64_e32 v[108:109], v[202:203]
	global_load_dwordx2 v[202:203], v243, s[46:47] offset:256
	s_waitcnt lgkmcnt(0)
	v_lshlrev_b32_e32 v94, 16, v108
	v_and_b32_e32 v95, 0xffff0000, v108
	v_lshlrev_b32_e32 v108, 16, v109
	v_and_b32_e32 v109, 0xffff0000, v109
	s_cbranch_vccnz .LBB0_1871
	v_sub_f32_e32 v109, v109, v103
	v_sub_f32_e32 v108, v108, v103
	v_mov_b32_e32 v110, v104
	v_mov_b32_e32 v111, v104
	v_pk_mul_f32 v[108:109], v[110:111], v[108:109]
	ds_read_b128 v[110:113], v244 offset:128
	ds_read_b128 v[114:117], v244 offset:384
	v_sub_f32_e32 v95, v95, v103
	v_sub_f32_e32 v94, v94, v103
	v_pk_mul_f32 v[94:95], v[104:105], v[94:95]
	s_waitcnt lgkmcnt(0)
	v_pk_fma_f32 v[108:109], v[108:109], v[112:113], v[116:117]
	v_pk_fma_f32 v[94:95], v[94:95], v[110:111], v[114:115]
.LBB0_1871:
	v_pk_fma_f32 v[90:91], v[108:109], s[72:73], v[90:91] op_sel_hi:[1,0,1]
	v_pk_fma_f32 v[88:89], v[94:95], s[72:73], v[88:89] op_sel_hi:[1,0,1]
	s_and_b64 vcc, exec, s[44:45]
	v_cvt_pk_bf16_f32 v88, v88, v89
	v_cvt_pk_bf16_f32 v89, v90, v91
	global_store_dwordx2 v[96:97], v[88:89], off offset:256
	s_waitcnt vmcnt(21)
	v_mov_b64_e32 v[94:95], v[204:205]
	global_load_dwordx2 v[204:205], v243, s[46:47] offset:288
	s_waitcnt lgkmcnt(0)
	v_lshlrev_b32_e32 v90, 16, v94
	v_and_b32_e32 v91, 0xffff0000, v94
	v_lshlrev_b32_e32 v94, 16, v95
	v_and_b32_e32 v95, 0xffff0000, v95
	s_cbranch_vccnz .LBB0_1873
	v_sub_f32_e32 v91, v91, v103
	v_sub_f32_e32 v90, v90, v103
	v_sub_f32_e32 v95, v95, v103
	v_sub_f32_e32 v94, v94, v103
	v_pk_mul_f32 v[90:91], v[104:105], v[90:91]
	v_mov_b32_e32 v105, v104
	v_pk_mul_f32 v[94:95], v[104:105], v[94:95]
	ds_read_b128 v[102:105], v244 offset:192
	ds_read_b128 v[106:109], v244 offset:448
	s_waitcnt lgkmcnt(0)
	v_pk_fma_f32 v[94:95], v[94:95], v[104:105], v[108:109]
	v_pk_fma_f32 v[90:91], v[90:91], v[102:103], v[106:107]

; __device__ __forceinline__ void stats_main(const float* stm, int row, int fq, float& mu, float& rs) {
;     const f32x4* p = (const f32x4*)(stm + (size_t)row * 32 + fq * 8);
;     const f32x4 a = p[0], b = p[1];
;     float s1 = (a.x + a.z) + (b.x + b.z), s2 = (a.y + a.w) + (b.y + b.w);
;     s1 += __shfl_xor(s1, 16); s2 += __shfl_xor(s2, 16); s1 += __shfl_xor(s1, 32); s2 += __shfl_xor(s2, 32);
;     mu = s1 * (1.f / DM); rs = __builtin_amdgcn_rsqf(fmaxf(s2 * (1.f / DM) - mu * mu, 0.f) + LN_EPS);
; }
.LBB0_1875:
	s_or_b64 exec, exec, s[0:1]
	v_or_b32_e32 v92, 48, v146
	v_ashrrev_i32_e32 v93, 31, v92
	s_and_b64 vcc, exec, s[44:45]
	v_lshlrev_b64 v[84:85], 7, v[92:93]
	s_cbranch_vccnz .LBB0_1877
	v_lshl_add_u64 v[90:91], v[134:135], 0, v[84:85]
	s_waitcnt lgkmcnt(0)
	s_waitcnt vmcnt(20)
	v_mov_b64_e32 v[86:87], v[214:215]
	v_mov_b64_e32 v[88:89], v[216:217]
	s_waitcnt vmcnt(21)
	v_mov_b64_e32 v[94:95], v[206:207]
	v_mov_b64_e32 v[96:97], v[208:209]
	s_waitcnt lgkmcnt(0)
	v_mov_b32_e32 v90, v86
	s_waitcnt lgkmcnt(0)
	v_mov_b32_e32 v91, v94
	v_mov_b32_e32 v98, v88
	v_mov_b32_e32 v99, v96
	v_pk_add_f32 v[90:91], v[90:91], v[98:99]
	v_add_f32_e32 v86, v87, v89
	v_add_f32_e32 v88, v95, v97
	v_mov_b32_e32 v87, v90
	v_mov_b32_e32 v89, v91
	v_pk_add_f32 v[86:87], v[86:87], v[88:89]
	ds_bpermute_b32 v89, v165, v87
	ds_bpermute_b32 v88, v165, v86
	s_waitcnt lgkmcnt(0)
	v_pk_add_f32 v[86:87], v[86:87], v[88:89]
	ds_bpermute_b32 v89, v164, v87
	ds_bpermute_b32 v88, v164, v86
	s_waitcnt lgkmcnt(0)
	v_pk_add_f32 v[86:87], v[86:87], v[88:89]
	s_nop 0
	v_pk_mul_f32 v[86:87], v[86:87], s[82:83] op_sel_hi:[1,0]
	s_nop 0
	v_fma_f32 v3, -v87, v87, v86
	v_max_f32_e32 v3, 0, v3
	v_add_f32_e32 v3, 0x3727c5ac, v3
	v_rsq_f32_e32 v88, v3
	s_branch .LBB0_1878

; __device__ __forceinline__ u32x2 pk4(f32x4 v) { u32x2 r; r.x = pk2(v.x, v.y); r.y = pk2(v.z, v.w); return r; }
;     __device__ __forceinline__ void operator()(const f32x4 (&acc)[2][2][4][2], const pg8::Unit& u, int wr, int wc, int fr, int fq) const {
;     ...
;                 for (int bj = 0; bj < 2; ++bj)
; #pragma unroll
;                     for (int n = 0; n < 2; ++n) {
;                         const int col = u.pn * 256 + bj * 128 + wc * 32 + n * 16 + fq * 4;
;                         const u32x2 raw = *(const u32x2*)(src + (size_t)row * DM + col);
;                         f32x4 x = (f32x4){bflo(raw.x), bfhi(raw.x), bflo(raw.y), bfhi(raw.y)};
;                         if (ln) x = (x - mu) * rs * *(const f32x4*)(g + col) + *(const f32x4*)(b + col);
;                         const u32x2 pz = pk4(x * ALPHA + acc[ai][bj][m][n]);
;                         *(u32x2*)(dst + (size_t)row * DM + col) = pz;
;                         const float z0 = bflo(pz.x), z1 = bfhi(pz.x), z2 = bflo(pz.y), z3 = bfhi(pz.y);
;                         s1 += (z0 + z1) + (z2 + z3); s2 += (z0 * z0 + z1 * z1) + (z2 * z2 + z3 * z3);
;                     }
.LBB0_1878:
	v_lshlrev_b64 v[90:91], 11, v[92:93]
	v_lshl_add_u64 v[90:91], s[46:47], 0, v[90:91]
	v_lshl_add_u64 v[90:91], v[144:145], 1, v[90:91]
	v_add_u32_e32 v243, 0x48000, v242
	s_waitcnt vmcnt(19)
	v_mov_b64_e32 v[96:97], v[234:235]
	global_load_dwordx4 v[206:209], v[248:249], off offset:-2032
	global_load_dwordx4 v[214:217], v[248:249], off offset:-2048
	global_load_dwordx2 v[234:235], v243, s[46:47]
	v_mov_b32_e32 v89, v88
	s_and_b64 vcc, exec, s[44:45]
	s_waitcnt lgkmcnt(0)
	v_lshlrev_b32_e32 v94, 16, v96
	v_and_b32_e32 v95, 0xffff0000, v96
	v_lshlrev_b32_e32 v96, 16, v97
	v_and_b32_e32 v97, 0xffff0000, v97
	s_cbranch_vccnz .LBB0_1880
	v_sub_f32_e32 v95, v95, v87
	v_sub_f32_e32 v94, v94, v87
	v_sub_f32_e32 v97, v97, v87
	v_sub_f32_e32 v96, v96, v87
	v_pk_mul_f32 v[102:103], v[88:89], v[94:95]
	v_mov_b32_e32 v94, v88
	v_mov_b32_e32 v95, v88
	v_pk_mul_f32 v[104:105], v[94:95], v[96:97]
	ds_read_b128 v[94:97], v244
	ds_read_b128 v[98:101], v244 offset:256
	s_waitcnt lgkmcnt(0)
	v_pk_fma_f32 v[96:97], v[104:105], v[96:97], v[100:101]
	v_pk_fma_f32 v[94:95], v[102:103], v[94:95], v[98:99]
.LBB0_1880:
	v_lshlrev_b64 v[92:93], 10, v[92:93]
	v_pk_fma_f32 v[80:81], v[94:95], s[72:73], v[80:81] op_sel_hi:[1,0,1]
	v_pk_fma_f32 v[96:97], v[96:97], s[72:73], v[82:83] op_sel_hi:[1,0,1]
	v_cvt_pk_bf16_f32 v82, v80, v81
	v_lshl_add_u64 v[80:81], v[92:93], 1, s[70:71]
	v_cvt_pk_bf16_f32 v83, v96, v97
	v_lshl_add_u64 v[80:81], v[144:145], 1, v[80:81]
	global_store_dwordx2 v[80:81], v[82:83], off
	s_waitcnt vmcnt(21)
	v_mov_b64_e32 v[94:95], v[236:237]
	global_load_dwordx2 v[236:237], v243, s[46:47] offset:32
	s_and_b64 vcc, exec, s[44:45]
	s_waitcnt lgkmcnt(0)
	v_lshlrev_b32_e32 v92, 16, v94
	v_and_b32_e32 v93, 0xffff0000, v94
	v_lshlrev_b32_e32 v94, 16, v95
	v_and_b32_e32 v95, 0xffff0000, v95
	s_cbranch_vccnz .LBB0_1882
	v_sub_f32_e32 v93, v93, v87
	v_sub_f32_e32 v92, v92, v87
	v_sub_f32_e32 v95, v95, v87
	v_sub_f32_e32 v94, v94, v87
	v_pk_mul_f32 v[100:101], v[88:89], v[92:93]
	v_mov_b32_e32 v92, v88
	v_mov_b32_e32 v93, v88
	v_pk_mul_f32 v[102:103], v[92:93], v[94:95]
	ds_read_b128 v[92:95], v244 offset:64
	ds_read_b128 v[96:99], v244 offset:320
	s_waitcnt lgkmcnt(0)
	v_pk_fma_f32 v[94:95], v[102:103], v[94:95], v[98:99]
	v_pk_fma_f32 v[92:93], v[100:101], v[92:93], v[96:97]
.LBB0_1882:
	v_pk_fma_f32 v[78:79], v[94:95], s[72:73], v[78:79] op_sel_hi:[1,0,1]
	v_pk_fma_f32 v[76:77], v[92:93], s[72:73], v[76:77] op_sel_hi:[1,0,1]
	s_and_b64 vcc, exec, s[44:45]
	v_cvt_pk_bf16_f32 v76, v76, v77
	v_cvt_pk_bf16_f32 v77, v78, v79
	global_store_dwordx2 v[80:81], v[76:77], off offset:32
	s_waitcnt vmcnt(21)
	v_mov_b64_e32 v[92:93], v[238:239]
	global_load_dwordx2 v[238:239], v243, s[46:47] offset:256
	s_waitcnt lgkmcnt(0)
	v_lshlrev_b32_e32 v78, 16, v92
	v_and_b32_e32 v79, 0xffff0000, v92
	v_lshlrev_b32_e32 v92, 16, v93
	v_and_b32_e32 v93, 0xffff0000, v93
	s_cbranch_vccnz .LBB0_1884
	v_sub_f32_e32 v93, v93, v87
	v_sub_f32_e32 v92, v92, v87
	v_mov_b32_e32 v94, v88
	v_mov_b32_e32 v95, v88
	v_pk_mul_f32 v[92:93], v[94:95], v[92:93]
	ds_read_b128 v[94:97], v244 offset:128
	ds_read_b128 v[98:101], v244 offset:384
	v_sub_f32_e32 v79, v79, v87
	v_sub_f32_e32 v78, v78, v87
	v_pk_mul_f32 v[78:79], v[88:89], v[78:79]
	s_waitcnt lgkmcnt(0)
	v_pk_fma_f32 v[92:93], v[92:93], v[96:97], v[100:101]
	v_pk_fma_f32 v[78:79], v[78:79], v[94:95], v[98:99]
.LBB0_1884:
	v_pk_fma_f32 v[74:75], v[92:93], s[72:73], v[74:75] op_sel_hi:[1,0,1]
	v_pk_fma_f32 v[72:73], v[78:79], s[72:73], v[72:73] op_sel_hi:[1,0,1]
	s_and_b64 vcc, exec, s[44:45]
	v_cvt_pk_bf16_f32 v72, v72, v73
	v_cvt_pk_bf16_f32 v73, v74, v75
	global_store_dwordx2 v[80:81], v[72:73], off offset:256
	s_waitcnt vmcnt(21)
	v_mov_b64_e32 v[78:79], v[240:241]
	global_load_dwordx2 v[240:241], v243, s[46:47] offset:288
	s_waitcnt lgkmcnt(0)
	v_lshlrev_b32_e32 v74, 16, v78
	v_and_b32_e32 v75, 0xffff0000, v78
	v_lshlrev_b32_e32 v78, 16, v79
	v_and_b32_e32 v79, 0xffff0000, v79
	s_cbranch_vccnz .LBB0_1886
	v_sub_f32_e32 v75, v75, v87
	v_sub_f32_e32 v74, v74, v87
	v_sub_f32_e32 v79, v79, v87
	v_sub_f32_e32 v78, v78, v87
	v_pk_mul_f32 v[74:75], v[88:89], v[74:75]
	v_mov_b32_e32 v89, v88
	v_pk_mul_f32 v[78:79], v[88:89], v[78:79]
	ds_read_b128 v[86:89], v244 offset:192
	ds_read_b128 v[90:93], v244 offset:448
	s_waitcnt lgkmcnt(0)
	v_pk_fma_f32 v[78:79], v[78:79], v[88:89], v[92:93]
	v_pk_fma_f32 v[74:75], v[74:75], v[86:87], v[90:91]

; __device__ __forceinline__ void stats_main(const float* stm, int row, int fq, float& mu, float& rs) {
;     const f32x4* p = (const f32x4*)(stm + (size_t)row * 32 + fq * 8);
;     const f32x4 a = p[0], b = p[1];
;     float s1 = (a.x + a.z) + (b.x + b.z), s2 = (a.y + a.w) + (b.y + b.w);
;     s1 += __shfl_xor(s1, 16); s2 += __shfl_xor(s2, 16); s1 += __shfl_xor(s1, 32); s2 += __shfl_xor(s2, 32);
;     mu = s1 * (1.f / DM); rs = __builtin_amdgcn_rsqf(fmaxf(s2 * (1.f / DM) - mu * mu, 0.f) + LN_EPS);
; }
.LBB0_1888:
	s_or_b64 exec, exec, s[0:1]
	v_add_u32_e32 v76, 0x80, v146
	v_ashrrev_i32_e32 v77, 31, v76
	s_and_b64 vcc, exec, s[44:45]
	v_lshlrev_b64 v[68:69], 7, v[76:77]
	s_cbranch_vccnz .LBB0_1890
	v_lshl_add_u64 v[74:75], v[134:135], 0, v[68:69]
	s_waitcnt lgkmcnt(0)
	s_waitcnt vmcnt(20)
	v_mov_b64_e32 v[70:71], v[194:195]
	v_mov_b64_e32 v[72:73], v[196:197]
	s_waitcnt vmcnt(21)
	v_mov_b64_e32 v[78:79], v[190:191]
	v_mov_b64_e32 v[80:81], v[192:193]
	s_waitcnt lgkmcnt(0)
	v_mov_b32_e32 v74, v70
	s_waitcnt lgkmcnt(0)
	v_mov_b32_e32 v75, v78
	v_mov_b32_e32 v82, v72
	v_mov_b32_e32 v83, v80
	v_pk_add_f32 v[74:75], v[74:75], v[82:83]
	v_add_f32_e32 v70, v71, v73
	v_add_f32_e32 v72, v79, v81
	v_mov_b32_e32 v71, v74
	v_mov_b32_e32 v73, v75
	v_pk_add_f32 v[70:71], v[70:71], v[72:73]
	ds_bpermute_b32 v73, v165, v71
	ds_bpermute_b32 v72, v165, v70
	s_waitcnt lgkmcnt(0)
	v_pk_add_f32 v[70:71], v[70:71], v[72:73]
	ds_bpermute_b32 v73, v164, v71
	ds_bpermute_b32 v72, v164, v70
	s_waitcnt lgkmcnt(0)
	v_pk_add_f32 v[70:71], v[70:71], v[72:73]
	s_nop 0
	v_pk_mul_f32 v[70:71], v[70:71], s[82:83] op_sel_hi:[1,0]
	s_nop 0
	v_fma_f32 v3, -v71, v71, v70
	v_max_f32_e32 v3, 0, v3
	v_add_f32_e32 v3, 0x3727c5ac, v3
	v_rsq_f32_e32 v72, v3
	s_branch .LBB0_1891

; __device__ __forceinline__ u32x2 pk4(f32x4 v) { u32x2 r; r.x = pk2(v.x, v.y); r.y = pk2(v.z, v.w); return r; }
;     __device__ __forceinline__ void operator()(const f32x4 (&acc)[2][2][4][2], const pg8::Unit& u, int wr, int wc, int fr, int fq) const {
;     ...
;                 for (int bj = 0; bj < 2; ++bj)
; #pragma unroll
;                     for (int n = 0; n < 2; ++n) {
;                         const int col = u.pn * 256 + bj * 128 + wc * 32 + n * 16 + fq * 4;
;                         const u32x2 raw = *(const u32x2*)(src + (size_t)row * DM + col);
;                         f32x4 x = (f32x4){bflo(raw.x), bfhi(raw.x), bflo(raw.y), bfhi(raw.y)};
;                         if (ln) x = (x - mu) * rs * *(const f32x4*)(g + col) + *(const f32x4*)(b + col);
;                         const u32x2 pz = pk4(x * ALPHA + acc[ai][bj][m][n]);
;                         *(u32x2*)(dst + (size_t)row * DM + col) = pz;
;                         const float z0 = bflo(pz.x), z1 = bfhi(pz.x), z2 = bflo(pz.y), z3 = bfhi(pz.y);
;                         s1 += (z0 + z1) + (z2 + z3); s2 += (z0 * z0 + z1 * z1) + (z2 * z2 + z3 * z3);
;                     }
.LBB0_1891:
	v_lshlrev_b64 v[74:75], 11, v[76:77]
	v_lshl_add_u64 v[74:75], s[46:47], 0, v[74:75]
	v_lshl_add_u64 v[74:75], v[144:145], 1, v[74:75]
	v_add_u32_e32 v243, 0x50000, v242
	s_waitcnt vmcnt(19)
	v_mov_b64_e32 v[80:81], v[198:199]
	global_load_dwordx4 v[190:193], v[248:249], off offset:16
	global_load_dwordx4 v[194:197], v[248:249], off
	global_load_dwordx2 v[198:199], v243, s[46:47]
	v_mov_b32_e32 v73, v72
	s_and_b64 vcc, exec, s[44:45]
	s_waitcnt lgkmcnt(0)
	v_lshlrev_b32_e32 v78, 16, v80
	v_and_b32_e32 v79, 0xffff0000, v80
	v_lshlrev_b32_e32 v80, 16, v81
	v_and_b32_e32 v81, 0xffff0000, v81
	s_cbranch_vccnz .LBB0_1893
	v_sub_f32_e32 v79, v79, v71
	v_sub_f32_e32 v78, v78, v71
	v_sub_f32_e32 v81, v81, v71
	v_sub_f32_e32 v80, v80, v71
	v_pk_mul_f32 v[86:87], v[72:73], v[78:79]
	v_mov_b32_e32 v78, v72
	v_mov_b32_e32 v79, v72
	v_pk_mul_f32 v[88:89], v[78:79], v[80:81]
	ds_read_b128 v[78:81], v244
	ds_read_b128 v[82:85], v244 offset:256
	s_waitcnt lgkmcnt(0)
	v_pk_fma_f32 v[80:81], v[88:89], v[80:81], v[84:85]
	v_pk_fma_f32 v[78:79], v[86:87], v[78:79], v[82:83]
.LBB0_1893:
	v_lshlrev_b64 v[76:77], 10, v[76:77]
	v_pk_fma_f32 v[64:65], v[78:79], s[72:73], v[64:65] op_sel_hi:[1,0,1]
	v_pk_fma_f32 v[80:81], v[80:81], s[72:73], v[66:67] op_sel_hi:[1,0,1]
	v_cvt_pk_bf16_f32 v66, v64, v65
	v_lshl_add_u64 v[64:65], v[76:77], 1, s[70:71]
	v_cvt_pk_bf16_f32 v67, v80, v81
	v_lshl_add_u64 v[64:65], v[144:145], 1, v[64:65]
	global_store_dwordx2 v[64:65], v[66:67], off
	s_waitcnt vmcnt(21)
	v_mov_b64_e32 v[78:79], v[200:201]
	global_load_dwordx2 v[200:201], v243, s[46:47] offset:32
	s_and_b64 vcc, exec, s[44:45]
	s_waitcnt lgkmcnt(0)
	v_lshlrev_b32_e32 v76, 16, v78
	v_and_b32_e32 v77, 0xffff0000, v78
	v_lshlrev_b32_e32 v78, 16, v79
	v_and_b32_e32 v79, 0xffff0000, v79
	s_cbranch_vccnz .LBB0_1895
	v_sub_f32_e32 v77, v77, v71
	v_sub_f32_e32 v76, v76, v71
	v_sub_f32_e32 v79, v79, v71
	v_sub_f32_e32 v78, v78, v71
	v_pk_mul_f32 v[84:85], v[72:73], v[76:77]
	v_mov_b32_e32 v76, v72
	v_mov_b32_e32 v77, v72
	v_pk_mul_f32 v[86:87], v[76:77], v[78:79]
	ds_read_b128 v[76:79], v244 offset:64
	ds_read_b128 v[80:83], v244 offset:320
	s_waitcnt lgkmcnt(0)
	v_pk_fma_f32 v[78:79], v[86:87], v[78:79], v[82:83]
	v_pk_fma_f32 v[76:77], v[84:85], v[76:77], v[80:81]
.LBB0_1895:
	v_pk_fma_f32 v[62:63], v[78:79], s[72:73], v[62:63] op_sel_hi:[1,0,1]
	v_pk_fma_f32 v[60:61], v[76:77], s[72:73], v[60:61] op_sel_hi:[1,0,1]
	s_and_b64 vcc, exec, s[44:45]
	v_cvt_pk_bf16_f32 v60, v60, v61
	v_cvt_pk_bf16_f32 v61, v62, v63
	global_store_dwordx2 v[64:65], v[60:61], off offset:32
	s_waitcnt vmcnt(21)
	v_mov_b64_e32 v[76:77], v[202:203]
	global_load_dwordx2 v[202:203], v243, s[46:47] offset:256
	s_waitcnt lgkmcnt(0)
	v_lshlrev_b32_e32 v62, 16, v76
	v_and_b32_e32 v63, 0xffff0000, v76
	v_lshlrev_b32_e32 v76, 16, v77
	v_and_b32_e32 v77, 0xffff0000, v77
	s_cbranch_vccnz .LBB0_1897
	v_sub_f32_e32 v77, v77, v71
	v_sub_f32_e32 v76, v76, v71
	v_mov_b32_e32 v78, v72
	v_mov_b32_e32 v79, v72
	v_pk_mul_f32 v[76:77], v[78:79], v[76:77]
	ds_read_b128 v[78:81], v244 offset:128
	ds_read_b128 v[82:85], v244 offset:384
	v_sub_f32_e32 v63, v63, v71
	v_sub_f32_e32 v62, v62, v71
	v_pk_mul_f32 v[62:63], v[72:73], v[62:63]
	s_waitcnt lgkmcnt(0)
	v_pk_fma_f32 v[76:77], v[76:77], v[80:81], v[84:85]
	v_pk_fma_f32 v[62:63], v[62:63], v[78:79], v[82:83]
.LBB0_1897:
	v_pk_fma_f32 v[58:59], v[76:77], s[72:73], v[58:59] op_sel_hi:[1,0,1]
	v_pk_fma_f32 v[56:57], v[62:63], s[72:73], v[56:57] op_sel_hi:[1,0,1]
	s_and_b64 vcc, exec, s[44:45]
	v_cvt_pk_bf16_f32 v56, v56, v57
	v_cvt_pk_bf16_f32 v57, v58, v59
	global_store_dwordx2 v[64:65], v[56:57], off offset:256
	s_waitcnt vmcnt(21)
	v_mov_b64_e32 v[62:63], v[204:205]
	global_load_dwordx2 v[204:205], v243, s[46:47] offset:288
	s_waitcnt lgkmcnt(0)
	v_lshlrev_b32_e32 v58, 16, v62
	v_and_b32_e32 v59, 0xffff0000, v62
	v_lshlrev_b32_e32 v62, 16, v63
	v_and_b32_e32 v63, 0xffff0000, v63
	s_cbranch_vccnz .LBB0_1899
	v_sub_f32_e32 v59, v59, v71
	v_sub_f32_e32 v58, v58, v71
	v_sub_f32_e32 v63, v63, v71
	v_sub_f32_e32 v62, v62, v71
	v_pk_mul_f32 v[58:59], v[72:73], v[58:59]
	v_mov_b32_e32 v73, v72
	v_pk_mul_f32 v[62:63], v[72:73], v[62:63]
	ds_read_b128 v[70:73], v244 offset:192
	ds_read_b128 v[74:77], v244 offset:448
	s_waitcnt lgkmcnt(0)
	v_pk_fma_f32 v[62:63], v[62:63], v[72:73], v[76:77]
	v_pk_fma_f32 v[58:59], v[58:59], v[70:71], v[74:75]

; __device__ __forceinline__ void stats_main(const float* stm, int row, int fq, float& mu, float& rs) {
;     const f32x4* p = (const f32x4*)(stm + (size_t)row * 32 + fq * 8);
;     const f32x4 a = p[0], b = p[1];
;     float s1 = (a.x + a.z) + (b.x + b.z), s2 = (a.y + a.w) + (b.y + b.w);
;     s1 += __shfl_xor(s1, 16); s2 += __shfl_xor(s2, 16); s1 += __shfl_xor(s1, 32); s2 += __shfl_xor(s2, 32);
;     mu = s1 * (1.f / DM); rs = __builtin_amdgcn_rsqf(fmaxf(s2 * (1.f / DM) - mu * mu, 0.f) + LN_EPS);
; }
.LBB0_1901:
	s_or_b64 exec, exec, s[0:1]
	v_add_u32_e32 v60, 0x90, v146
	v_ashrrev_i32_e32 v61, 31, v60
	s_and_b64 vcc, exec, s[44:45]
	v_lshlrev_b64 v[52:53], 7, v[60:61]
	s_cbranch_vccnz .LBB0_1903
	v_lshl_add_u64 v[58:59], v[134:135], 0, v[52:53]
	s_waitcnt lgkmcnt(0)
	s_waitcnt vmcnt(20)
	v_mov_b64_e32 v[54:55], v[214:215]
	v_mov_b64_e32 v[56:57], v[216:217]
	s_waitcnt vmcnt(21)
	v_mov_b64_e32 v[62:63], v[206:207]
	v_mov_b64_e32 v[64:65], v[208:209]
	s_waitcnt lgkmcnt(0)
	v_mov_b32_e32 v58, v54
	s_waitcnt lgkmcnt(0)
	v_mov_b32_e32 v59, v62
	v_mov_b32_e32 v66, v56
	v_mov_b32_e32 v67, v64
	v_pk_add_f32 v[58:59], v[58:59], v[66:67]
	v_add_f32_e32 v54, v55, v57
	v_add_f32_e32 v56, v63, v65
	v_mov_b32_e32 v55, v58
	v_mov_b32_e32 v57, v59
	v_pk_add_f32 v[54:55], v[54:55], v[56:57]
	ds_bpermute_b32 v57, v165, v55
	ds_bpermute_b32 v56, v165, v54
	s_waitcnt lgkmcnt(0)
	v_pk_add_f32 v[54:55], v[54:55], v[56:57]
	ds_bpermute_b32 v57, v164, v55
	ds_bpermute_b32 v56, v164, v54
	s_waitcnt lgkmcnt(0)
	v_pk_add_f32 v[54:55], v[54:55], v[56:57]
	s_nop 0
	v_pk_mul_f32 v[54:55], v[54:55], s[82:83] op_sel_hi:[1,0]
	s_nop 0
	v_fma_f32 v3, -v55, v55, v54
	v_max_f32_e32 v3, 0, v3
	v_add_f32_e32 v3, 0x3727c5ac, v3
	v_rsq_f32_e32 v56, v3
	s_branch .LBB0_1904

; __device__ __forceinline__ u32x2 pk4(f32x4 v) { u32x2 r; r.x = pk2(v.x, v.y); r.y = pk2(v.z, v.w); return r; }
;     __device__ __forceinline__ void operator()(const f32x4 (&acc)[2][2][4][2], const pg8::Unit& u, int wr, int wc, int fr, int fq) const {
;     ...
;                 for (int bj = 0; bj < 2; ++bj)
; #pragma unroll
;                     for (int n = 0; n < 2; ++n) {
;                         const int col = u.pn * 256 + bj * 128 + wc * 32 + n * 16 + fq * 4;
;                         const u32x2 raw = *(const u32x2*)(src + (size_t)row * DM + col);
;                         f32x4 x = (f32x4){bflo(raw.x), bfhi(raw.x), bflo(raw.y), bfhi(raw.y)};
;                         if (ln) x = (x - mu) * rs * *(const f32x4*)(g + col) + *(const f32x4*)(b + col);
;                         const u32x2 pz = pk4(x * ALPHA + acc[ai][bj][m][n]);
;                         *(u32x2*)(dst + (size_t)row * DM + col) = pz;
;                         const float z0 = bflo(pz.x), z1 = bfhi(pz.x), z2 = bflo(pz.y), z3 = bfhi(pz.y);
;                         s1 += (z0 + z1) + (z2 + z3); s2 += (z0 * z0 + z1 * z1) + (z2 * z2 + z3 * z3);
;                     }
.LBB0_1904:
	v_lshlrev_b64 v[58:59], 11, v[60:61]
	v_lshl_add_u64 v[58:59], s[46:47], 0, v[58:59]
	v_lshl_add_u64 v[58:59], v[144:145], 1, v[58:59]
	v_add_u32_e32 v243, 0x58000, v242
	s_waitcnt vmcnt(19)
	v_mov_b64_e32 v[64:65], v[234:235]
	global_load_dwordx4 v[206:209], v[248:249], off offset:2064
	global_load_dwordx4 v[214:217], v[248:249], off offset:2048
	global_load_dwordx2 v[234:235], v243, s[46:47]
	v_mov_b32_e32 v57, v56
	s_and_b64 vcc, exec, s[44:45]
	s_waitcnt lgkmcnt(0)
	v_lshlrev_b32_e32 v62, 16, v64
	v_and_b32_e32 v63, 0xffff0000, v64
	v_lshlrev_b32_e32 v64, 16, v65
	v_and_b32_e32 v65, 0xffff0000, v65
	s_cbranch_vccnz .LBB0_1906
	v_sub_f32_e32 v63, v63, v55
	v_sub_f32_e32 v62, v62, v55
	v_sub_f32_e32 v65, v65, v55
	v_sub_f32_e32 v64, v64, v55
	v_pk_mul_f32 v[70:71], v[56:57], v[62:63]
	v_mov_b32_e32 v62, v56
	v_mov_b32_e32 v63, v56
	v_pk_mul_f32 v[72:73], v[62:63], v[64:65]
	ds_read_b128 v[62:65], v244
	ds_read_b128 v[66:69], v244 offset:256
	s_waitcnt lgkmcnt(0)
	v_pk_fma_f32 v[64:65], v[72:73], v[64:65], v[68:69]
	v_pk_fma_f32 v[62:63], v[70:71], v[62:63], v[66:67]
.LBB0_1906:
	v_lshlrev_b64 v[60:61], 10, v[60:61]
	v_pk_fma_f32 v[48:49], v[62:63], s[72:73], v[48:49] op_sel_hi:[1,0,1]
	v_pk_fma_f32 v[64:65], v[64:65], s[72:73], v[50:51] op_sel_hi:[1,0,1]
	v_cvt_pk_bf16_f32 v50, v48, v49
	v_lshl_add_u64 v[48:49], v[60:61], 1, s[70:71]
	v_cvt_pk_bf16_f32 v51, v64, v65
	v_lshl_add_u64 v[48:49], v[144:145], 1, v[48:49]
	global_store_dwordx2 v[48:49], v[50:51], off
	s_waitcnt vmcnt(21)
	v_mov_b64_e32 v[62:63], v[236:237]
	global_load_dwordx2 v[236:237], v243, s[46:47] offset:32
	s_and_b64 vcc, exec, s[44:45]
	s_waitcnt lgkmcnt(0)
	v_lshlrev_b32_e32 v60, 16, v62
	v_and_b32_e32 v61, 0xffff0000, v62
	v_lshlrev_b32_e32 v62, 16, v63
	v_and_b32_e32 v63, 0xffff0000, v63
	s_cbranch_vccnz .LBB0_1908
	v_sub_f32_e32 v61, v61, v55
	v_sub_f32_e32 v60, v60, v55
	v_sub_f32_e32 v63, v63, v55
	v_sub_f32_e32 v62, v62, v55
	v_pk_mul_f32 v[68:69], v[56:57], v[60:61]
	v_mov_b32_e32 v60, v56
	v_mov_b32_e32 v61, v56
	v_pk_mul_f32 v[70:71], v[60:61], v[62:63]
	ds_read_b128 v[60:63], v244 offset:64
	ds_read_b128 v[64:67], v244 offset:320
	s_waitcnt lgkmcnt(0)
	v_pk_fma_f32 v[62:63], v[70:71], v[62:63], v[66:67]
	v_pk_fma_f32 v[60:61], v[68:69], v[60:61], v[64:65]
.LBB0_1908:
	v_pk_fma_f32 v[46:47], v[62:63], s[72:73], v[46:47] op_sel_hi:[1,0,1]
	v_pk_fma_f32 v[44:45], v[60:61], s[72:73], v[44:45] op_sel_hi:[1,0,1]
	s_and_b64 vcc, exec, s[44:45]
	v_cvt_pk_bf16_f32 v44, v44, v45
	v_cvt_pk_bf16_f32 v45, v46, v47
	global_store_dwordx2 v[48:49], v[44:45], off offset:32
	s_waitcnt vmcnt(21)
	v_mov_b64_e32 v[60:61], v[238:239]
	global_load_dwordx2 v[238:239], v243, s[46:47] offset:256
	s_waitcnt lgkmcnt(0)
	v_lshlrev_b32_e32 v46, 16, v60
	v_and_b32_e32 v47, 0xffff0000, v60
	v_lshlrev_b32_e32 v60, 16, v61
	v_and_b32_e32 v61, 0xffff0000, v61
	s_cbranch_vccnz .LBB0_1910
	v_sub_f32_e32 v61, v61, v55
	v_sub_f32_e32 v60, v60, v55
	v_mov_b32_e32 v62, v56
	v_mov_b32_e32 v63, v56
	v_pk_mul_f32 v[60:61], v[62:63], v[60:61]
	ds_read_b128 v[62:65], v244 offset:128
	ds_read_b128 v[66:69], v244 offset:384
	v_sub_f32_e32 v47, v47, v55
	v_sub_f32_e32 v46, v46, v55
	v_pk_mul_f32 v[46:47], v[56:57], v[46:47]
	s_waitcnt lgkmcnt(0)
	v_pk_fma_f32 v[60:61], v[60:61], v[64:65], v[68:69]
	v_pk_fma_f32 v[46:47], v[46:47], v[62:63], v[66:67]
.LBB0_1910:
	v_pk_fma_f32 v[42:43], v[60:61], s[72:73], v[42:43] op_sel_hi:[1,0,1]
	v_pk_fma_f32 v[40:41], v[46:47], s[72:73], v[40:41] op_sel_hi:[1,0,1]
	s_and_b64 vcc, exec, s[44:45]
	v_cvt_pk_bf16_f32 v40, v40, v41
	v_cvt_pk_bf16_f32 v41, v42, v43
	global_store_dwordx2 v[48:49], v[40:41], off offset:256
	s_waitcnt vmcnt(21)
	v_mov_b64_e32 v[46:47], v[240:241]
	global_load_dwordx2 v[240:241], v243, s[46:47] offset:288
	s_waitcnt lgkmcnt(0)
	v_lshlrev_b32_e32 v42, 16, v46
	v_and_b32_e32 v43, 0xffff0000, v46
	v_lshlrev_b32_e32 v46, 16, v47
	v_and_b32_e32 v47, 0xffff0000, v47
	s_cbranch_vccnz .LBB0_1912
	v_sub_f32_e32 v43, v43, v55
	v_sub_f32_e32 v42, v42, v55
	v_sub_f32_e32 v47, v47, v55
	v_sub_f32_e32 v46, v46, v55
	v_pk_mul_f32 v[42:43], v[56:57], v[42:43]
	v_mov_b32_e32 v57, v56
	v_pk_mul_f32 v[46:47], v[56:57], v[46:47]
	ds_read_b128 v[54:57], v244 offset:192
	ds_read_b128 v[58:61], v244 offset:448
	s_waitcnt lgkmcnt(0)
	v_pk_fma_f32 v[46:47], v[46:47], v[56:57], v[60:61]
	v_pk_fma_f32 v[42:43], v[42:43], v[54:55], v[58:59]

; __device__ __forceinline__ void stats_main(const float* stm, int row, int fq, float& mu, float& rs) {
;     const f32x4* p = (const f32x4*)(stm + (size_t)row * 32 + fq * 8);
;     const f32x4 a = p[0], b = p[1];
;     float s1 = (a.x + a.z) + (b.x + b.z), s2 = (a.y + a.w) + (b.y + b.w);
;     s1 += __shfl_xor(s1, 16); s2 += __shfl_xor(s2, 16); s1 += __shfl_xor(s1, 32); s2 += __shfl_xor(s2, 32);
;     mu = s1 * (1.f / DM); rs = __builtin_amdgcn_rsqf(fmaxf(s2 * (1.f / DM) - mu * mu, 0.f) + LN_EPS);
; }
.LBB0_1914:
	s_or_b64 exec, exec, s[0:1]
	v_add_u32_e32 v44, 0xa0, v146
	v_ashrrev_i32_e32 v45, 31, v44
	s_and_b64 vcc, exec, s[44:45]
	v_lshlrev_b64 v[36:37], 7, v[44:45]
	s_cbranch_vccnz .LBB0_1916
	v_lshl_add_u64 v[42:43], v[134:135], 0, v[36:37]
	s_waitcnt lgkmcnt(0)
	s_waitcnt vmcnt(20)
	v_mov_b64_e32 v[38:39], v[194:195]
	v_mov_b64_e32 v[40:41], v[196:197]
	s_waitcnt vmcnt(21)
	v_mov_b64_e32 v[46:47], v[190:191]
	v_mov_b64_e32 v[48:49], v[192:193]
	s_waitcnt lgkmcnt(0)
	v_mov_b32_e32 v42, v38
	s_waitcnt lgkmcnt(0)
	v_mov_b32_e32 v43, v46
	v_mov_b32_e32 v50, v40
	v_mov_b32_e32 v51, v48
	v_pk_add_f32 v[42:43], v[42:43], v[50:51]
	v_add_f32_e32 v38, v39, v41
	v_add_f32_e32 v40, v47, v49
	v_mov_b32_e32 v39, v42
	v_mov_b32_e32 v41, v43
	v_pk_add_f32 v[38:39], v[38:39], v[40:41]
	ds_bpermute_b32 v41, v165, v39
	ds_bpermute_b32 v40, v165, v38
	s_waitcnt lgkmcnt(0)
	v_pk_add_f32 v[38:39], v[38:39], v[40:41]
	ds_bpermute_b32 v41, v164, v39
	ds_bpermute_b32 v40, v164, v38
	s_waitcnt lgkmcnt(0)
	v_pk_add_f32 v[38:39], v[38:39], v[40:41]
	s_nop 0
	v_pk_mul_f32 v[38:39], v[38:39], s[82:83] op_sel_hi:[1,0]
	s_nop 0
	v_fma_f32 v3, -v39, v39, v38
	v_max_f32_e32 v3, 0, v3
	v_add_f32_e32 v3, 0x3727c5ac, v3
	v_rsq_f32_e32 v40, v3
	s_branch .LBB0_1917

; __device__ __forceinline__ u32x2 pk4(f32x4 v) { u32x2 r; r.x = pk2(v.x, v.y); r.y = pk2(v.z, v.w); return r; }
;     __device__ __forceinline__ void operator()(const f32x4 (&acc)[2][2][4][2], const pg8::Unit& u, int wr, int wc, int fr, int fq) const {
;     ...
;                 for (int bj = 0; bj < 2; ++bj)
; #pragma unroll
;                     for (int n = 0; n < 2; ++n) {
;                         const int col = u.pn * 256 + bj * 128 + wc * 32 + n * 16 + fq * 4;
;                         const u32x2 raw = *(const u32x2*)(src + (size_t)row * DM + col);
;                         f32x4 x = (f32x4){bflo(raw.x), bfhi(raw.x), bflo(raw.y), bfhi(raw.y)};
;                         if (ln) x = (x - mu) * rs * *(const f32x4*)(g + col) + *(const f32x4*)(b + col);
;                         const u32x2 pz = pk4(x * ALPHA + acc[ai][bj][m][n]);
;                         *(u32x2*)(dst + (size_t)row * DM + col) = pz;
;                         const float z0 = bflo(pz.x), z1 = bfhi(pz.x), z2 = bflo(pz.y), z3 = bfhi(pz.y);
;                         s1 += (z0 + z1) + (z2 + z3); s2 += (z0 * z0 + z1 * z1) + (z2 * z2 + z3 * z3);
.LBB0_1917:
	v_lshlrev_b64 v[42:43], 11, v[44:45]
	v_lshl_add_u64 v[42:43], s[46:47], 0, v[42:43]
	v_lshl_add_u64 v[42:43], v[144:145], 1, v[42:43]
	s_waitcnt vmcnt(19)
	v_mov_b64_e32 v[48:49], v[198:199]
	v_mov_b32_e32 v41, v40
	s_and_b64 vcc, exec, s[44:45]
	s_waitcnt lgkmcnt(0)
	v_lshlrev_b32_e32 v46, 16, v48
	v_and_b32_e32 v47, 0xffff0000, v48
	v_lshlrev_b32_e32 v48, 16, v49
	v_and_b32_e32 v49, 0xffff0000, v49
	s_cbranch_vccnz .LBB0_1919
	v_sub_f32_e32 v47, v47, v39
	v_sub_f32_e32 v46, v46, v39
	v_sub_f32_e32 v49, v49, v39
	v_sub_f32_e32 v48, v48, v39
	v_pk_mul_f32 v[54:55], v[40:41], v[46:47]
	v_mov_b32_e32 v46, v40
	v_mov_b32_e32 v47, v40
	v_pk_mul_f32 v[56:57], v[46:47], v[48:49]
	ds_read_b128 v[46:49], v244
	ds_read_b128 v[50:53], v244 offset:256
	s_waitcnt lgkmcnt(0)
	v_pk_fma_f32 v[48:49], v[56:57], v[48:49], v[52:53]
	v_pk_fma_f32 v[46:47], v[54:55], v[46:47], v[50:51]
.LBB0_1919:
	v_lshlrev_b64 v[44:45], 10, v[44:45]
	v_pk_fma_f32 v[32:33], v[46:47], s[72:73], v[32:33] op_sel_hi:[1,0,1]
	v_pk_fma_f32 v[48:49], v[48:49], s[72:73], v[34:35] op_sel_hi:[1,0,1]
	v_cvt_pk_bf16_f32 v34, v32, v33
	v_lshl_add_u64 v[32:33], v[44:45], 1, s[70:71]
	v_cvt_pk_bf16_f32 v35, v48, v49
	v_lshl_add_u64 v[32:33], v[144:145], 1, v[32:33]
	global_store_dwordx2 v[32:33], v[34:35], off
	s_waitcnt vmcnt(18)
	v_mov_b64_e32 v[46:47], v[200:201]
	s_and_b64 vcc, exec, s[44:45]
	s_waitcnt lgkmcnt(0)
	v_lshlrev_b32_e32 v44, 16, v46
	v_and_b32_e32 v45, 0xffff0000, v46
	v_lshlrev_b32_e32 v46, 16, v47
	v_and_b32_e32 v47, 0xffff0000, v47
	s_cbranch_vccnz .LBB0_1921
	v_sub_f32_e32 v45, v45, v39
	v_sub_f32_e32 v44, v44, v39
	v_sub_f32_e32 v47, v47, v39
	v_sub_f32_e32 v46, v46, v39
	v_pk_mul_f32 v[52:53], v[40:41], v[44:45]
	v_mov_b32_e32 v44, v40
	v_mov_b32_e32 v45, v40
	v_pk_mul_f32 v[54:55], v[44:45], v[46:47]
	ds_read_b128 v[44:47], v244 offset:64
	ds_read_b128 v[48:51], v244 offset:320
	s_waitcnt lgkmcnt(0)
	v_pk_fma_f32 v[46:47], v[54:55], v[46:47], v[50:51]
	v_pk_fma_f32 v[44:45], v[52:53], v[44:45], v[48:49]
.LBB0_1921:
	v_pk_fma_f32 v[30:31], v[46:47], s[72:73], v[30:31] op_sel_hi:[1,0,1]
	v_pk_fma_f32 v[28:29], v[44:45], s[72:73], v[28:29] op_sel_hi:[1,0,1]
	s_and_b64 vcc, exec, s[44:45]
	v_cvt_pk_bf16_f32 v28, v28, v29
	v_cvt_pk_bf16_f32 v29, v30, v31
	global_store_dwordx2 v[32:33], v[28:29], off offset:32
	s_waitcnt vmcnt(17)
	v_mov_b64_e32 v[44:45], v[202:203]
	s_waitcnt lgkmcnt(0)
	v_lshlrev_b32_e32 v30, 16, v44
	v_and_b32_e32 v31, 0xffff0000, v44
	v_lshlrev_b32_e32 v44, 16, v45
	v_and_b32_e32 v45, 0xffff0000, v45
	s_cbranch_vccnz .LBB0_1923
	v_sub_f32_e32 v45, v45, v39
	v_sub_f32_e32 v44, v44, v39
	v_mov_b32_e32 v46, v40
	v_mov_b32_e32 v47, v40
	v_pk_mul_f32 v[44:45], v[46:47], v[44:45]
	ds_read_b128 v[46:49], v244 offset:128
	ds_read_b128 v[50:53], v244 offset:384
	v_sub_f32_e32 v31, v31, v39
	v_sub_f32_e32 v30, v30, v39
	v_pk_mul_f32 v[30:31], v[40:41], v[30:31]
	s_waitcnt lgkmcnt(0)
	v_pk_fma_f32 v[44:45], v[44:45], v[48:49], v[52:53]
	v_pk_fma_f32 v[30:31], v[30:31], v[46:47], v[50:51]
.LBB0_1923:
	v_pk_fma_f32 v[26:27], v[44:45], s[72:73], v[26:27] op_sel_hi:[1,0,1]
	v_pk_fma_f32 v[24:25], v[30:31], s[72:73], v[24:25] op_sel_hi:[1,0,1]
	s_and_b64 vcc, exec, s[44:45]
	v_cvt_pk_bf16_f32 v24, v24, v25
	v_cvt_pk_bf16_f32 v25, v26, v27
	global_store_dwordx2 v[32:33], v[24:25], off offset:256
	s_waitcnt vmcnt(16)
	v_mov_b64_e32 v[30:31], v[204:205]
	s_waitcnt lgkmcnt(0)
	v_lshlrev_b32_e32 v26, 16, v30
	v_and_b32_e32 v27, 0xffff0000, v30
	v_lshlrev_b32_e32 v30, 16, v31
	v_and_b32_e32 v31, 0xffff0000, v31
	s_cbranch_vccnz .LBB0_1925
	v_sub_f32_e32 v27, v27, v39
	v_sub_f32_e32 v26, v26, v39
	v_sub_f32_e32 v31, v31, v39
	v_sub_f32_e32 v30, v30, v39
	v_pk_mul_f32 v[26:27], v[40:41], v[26:27]
	v_mov_b32_e32 v41, v40
	v_pk_mul_f32 v[30:31], v[40:41], v[30:31]
	ds_read_b128 v[38:41], v244 offset:192
	ds_read_b128 v[42:45], v244 offset:448
	s_waitcnt lgkmcnt(0)
	v_pk_fma_f32 v[30:31], v[30:31], v[40:41], v[44:45]
	v_pk_fma_f32 v[26:27], v[26:27], v[38:39], v[42:43]

; __device__ __forceinline__ void stats_main(const float* stm, int row, int fq, float& mu, float& rs) {
;     const f32x4* p = (const f32x4*)(stm + (size_t)row * 32 + fq * 8);
;     const f32x4 a = p[0], b = p[1];
;     float s1 = (a.x + a.z) + (b.x + b.z), s2 = (a.y + a.w) + (b.y + b.w);
;     s1 += __shfl_xor(s1, 16); s2 += __shfl_xor(s2, 16); s1 += __shfl_xor(s1, 32); s2 += __shfl_xor(s2, 32);
;     mu = s1 * (1.f / DM); rs = __builtin_amdgcn_rsqf(fmaxf(s2 * (1.f / DM) - mu * mu, 0.f) + LN_EPS);
; }
;     __device__ __forceinline__ void operator()(const f32x4 (&acc)[2][2][4][2], const pg8::Unit& u, int wr, int wc, int fr, int fq) const {
;     ...
;                 const int row = u.pm * 256 + ai * 128 + wr * 64 + m * 16 + fr;
;                 float mu = 0.f, rs = 1.f; if (ln) stats_main(stm_p, row, fq, mu, rs);
.LBB0_1927:
	s_or_b64 exec, exec, s[0:1]
	v_add_u32_e32 v28, 0xb0, v146
	v_ashrrev_i32_e32 v29, 31, v28
	s_and_b64 vcc, exec, s[44:45]
	v_lshlrev_b64 v[20:21], 7, v[28:29]
	s_cbranch_vccnz .LBB0_1929
	v_lshl_add_u64 v[26:27], v[134:135], 0, v[20:21]
	s_waitcnt lgkmcnt(0)
	s_waitcnt vmcnt(14)
	v_mov_b64_e32 v[22:23], v[214:215]
	v_mov_b64_e32 v[24:25], v[216:217]
	s_waitcnt vmcnt(15)
	v_mov_b64_e32 v[30:31], v[206:207]
	v_mov_b64_e32 v[32:33], v[208:209]
	s_waitcnt lgkmcnt(0)
	v_mov_b32_e32 v26, v22
	s_waitcnt lgkmcnt(0)
	v_mov_b32_e32 v27, v30
	v_mov_b32_e32 v34, v24
	v_mov_b32_e32 v35, v32
	v_pk_add_f32 v[26:27], v[26:27], v[34:35]
	v_add_f32_e32 v22, v23, v25
	v_add_f32_e32 v24, v31, v33
	v_mov_b32_e32 v23, v26
	v_mov_b32_e32 v25, v27
	v_pk_add_f32 v[22:23], v[22:23], v[24:25]
	ds_bpermute_b32 v25, v165, v23
	ds_bpermute_b32 v24, v165, v22
	s_waitcnt lgkmcnt(0)
	v_pk_add_f32 v[22:23], v[22:23], v[24:25]
	ds_bpermute_b32 v25, v164, v23
	ds_bpermute_b32 v24, v164, v22
	s_waitcnt lgkmcnt(0)
	v_pk_add_f32 v[22:23], v[22:23], v[24:25]
	s_nop 0
	v_pk_mul_f32 v[22:23], v[22:23], s[82:83] op_sel_hi:[1,0]
	s_nop 0
	v_fma_f32 v3, -v23, v23, v22
	v_max_f32_e32 v3, 0, v3
	v_add_f32_e32 v3, 0x3727c5ac, v3
	v_rsq_f32_e32 v24, v3
	s_branch .LBB0_1930

; __device__ __forceinline__ u32x2 pk4(f32x4 v) { u32x2 r; r.x = pk2(v.x, v.y); r.y = pk2(v.z, v.w); return r; }
;     __device__ __forceinline__ void operator()(const f32x4 (&acc)[2][2][4][2], const pg8::Unit& u, int wr, int wc, int fr, int fq) const {
;     ...
;                 for (int bj = 0; bj < 2; ++bj)
; #pragma unroll
;                     for (int n = 0; n < 2; ++n) {
;                         const int col = u.pn * 256 + bj * 128 + wc * 32 + n * 16 + fq * 4;
;                         const u32x2 raw = *(const u32x2*)(src + (size_t)row * DM + col);
;                         f32x4 x = (f32x4){bflo(raw.x), bfhi(raw.x), bflo(raw.y), bfhi(raw.y)};
;                         if (ln) x = (x - mu) * rs * *(const f32x4*)(g + col) + *(const f32x4*)(b + col);
;                         const u32x2 pz = pk4(x * ALPHA + acc[ai][bj][m][n]);
;                         *(u32x2*)(dst + (size_t)row * DM + col) = pz;
;                         const float z0 = bflo(pz.x), z1 = bfhi(pz.x), z2 = bflo(pz.y), z3 = bfhi(pz.y);
;                         s1 += (z0 + z1) + (z2 + z3); s2 += (z0 * z0 + z1 * z1) + (z2 * z2 + z3 * z3);
.LBB0_1930:
	v_lshlrev_b64 v[26:27], 11, v[28:29]
	v_lshl_add_u64 v[26:27], s[46:47], 0, v[26:27]
	v_lshl_add_u64 v[26:27], v[144:145], 1, v[26:27]
	s_waitcnt vmcnt(13)
	v_mov_b64_e32 v[32:33], v[234:235]
	v_mov_b32_e32 v25, v24
	s_and_b64 vcc, exec, s[44:45]
	s_waitcnt lgkmcnt(0)
	v_lshlrev_b32_e32 v30, 16, v32
	v_and_b32_e32 v31, 0xffff0000, v32
	v_lshlrev_b32_e32 v32, 16, v33
	v_and_b32_e32 v33, 0xffff0000, v33
	s_cbranch_vccnz .LBB0_1932
	v_sub_f32_e32 v31, v31, v23
	v_sub_f32_e32 v30, v30, v23
	v_sub_f32_e32 v33, v33, v23
	v_sub_f32_e32 v32, v32, v23
	v_pk_mul_f32 v[38:39], v[24:25], v[30:31]
	v_mov_b32_e32 v30, v24
	v_mov_b32_e32 v31, v24
	v_pk_mul_f32 v[40:41], v[30:31], v[32:33]
	ds_read_b128 v[30:33], v244
	ds_read_b128 v[34:37], v244 offset:256
	s_waitcnt lgkmcnt(0)
	v_pk_fma_f32 v[32:33], v[40:41], v[32:33], v[36:37]
	v_pk_fma_f32 v[30:31], v[38:39], v[30:31], v[34:35]
.LBB0_1932:
	v_lshlrev_b64 v[28:29], 10, v[28:29]
	v_pk_fma_f32 v[16:17], v[30:31], s[72:73], v[16:17] op_sel_hi:[1,0,1]
	v_pk_fma_f32 v[32:33], v[32:33], s[72:73], v[18:19] op_sel_hi:[1,0,1]
	v_cvt_pk_bf16_f32 v18, v16, v17
	v_lshl_add_u64 v[16:17], v[28:29], 1, s[70:71]
	v_cvt_pk_bf16_f32 v19, v32, v33
	v_lshl_add_u64 v[16:17], v[144:145], 1, v[16:17]
	global_store_dwordx2 v[16:17], v[18:19], off
	s_waitcnt vmcnt(12)
	v_mov_b64_e32 v[30:31], v[236:237]
	s_and_b64 vcc, exec, s[44:45]
	s_waitcnt lgkmcnt(0)
	v_lshlrev_b32_e32 v28, 16, v30
	v_and_b32_e32 v29, 0xffff0000, v30
	v_lshlrev_b32_e32 v30, 16, v31
	v_and_b32_e32 v31, 0xffff0000, v31
	s_cbranch_vccnz .LBB0_1934
	v_sub_f32_e32 v29, v29, v23
	v_sub_f32_e32 v28, v28, v23
	v_sub_f32_e32 v31, v31, v23
	v_sub_f32_e32 v30, v30, v23
	v_pk_mul_f32 v[36:37], v[24:25], v[28:29]
	v_mov_b32_e32 v28, v24
	v_mov_b32_e32 v29, v24
	v_pk_mul_f32 v[38:39], v[28:29], v[30:31]
	ds_read_b128 v[28:31], v244 offset:64
	ds_read_b128 v[32:35], v244 offset:320
	s_waitcnt lgkmcnt(0)
	v_pk_fma_f32 v[30:31], v[38:39], v[30:31], v[34:35]
	v_pk_fma_f32 v[28:29], v[36:37], v[28:29], v[32:33]
.LBB0_1934:
	v_pk_fma_f32 v[14:15], v[30:31], s[72:73], v[14:15] op_sel_hi:[1,0,1]
	v_pk_fma_f32 v[12:13], v[28:29], s[72:73], v[12:13] op_sel_hi:[1,0,1]
	s_and_b64 vcc, exec, s[44:45]
	v_cvt_pk_bf16_f32 v12, v12, v13
	v_cvt_pk_bf16_f32 v13, v14, v15
	global_store_dwordx2 v[16:17], v[12:13], off offset:32
	s_waitcnt vmcnt(11)
	v_mov_b64_e32 v[28:29], v[238:239]
	s_waitcnt lgkmcnt(0)
	v_lshlrev_b32_e32 v14, 16, v28
	v_and_b32_e32 v15, 0xffff0000, v28
	v_lshlrev_b32_e32 v28, 16, v29
	v_and_b32_e32 v29, 0xffff0000, v29
	s_cbranch_vccnz .LBB0_1936
	v_sub_f32_e32 v29, v29, v23
	v_sub_f32_e32 v28, v28, v23
	v_mov_b32_e32 v30, v24
	v_mov_b32_e32 v31, v24
	v_pk_mul_f32 v[28:29], v[30:31], v[28:29]
	ds_read_b128 v[30:33], v244 offset:128
	ds_read_b128 v[34:37], v244 offset:384
	v_sub_f32_e32 v15, v15, v23
	v_sub_f32_e32 v14, v14, v23
	v_pk_mul_f32 v[14:15], v[24:25], v[14:15]
	s_waitcnt lgkmcnt(0)
	v_pk_fma_f32 v[28:29], v[28:29], v[32:33], v[36:37]
	v_pk_fma_f32 v[14:15], v[14:15], v[30:31], v[34:35]
.LBB0_1936:
	v_pk_fma_f32 v[10:11], v[28:29], s[72:73], v[10:11] op_sel_hi:[1,0,1]
	v_pk_fma_f32 v[8:9], v[14:15], s[72:73], v[8:9] op_sel_hi:[1,0,1]
	s_and_b64 vcc, exec, s[44:45]
	v_cvt_pk_bf16_f32 v8, v8, v9
	v_cvt_pk_bf16_f32 v9, v10, v11
	global_store_dwordx2 v[16:17], v[8:9], off offset:256
	s_waitcnt vmcnt(10)
	v_mov_b64_e32 v[14:15], v[240:241]
	s_waitcnt lgkmcnt(0)
	v_lshlrev_b32_e32 v10, 16, v14
	v_and_b32_e32 v11, 0xffff0000, v14
	v_lshlrev_b32_e32 v14, 16, v15
	v_and_b32_e32 v15, 0xffff0000, v15
	s_cbranch_vccnz .LBB0_1938
	v_sub_f32_e32 v11, v11, v23
	v_sub_f32_e32 v10, v10, v23
	v_sub_f32_e32 v15, v15, v23
	v_sub_f32_e32 v14, v14, v23
	v_pk_mul_f32 v[10:11], v[24:25], v[10:11]
	v_mov_b32_e32 v25, v24
	v_pk_mul_f32 v[14:15], v[24:25], v[14:15]
	ds_read_b128 v[22:25], v244 offset:192
	ds_read_b128 v[26:29], v244 offset:448
	s_waitcnt lgkmcnt(0)
	v_pk_fma_f32 v[14:15], v[14:15], v[24:25], v[28:29]
	v_pk_fma_f32 v[10:11], v[10:11], v[22:23], v[26:27]

; __device__ __forceinline__ u32x2 pk4(f32x4 v) { u32x2 r; r.x = pk2(v.x, v.y); r.y = pk2(v.z, v.w); return r; }
; __device__ __forceinline__ void stats_main(const float* stm, int row, int fq, float& mu, float& rs) {
;     const f32x4* p = (const f32x4*)(stm + (size_t)row * 32 + fq * 8);
;     const f32x4 a = p[0], b = p[1];
;     float s1 = (a.x + a.z) + (b.x + b.z), s2 = (a.y + a.w) + (b.y + b.w);
;     s1 += __shfl_xor(s1, 16); s2 += __shfl_xor(s2, 16); s1 += __shfl_xor(s1, 32); s2 += __shfl_xor(s2, 32);
;     mu = s1 * (1.f / DM); rs = __builtin_amdgcn_rsqf(fmaxf(s2 * (1.f / DM) - mu * mu, 0.f) + LN_EPS);
;     __device__ __forceinline__ void operator()(const f32x4 (&acc)[2][2][4][2], const pg8::Unit& u, int wr, int wc, int fr, int fq) const {
; #pragma unroll
;         for (int ai = 0; ai < 2; ++ai)
; #pragma unroll
;             for (int m = 0; m < 4; ++m) {
;                 const int row = u.pm * 256 + ai * 128 + wr * 64 + m * 16 + fr;
;                 float mu = 0.f, rs = 1.f; if (ln) stats_main(stm_p, row, fq, mu, rs);
;                 float s1 = 0.f, s2 = 0.f;
; #pragma unroll
;                 for (int bj = 0; bj < 2; ++bj)
; #pragma unroll
;                     for (int n = 0; n < 2; ++n) {
;                         const int col = u.pn * 256 + bj * 128 + wc * 32 + n * 16 + fq * 4;
;                         const u32x2 raw = *(const u32x2*)(src + (size_t)row * DM + col);
;                         f32x4 x = (f32x4){bflo(raw.x), bfhi(raw.x), bflo(raw.y), bfhi(raw.y)};
;                         if (ln) x = (x - mu) * rs * *(const f32x4*)(g + col) + *(const f32x4*)(b + col);
;                         const u32x2 pz = pk4(x * ALPHA + acc[ai][bj][m][n]);
;                         *(u32x2*)(dst + (size_t)row * DM + col) = pz;
;                         const float z0 = bflo(pz.x), z1 = bfhi(pz.x), z2 = bflo(pz.y), z3 = bfhi(pz.y);
;                         s1 += (z0 + z1) + (z2 + z3); s2 += (z0 * z0 + z1 * z1) + (z2 * z2 + z3 * z3);
.LBB0_2377:
	v_readlane_b32 s70, v250, 30
	v_readlane_b32 s71, v250, 31
	v_and_b32_e32 v244, 0xfffffff0, v166
	v_lshl_add_u32 v244, s22, 8, v244
	v_and_b32_e32 v245, 31, v219
	v_add_u32_e32 v244, v244, v245
	v_lshrrev_b32_e32 v245, 5, v219
	v_lshl_add_u32 v244, v245, 7, v244
	v_lshlrev_b32_e32 v244, 2, v244
	global_load_dword v214, v244, s[46:47]
	global_load_dword v215, v244, s[48:49]
	v_lshl_add_u32 v245, s23, 8, v164
	v_lshl_add_u32 v244, s22, 8, v166
	v_lshlrev_b32_e32 v242, 11, v245
	v_lshl_add_u32 v242, v244, 1, v242
	v_lshlrev_b32_e32 v246, 7, v245
	v_mov_b32_e32 v247, 0
	v_lshlrev_b32_e32 v248, 7, v245
	v_mov_b32_e32 v249, 0
	v_add_u32_e32 v246, 0x1000, v246
	v_add_u32_e32 v248, 0x5000, v248
	v_lshl_add_u64 v[246:247], v[246:247], 0, v[134:135]
	v_lshl_add_u64 v[248:249], v[248:249], 0, v[134:135]
	global_load_dwordx4 v[190:193], v[246:247], off offset:-4080
	global_load_dwordx4 v[194:197], v[246:247], off offset:-4096
	global_load_dwordx2 v[198:199], v242, s[70:71]
	global_load_dwordx2 v[200:201], v242, s[70:71] offset:32
	global_load_dwordx2 v[202:203], v242, s[70:71] offset:256
	global_load_dwordx2 v[204:205], v242, s[70:71] offset:288
	v_lshrrev_b32_e32 v245, 6, v164
	v_lshrrev_b32_e32 v244, 5, v166
	v_lshl_add_u32 v245, v245, 2, v244
	v_lshlrev_b32_e32 v245, 9, v245
	v_and_b32_e32 v244, 12, v166
	v_lshl_add_u32 v244, v244, 2, v245
	v_add_u32_e32 v244, 0x20000, v244
	v_lshl_add_u32 v245, v219, 2, v245
	v_add_u32_e32 v245, 0x20000, v245
	s_waitcnt vmcnt(7)
	ds_write_b32 v245, v214
	s_waitcnt vmcnt(6)
	ds_write_b32 v245, v215 offset:256
	v_add_u32_e32 v243, 0x8000, v242
	global_load_dwordx4 v[206:209], v[246:247], off offset:-2032
	global_load_dwordx4 v[214:217], v[246:247], off offset:-2048
	global_load_dwordx2 v[234:235], v243, s[70:71]
	global_load_dwordx2 v[236:237], v243, s[70:71] offset:32
	global_load_dwordx2 v[238:239], v243, s[70:71] offset:256
	global_load_dwordx2 v[240:241], v243, s[70:71] offset:288
	s_waitcnt lgkmcnt(0)
	v_and_b32_e32 v140, 64, v219
	v_lshl_add_u32 v146, s23, 8, v164
	v_xor_b32_e32 v3, 16, v219
	v_add_u32_e32 v140, 64, v140
	v_cmp_lt_i32_e32 vcc, v3, v140
	v_ashrrev_i32_e32 v147, 31, v146
	v_lshlrev_b64 v[148:149], 7, v[146:147]
	v_cndmask_b32_e32 v3, v219, v3, vcc
	v_lshlrev_b32_e32 v181, 2, v3
	v_xor_b32_e32 v3, 32, v219
	v_lshl_add_u64 v[150:151], v[134:135], 0, v[148:149]
	v_cmp_lt_i32_e32 vcc, v3, v140
	s_waitcnt vmcnt(11)
	v_mov_b64_e32 v[140:141], v[190:191]
	v_mov_b64_e32 v[142:143], v[192:193]
	global_load_dwordx4 v[190:193], v[246:247], off offset:16
	s_nop 0
	s_waitcnt vmcnt(11)
	v_mov_b64_e32 v[150:151], v[194:195]
	v_mov_b64_e32 v[152:153], v[196:197]
	global_load_dwordx4 v[194:197], v[246:247], off
	v_cndmask_b32_e32 v3, v219, v3, vcc
	v_lshlrev_b32_e32 v180, 2, v3
	v_readlane_b32 s70, v250, 30
	v_lshl_add_u32 v144, s22, 8, v166
	v_readlane_b32 s71, v250, 31
	v_ashrrev_i32_e32 v145, 31, v144
	s_lshl_b32 s0, s22, 3
	v_readlane_b32 s1, v252, 30
	s_or_b32 s68, s0, s1
	s_ashr_i32 s69, s68, 31
	s_waitcnt lgkmcnt(0)
	v_pk_add_f32 v[140:141], v[140:141], v[142:143]
	v_pk_add_f32 v[150:151], v[150:151], v[152:153]
	s_nop 0
	v_pk_add_f32 v[140:141], v[150:151], v[140:141]
	ds_bpermute_b32 v142, v181, v140
	ds_bpermute_b32 v143, v181, v141
	s_waitcnt lgkmcnt(0)
	v_pk_add_f32 v[140:141], v[140:141], v[142:143]
	ds_bpermute_b32 v142, v180, v140
	ds_bpermute_b32 v143, v180, v141
	s_waitcnt lgkmcnt(0)
	v_pk_add_f32 v[140:141], v[140:141], v[142:143]
	s_nop 0
	v_pk_mul_f32 v[160:161], v[140:141], s[82:83] op_sel_hi:[1,0]
	v_lshlrev_b64 v[140:141], 11, v[146:147]
	v_lshl_add_u64 v[140:141], s[70:71], 0, v[140:141]
	v_lshl_add_u64 v[152:153], v[144:145], 1, v[140:141]
	v_add_u32_e32 v243, 0x10000, v242
	s_waitcnt vmcnt(11)
	v_mov_b64_e32 v[140:141], v[198:199]
	global_load_dwordx2 v[198:199], v243, s[70:71]
	v_fma_f32 v3, -v160, v160, v161
	v_max_f32_e32 v3, 0, v3
	v_add_f32_e32 v3, 0x3727c5ac, v3
	v_rsq_f32_e32 v162, v3
	s_waitcnt lgkmcnt(0)
	v_lshlrev_b32_e32 v142, 16, v141
	v_and_b32_e32 v143, 0xffff0000, v141
	v_lshlrev_b32_e32 v3, 16, v140
	v_and_b32_e32 v140, 0xffff0000, v140
	v_sub_f32_e32 v143, v143, v160
	v_sub_f32_e32 v142, v142, v160
	v_sub_f32_e32 v141, v140, v160
	v_sub_f32_e32 v140, v3, v160
	v_pk_mul_f32 v[150:151], v[142:143], v[162:163] op_sel_hi:[1,0]
	v_lshlrev_b64 v[142:143], 2, v[144:145]
	v_pk_mul_f32 v[158:159], v[140:141], v[162:163] op_sel_hi:[1,0]
	v_lshl_add_u64 v[140:141], s[46:47], 0, v[142:143]
	v_lshl_add_u64 v[142:143], s[48:49], 0, v[142:143]
	ds_read_b128 v[154:157], v244
	ds_read_b128 v[182:185], v244 offset:256
	s_waitcnt lgkmcnt(0)
	v_pk_fma_f32 v[154:155], v[154:155], v[158:159], v[182:183]
	s_nop 0
	v_pk_fma_f32 v[128:129], v[154:155], s[72:73], v[128:129] op_sel_hi:[1,0,1]
	s_waitcnt vmcnt(11)
	v_mov_b64_e32 v[154:155], v[200:201]
	global_load_dwordx2 v[200:201], v243, s[70:71] offset:32
	v_pk_fma_f32 v[150:151], v[156:157], v[150:151], v[184:185]
	s_waitcnt lgkmcnt(0)
	v_lshlrev_b32_e32 v3, 16, v154
	v_pk_fma_f32 v[130:131], v[150:151], s[72:73], v[130:131] op_sel_hi:[1,0,1]
	v_cvt_pk_bf16_f32 v150, v128, v129
	v_cvt_pk_bf16_f32 v151, v130, v131
	v_and_b32_e32 v129, 0xffff0000, v154
	v_lshlrev_b32_e32 v131, 16, v155
	v_and_b32_e32 v147, 0xffff0000, v155
	global_store_dwordx2 v[152:153], v[150:151], off
	v_sub_f32_e32 v155, v129, v160
	v_sub_f32_e32 v154, v3, v160
	v_sub_f32_e32 v157, v147, v160
	v_sub_f32_e32 v156, v131, v160
	v_pk_mul_f32 v[158:159], v[162:163], v[156:157] op_sel_hi:[0,1]
	v_pk_mul_f32 v[168:169], v[162:163], v[154:155] op_sel_hi:[0,1]
	ds_read_b128 v[154:157], v244 offset:64
	ds_read_b128 v[182:185], v244 offset:320
	v_and_b32_e32 v130, 0xffff0000, v150
	v_lshlrev_b32_e32 v128, 16, v151
	s_waitcnt lgkmcnt(0)
; __device__ __forceinline__ u32x2 pk4(f32x4 v) { u32x2 r; r.x = pk2(v.x, v.y); r.y = pk2(v.z, v.w); return r; }
;     __device__ __forceinline__ void operator()(const f32x4 (&acc)[2][2][4][2], const pg8::Unit& u, int wr, int wc, int fr, int fq) const {
;     ...
;                 for (int bj = 0; bj < 2; ++bj)
; #pragma unroll
;                     for (int n = 0; n < 2; ++n) {
;                         const int col = u.pn * 256 + bj * 128 + wc * 32 + n * 16 + fq * 4;
;                         const u32x2 raw = *(const u32x2*)(src + (size_t)row * DM + col);
;                         f32x4 x = (f32x4){bflo(raw.x), bfhi(raw.x), bflo(raw.y), bfhi(raw.y)};
;                         if (ln) x = (x - mu) * rs * *(const f32x4*)(g + col) + *(const f32x4*)(b + col);
;                         const u32x2 pz = pk4(x * ALPHA + acc[ai][bj][m][n]);
;                         *(u32x2*)(dst + (size_t)row * DM + col) = pz;
;                         const float z0 = bflo(pz.x), z1 = bfhi(pz.x), z2 = bflo(pz.y), z3 = bfhi(pz.y);
;                         s1 += (z0 + z1) + (z2 + z3); s2 += (z0 * z0 + z1 * z1) + (z2 * z2 + z3 * z3);
;                     }
;                 s1 += __shfl_xor(s1, 16); s2 += __shfl_xor(s2, 16); s1 += __shfl_xor(s1, 32); s2 += __shfl_xor(s2, 32);
;                 if (fq == 0) { float* p = stm_n + (size_t)row * 32 + (u.pn * 4 + wc) * 2; p[0] = s1; p[1] = s2; }
	v_pk_fma_f32 v[154:155], v[154:155], v[168:169], v[182:183]
	s_nop 0
	v_pk_fma_f32 v[124:125], v[154:155], s[72:73], v[124:125] op_sel_hi:[1,0,1]
	s_waitcnt vmcnt(12)
	v_mov_b64_e32 v[154:155], v[202:203]
	global_load_dwordx2 v[202:203], v243, s[70:71] offset:256
	v_pk_fma_f32 v[156:157], v[156:157], v[158:159], v[184:185]
	v_cvt_pk_bf16_f32 v158, v124, v125
	v_pk_fma_f32 v[126:127], v[156:157], s[72:73], v[126:127] op_sel_hi:[1,0,1]
	s_waitcnt lgkmcnt(0)
	v_lshlrev_b32_e32 v3, 16, v154
	v_cvt_pk_bf16_f32 v159, v126, v127
	v_lshlrev_b32_e32 v126, 16, v159
	v_and_b32_e32 v127, 0xffff0000, v159
	v_mul_f32_e32 v124, v126, v126
	v_pk_fma_f32 v[124:125], v[126:127], v[126:127], v[124:125] op_sel_hi:[1,1,0]
	v_lshlrev_b32_e32 v129, 16, v155
	v_and_b32_e32 v124, 0xffff0000, v154
	v_and_b32_e32 v131, 0xffff0000, v155
	global_store_dwordx2 v[152:153], v[158:159], off offset:32
	v_sub_f32_e32 v155, v124, v160
	v_sub_f32_e32 v154, v3, v160
	v_sub_f32_e32 v157, v131, v160
	v_sub_f32_e32 v156, v129, v160
	v_pk_mul_f32 v[168:169], v[162:163], v[156:157] op_sel_hi:[0,1]
	v_pk_mul_f32 v[186:187], v[162:163], v[154:155] op_sel_hi:[0,1]
	ds_read_b128 v[154:157], v244 offset:128
	ds_read_b128 v[182:185], v244 offset:384
	v_and_b32_e32 v159, 0xffff0000, v158
	s_waitcnt lgkmcnt(0)
	v_pk_fma_f32 v[154:155], v[154:155], v[186:187], v[182:183]
	v_pk_fma_f32 v[156:157], v[156:157], v[168:169], v[184:185]
	v_pk_fma_f32 v[120:121], v[154:155], s[72:73], v[120:121] op_sel_hi:[1,0,1]
	v_pk_fma_f32 v[122:123], v[156:157], s[72:73], v[122:123] op_sel_hi:[1,0,1]
	s_waitcnt vmcnt(13)
	v_mov_b64_e32 v[168:169], v[204:205]
	global_load_dwordx2 v[204:205], v243, s[70:71] offset:288
	v_cvt_pk_bf16_f32 v120, v120, v121
	v_cvt_pk_bf16_f32 v121, v122, v123
	global_store_dwordx2 v[152:153], v[120:121], off offset:256
	ds_read_b128 v[182:185], v244 offset:192
	ds_read_b128 v[186:189], v244 offset:448
	v_lshlrev_b32_e32 v154, 16, v120
	v_and_b32_e32 v156, 0xffff0000, v120
	v_lshlrev_b32_e32 v120, 16, v121
	v_and_b32_e32 v122, 0xffff0000, v121
	v_mul_f32_e32 v155, v154, v154
	v_mul_f32_e32 v157, v156, v156
	v_mul_f32_e32 v121, v120, v120
	v_mul_f32_e32 v123, v122, v122
	v_pk_add_f32 v[120:121], v[120:121], v[122:123]
	s_waitcnt lgkmcnt(0)
	v_lshlrev_b32_e32 v3, 16, v168
	v_and_b32_e32 v124, 0xffff0000, v168
	v_lshlrev_b32_e32 v129, 16, v169
	v_and_b32_e32 v131, 0xffff0000, v169
	v_sub_f32_e32 v169, v124, v160
	v_sub_f32_e32 v168, v3, v160
	v_sub_f32_e32 v161, v131, v160
	v_sub_f32_e32 v160, v129, v160
	v_pk_mul_f32 v[160:161], v[162:163], v[160:161] op_sel_hi:[0,1]
	v_pk_mul_f32 v[162:163], v[162:163], v[168:169] op_sel_hi:[0,1]
	s_waitcnt lgkmcnt(0)
	v_pk_fma_f32 v[162:163], v[182:183], v[162:163], v[186:187]
	v_mov_b32_e32 v129, v159
	v_pk_fma_f32 v[116:117], v[162:163], s[72:73], v[116:117] op_sel_hi:[1,0,1]
	v_lshlrev_b32_e32 v163, 16, v158
	v_lshlrev_b32_e32 v162, 16, v150
	v_mov_b32_e32 v131, v163
	v_pk_mul_f32 v[168:169], v[162:163], v[162:163]
	v_pk_mul_f32 v[182:183], v[130:131], v[130:131]
	v_and_b32_e32 v158, 0xffff0000, v151
	v_pk_fma_f32 v[160:161], v[184:185], v[160:161], v[188:189]
	v_pk_mul_f32 v[150:151], v[128:129], v[128:129]
	v_pk_mul_f32 v[184:185], v[158:159], v[158:159]
	v_pk_mov_b32 v[186:187], v[162:163], v[168:169] op_sel:[1,0]
	v_pk_mov_b32 v[182:183], v[158:159], v[182:183] op_sel:[1,0]
	v_pk_add_f32 v[130:131], v[162:163], v[130:131]
	v_pk_add_f32 v[128:129], v[158:159], v[128:129]
	v_pk_fma_f32 v[118:119], v[160:161], s[72:73], v[118:119] op_sel_hi:[1,0,1]
	v_pk_add_f32 v[182:183], v[186:187], v[182:183]
	v_mov_b32_e32 v186, v126
	v_mov_b32_e32 v187, v150
	v_pk_mov_b32 v[126:127], v[126:127], v[184:185] op_sel:[1,0]
	v_mov_b32_e32 v131, v169
	v_mov_b32_e32 v129, v185
	v_cvt_pk_bf16_f32 v116, v116, v117
	v_cvt_pk_bf16_f32 v117, v118, v119
	v_pk_add_f32 v[126:127], v[186:187], v[126:127]
	v_pk_add_f32 v[128:129], v[130:131], v[128:129]
	v_mov_b32_e32 v3, v125
	global_store_dwordx2 v[152:153], v[116:117], off offset:288
	v_lshlrev_b32_e32 v152, 16, v116
	v_and_b32_e32 v160, 0xffff0000, v116
	v_lshlrev_b32_e32 v116, 16, v117
	v_and_b32_e32 v118, 0xffff0000, v117
	v_pk_add_f32 v[126:127], v[182:183], v[126:127]
	v_pk_add_f32 v[124:125], v[128:129], v[2:3]
	v_mul_f32_e32 v153, v152, v152
	v_mul_f32_e32 v161, v160, v160
	v_mul_f32_e32 v117, v116, v116
	v_mul_f32_e32 v119, v118, v118
	v_pk_add_f32 v[124:125], v[126:127], v[124:125]
	v_pk_add_f32 v[126:127], v[154:155], v[156:157]
	v_pk_add_f32 v[122:123], v[152:153], v[160:161]
	v_pk_add_f32 v[120:121], v[126:127], v[120:121]
	v_pk_add_f32 v[116:117], v[116:117], v[118:119]
	v_pk_add_f32 v[120:121], v[124:125], v[120:121]
	v_pk_add_f32 v[116:117], v[122:123], v[116:117]
	s_nop 0
	v_pk_add_f32 v[116:117], v[120:121], v[116:117]
	ds_bpermute_b32 v118, v181, v116
	ds_bpermute_b32 v119, v181, v117
	s_waitcnt lgkmcnt(0)
	v_pk_add_f32 v[116:117], v[116:117], v[118:119]
	ds_bpermute_b32 v118, v180, v116
	ds_bpermute_b32 v119, v180, v117
	s_and_saveexec_b64 s[0:1], s[40:41]
	s_cbranch_execz .LBB0_2379
	v_lshl_add_u64 v[120:121], s[52:53], 0, v[148:149]
	v_lshl_add_u64 v[120:121], s[68:69], 2, v[120:121]
	s_waitcnt lgkmcnt(0)
	v_pk_add_f32 v[116:117], v[116:117], v[118:119]
	global_store_dwordx2 v[120:121], v[116:117], off
; __device__ __forceinline__ u32x2 pk4(f32x4 v) { u32x2 r; r.x = pk2(v.x, v.y); r.y = pk2(v.z, v.w); return r; }
; __device__ __forceinline__ void stats_main(const float* stm, int row, int fq, float& mu, float& rs) {
;     const f32x4* p = (const f32x4*)(stm + (size_t)row * 32 + fq * 8);
;     const f32x4 a = p[0], b = p[1];
;     float s1 = (a.x + a.z) + (b.x + b.z), s2 = (a.y + a.w) + (b.y + b.w);
;     s1 += __shfl_xor(s1, 16); s2 += __shfl_xor(s2, 16); s1 += __shfl_xor(s1, 32); s2 += __shfl_xor(s2, 32);
;     mu = s1 * (1.f / DM); rs = __builtin_amdgcn_rsqf(fmaxf(s2 * (1.f / DM) - mu * mu, 0.f) + LN_EPS);
;     __device__ __forceinline__ void operator()(const f32x4 (&acc)[2][2][4][2], const pg8::Unit& u, int wr, int wc, int fr, int fq) const {
;     ...
;                 const int row = u.pm * 256 + ai * 128 + wr * 64 + m * 16 + fr;
;                 float mu = 0.f, rs = 1.f; if (ln) stats_main(stm_p, row, fq, mu, rs);
;                 float s1 = 0.f, s2 = 0.f;
; #pragma unroll
;                 for (int bj = 0; bj < 2; ++bj)
; #pragma unroll
;                     for (int n = 0; n < 2; ++n) {
;                         const int col = u.pn * 256 + bj * 128 + wc * 32 + n * 16 + fq * 4;
;                         const u32x2 raw = *(const u32x2*)(src + (size_t)row * DM + col);
;                         f32x4 x = (f32x4){bflo(raw.x), bfhi(raw.x), bflo(raw.y), bfhi(raw.y)};
;                         if (ln) x = (x - mu) * rs * *(const f32x4*)(g + col) + *(const f32x4*)(b + col);
;                         const u32x2 pz = pk4(x * ALPHA + acc[ai][bj][m][n]);
;                         *(u32x2*)(dst + (size_t)row * DM + col) = pz;
;                         const float z0 = bflo(pz.x), z1 = bfhi(pz.x), z2 = bflo(pz.y), z3 = bfhi(pz.y);
;                         s1 += (z0 + z1) + (z2 + z3); s2 += (z0 * z0 + z1 * z1) + (z2 * z2 + z3 * z3);
.LBB0_2379:
	s_or_b64 exec, exec, s[0:1]
	v_or_b32_e32 v126, 16, v146
	v_ashrrev_i32_e32 v127, 31, v126
	v_lshlrev_b64 v[116:117], 7, v[126:127]
	v_lshl_add_u64 v[122:123], v[134:135], 0, v[116:117]
	s_waitcnt lgkmcnt(0)
	s_waitcnt vmcnt(16)
	v_mov_b64_e32 v[118:119], v[206:207]
	v_mov_b64_e32 v[120:121], v[208:209]
	global_load_dwordx4 v[206:209], v[246:247], off offset:2064
	s_nop 0
	s_waitcnt vmcnt(16)
	v_mov_b64_e32 v[122:123], v[214:215]
	v_mov_b64_e32 v[124:125], v[216:217]
	global_load_dwordx4 v[214:217], v[246:247], off offset:2048
	s_waitcnt lgkmcnt(0)
	v_pk_add_f32 v[118:119], v[118:119], v[120:121]
	s_waitcnt lgkmcnt(0)
	v_pk_add_f32 v[122:123], v[122:123], v[124:125]
	s_nop 0
	v_pk_add_f32 v[118:119], v[122:123], v[118:119]
	ds_bpermute_b32 v120, v181, v118
	ds_bpermute_b32 v121, v181, v119
	s_waitcnt lgkmcnt(0)
	v_pk_add_f32 v[118:119], v[118:119], v[120:121]
	ds_bpermute_b32 v120, v180, v118
	ds_bpermute_b32 v121, v180, v119
	s_waitcnt lgkmcnt(0)
	v_pk_add_f32 v[118:119], v[118:119], v[120:121]
	s_nop 0
	v_pk_mul_f32 v[128:129], v[118:119], s[82:83] op_sel_hi:[1,0]
	v_lshlrev_b64 v[118:119], 11, v[126:127]
	v_lshl_add_u64 v[118:119], s[70:71], 0, v[118:119]
	v_lshl_add_u64 v[124:125], v[144:145], 1, v[118:119]
	v_add_u32_e32 v243, 0x18000, v242
	s_waitcnt vmcnt(16)
	v_mov_b64_e32 v[118:119], v[234:235]
	global_load_dwordx2 v[234:235], v243, s[70:71]
	v_fma_f32 v3, -v128, v128, v129
	v_max_f32_e32 v3, 0, v3
	v_add_f32_e32 v3, 0x3727c5ac, v3
	v_rsq_f32_e32 v130, v3
	s_waitcnt lgkmcnt(0)
	v_lshlrev_b32_e32 v3, 16, v118
	v_and_b32_e32 v118, 0xffff0000, v118
	v_lshlrev_b32_e32 v120, 16, v119
	v_and_b32_e32 v121, 0xffff0000, v119
	v_sub_f32_e32 v119, v118, v128
	v_sub_f32_e32 v118, v3, v128
	v_sub_f32_e32 v121, v121, v128
	v_sub_f32_e32 v120, v120, v128
	v_pk_mul_f32 v[122:123], v[120:121], v[130:131] op_sel_hi:[1,0]
	v_pk_mul_f32 v[126:127], v[118:119], v[130:131] op_sel_hi:[1,0]
	ds_read_b128 v[118:121], v244
	ds_read_b128 v[148:151], v244 offset:256
	s_waitcnt lgkmcnt(0)
	v_pk_fma_f32 v[120:121], v[120:121], v[122:123], v[150:151]
	s_nop 0
	v_pk_fma_f32 v[114:115], v[120:121], s[72:73], v[114:115] op_sel_hi:[1,0,1]
	s_waitcnt vmcnt(16)
	v_mov_b64_e32 v[120:121], v[236:237]
	global_load_dwordx2 v[236:237], v243, s[70:71] offset:32
	v_pk_fma_f32 v[118:119], v[118:119], v[126:127], v[148:149]
	s_waitcnt lgkmcnt(0)
	v_lshlrev_b32_e32 v3, 16, v120
	v_pk_fma_f32 v[112:113], v[118:119], s[72:73], v[112:113] op_sel_hi:[1,0,1]
	v_cvt_pk_bf16_f32 v119, v114, v115
	v_cvt_pk_bf16_f32 v118, v112, v113
	v_and_b32_e32 v113, 0xffff0000, v120
	v_lshlrev_b32_e32 v115, 16, v121
	v_and_b32_e32 v122, 0xffff0000, v121
	global_store_dwordx2 v[124:125], v[118:119], off
	v_sub_f32_e32 v121, v113, v128
	v_sub_f32_e32 v120, v3, v128
	v_sub_f32_e32 v123, v122, v128
	v_sub_f32_e32 v122, v115, v128
	v_pk_mul_f32 v[126:127], v[130:131], v[122:123] op_sel_hi:[0,1]
	v_pk_mul_f32 v[152:153], v[130:131], v[120:121] op_sel_hi:[0,1]
	ds_read_b128 v[120:123], v244 offset:64
	ds_read_b128 v[148:151], v244 offset:320
	v_and_b32_e32 v114, 0xffff0000, v118
	v_lshlrev_b32_e32 v112, 16, v119
	s_waitcnt lgkmcnt(0)
	v_pk_fma_f32 v[120:121], v[120:121], v[152:153], v[148:149]
	s_nop 0
	v_pk_fma_f32 v[108:109], v[120:121], s[72:73], v[108:109] op_sel_hi:[1,0,1]
	s_waitcnt vmcnt(17)
	v_mov_b64_e32 v[120:121], v[238:239]
	global_load_dwordx2 v[238:239], v243, s[70:71] offset:256
	v_pk_fma_f32 v[122:123], v[122:123], v[126:127], v[150:151]
	v_cvt_pk_bf16_f32 v126, v108, v109
	v_pk_fma_f32 v[110:111], v[122:123], s[72:73], v[110:111] op_sel_hi:[1,0,1]
	s_waitcnt lgkmcnt(0)
	v_lshlrev_b32_e32 v3, 16, v120
	v_cvt_pk_bf16_f32 v127, v110, v111
	v_lshlrev_b32_e32 v110, 16, v127
	v_and_b32_e32 v111, 0xffff0000, v127
	v_mul_f32_e32 v108, v110, v110
	v_pk_fma_f32 v[108:109], v[110:111], v[110:111], v[108:109] op_sel_hi:[1,1,0]
	v_lshlrev_b32_e32 v113, 16, v121
	v_and_b32_e32 v108, 0xffff0000, v120
	v_and_b32_e32 v115, 0xffff0000, v121
	global_store_dwordx2 v[124:125], v[126:127], off offset:32
	v_sub_f32_e32 v121, v108, v128
	v_sub_f32_e32 v120, v3, v128
	v_sub_f32_e32 v123, v115, v128
	v_sub_f32_e32 v122, v113, v128
	v_pk_mul_f32 v[152:153], v[130:131], v[122:123] op_sel_hi:[0,1]
	v_pk_mul_f32 v[154:155], v[130:131], v[120:121] op_sel_hi:[0,1]
	ds_read_b128 v[120:123], v244 offset:128
	ds_read_b128 v[148:151], v244 offset:384
	v_and_b32_e32 v127, 0xffff0000, v126
	s_waitcnt lgkmcnt(0)
	v_pk_fma_f32 v[120:121], v[120:121], v[154:155], v[148:149]
	s_waitcnt vmcnt(18)
	v_mov_b64_e32 v[148:149], v[240:241]
	global_load_dwordx2 v[240:241], v243, s[70:71] offset:288
	v_pk_fma_f32 v[122:123], v[122:123], v[152:153], v[150:151]
	v_pk_fma_f32 v[104:105], v[120:121], s[72:73], v[104:105] op_sel_hi:[1,0,1]
	v_pk_fma_f32 v[106:107], v[122:123], s[72:73], v[106:107] op_sel_hi:[1,0,1]
	v_cvt_pk_bf16_f32 v104, v104, v105
	v_cvt_pk_bf16_f32 v105, v106, v107
	global_store_dwordx2 v[124:125], v[104:105], off offset:256
	v_lshlrev_b32_e32 v120, 16, v104
	v_and_b32_e32 v122, 0xffff0000, v104
	v_lshlrev_b32_e32 v104, 16, v105
	v_and_b32_e32 v106, 0xffff0000, v105
	v_mul_f32_e32 v121, v120, v120
	v_mul_f32_e32 v123, v122, v122
	v_mul_f32_e32 v105, v104, v104
	v_mul_f32_e32 v107, v106, v106
	v_pk_add_f32 v[104:105], v[104:105], v[106:107]
	s_waitcnt lgkmcnt(0)
	v_lshlrev_b32_e32 v3, 16, v148
	v_and_b32_e32 v108, 0xffff0000, v148
	v_lshlrev_b32_e32 v113, 16, v149
	v_and_b32_e32 v115, 0xffff0000, v149
	v_sub_f32_e32 v149, v108, v128
	v_sub_f32_e32 v148, v3, v128
	v_sub_f32_e32 v129, v115, v128
	v_sub_f32_e32 v128, v113, v128
	v_pk_mul_f32 v[128:129], v[130:131], v[128:129] op_sel_hi:[0,1]
	v_pk_mul_f32 v[130:131], v[130:131], v[148:149] op_sel_hi:[0,1]
	ds_read_b128 v[148:151], v244 offset:192
	ds_read_b128 v[152:155], v244 offset:448
	v_mov_b32_e32 v113, v127
	v_mov_b32_e32 v3, v109
	s_waitcnt lgkmcnt(0)
; __device__ __forceinline__ u32x2 pk4(f32x4 v) { u32x2 r; r.x = pk2(v.x, v.y); r.y = pk2(v.z, v.w); return r; }
; __device__ __forceinline__ void stats_main(const float* stm, int row, int fq, float& mu, float& rs) {
;     const f32x4* p = (const f32x4*)(stm + (size_t)row * 32 + fq * 8);
;     const f32x4 a = p[0], b = p[1];
;     float s1 = (a.x + a.z) + (b.x + b.z), s2 = (a.y + a.w) + (b.y + b.w);
;     s1 += __shfl_xor(s1, 16); s2 += __shfl_xor(s2, 16); s1 += __shfl_xor(s1, 32); s2 += __shfl_xor(s2, 32);
;     mu = s1 * (1.f / DM); rs = __builtin_amdgcn_rsqf(fmaxf(s2 * (1.f / DM) - mu * mu, 0.f) + LN_EPS);
;     __device__ __forceinline__ void operator()(const f32x4 (&acc)[2][2][4][2], const pg8::Unit& u, int wr, int wc, int fr, int fq) const {
;     ...
;                 const int row = u.pm * 256 + ai * 128 + wr * 64 + m * 16 + fr;
;                 float mu = 0.f, rs = 1.f; if (ln) stats_main(stm_p, row, fq, mu, rs);
;                 float s1 = 0.f, s2 = 0.f;
; #pragma unroll
;                 for (int bj = 0; bj < 2; ++bj)
; #pragma unroll
;                     for (int n = 0; n < 2; ++n) {
;                         const int col = u.pn * 256 + bj * 128 + wc * 32 + n * 16 + fq * 4;
;                         const u32x2 raw = *(const u32x2*)(src + (size_t)row * DM + col);
;                         f32x4 x = (f32x4){bflo(raw.x), bfhi(raw.x), bflo(raw.y), bfhi(raw.y)};
;                         if (ln) x = (x - mu) * rs * *(const f32x4*)(g + col) + *(const f32x4*)(b + col);
;                         const u32x2 pz = pk4(x * ALPHA + acc[ai][bj][m][n]);
;                         *(u32x2*)(dst + (size_t)row * DM + col) = pz;
;                         const float z0 = bflo(pz.x), z1 = bfhi(pz.x), z2 = bflo(pz.y), z3 = bfhi(pz.y);
;                         s1 += (z0 + z1) + (z2 + z3); s2 += (z0 * z0 + z1 * z1) + (z2 * z2 + z3 * z3);
;                     }
;                 s1 += __shfl_xor(s1, 16); s2 += __shfl_xor(s2, 16); s1 += __shfl_xor(s1, 32); s2 += __shfl_xor(s2, 32);
;                 if (fq == 0) { float* p = stm_n + (size_t)row * 32 + (u.pn * 4 + wc) * 2; p[0] = s1; p[1] = s2; }
	v_pk_fma_f32 v[130:131], v[148:149], v[130:131], v[152:153]
	s_nop 0
	v_pk_fma_f32 v[100:101], v[130:131], s[72:73], v[100:101] op_sel_hi:[1,0,1]
	v_lshlrev_b32_e32 v131, 16, v126
	v_lshlrev_b32_e32 v130, 16, v118
	v_mov_b32_e32 v115, v131
	v_pk_fma_f32 v[128:129], v[150:151], v[128:129], v[154:155]
	v_pk_mul_f32 v[148:149], v[130:131], v[130:131]
	v_pk_mul_f32 v[150:151], v[114:115], v[114:115]
	v_and_b32_e32 v126, 0xffff0000, v119
	v_pk_mul_f32 v[118:119], v[112:113], v[112:113]
	v_pk_mul_f32 v[152:153], v[126:127], v[126:127]
	v_pk_mov_b32 v[154:155], v[130:131], v[148:149] op_sel:[1,0]
	v_pk_mov_b32 v[150:151], v[126:127], v[150:151] op_sel:[1,0]
	v_pk_add_f32 v[114:115], v[130:131], v[114:115]
	v_pk_add_f32 v[112:113], v[126:127], v[112:113]
	v_pk_fma_f32 v[102:103], v[128:129], s[72:73], v[102:103] op_sel_hi:[1,0,1]
	v_pk_add_f32 v[150:151], v[154:155], v[150:151]
	v_mov_b32_e32 v154, v110
	v_mov_b32_e32 v155, v118
	v_pk_mov_b32 v[110:111], v[110:111], v[152:153] op_sel:[1,0]
	v_mov_b32_e32 v115, v149
	v_mov_b32_e32 v113, v153
	v_cvt_pk_bf16_f32 v100, v100, v101
	v_cvt_pk_bf16_f32 v101, v102, v103
	v_pk_add_f32 v[110:111], v[154:155], v[110:111]
	v_pk_add_f32 v[112:113], v[114:115], v[112:113]
	global_store_dwordx2 v[124:125], v[100:101], off offset:288
	v_lshlrev_b32_e32 v124, 16, v100
	v_and_b32_e32 v128, 0xffff0000, v100
	v_lshlrev_b32_e32 v100, 16, v101
	v_and_b32_e32 v102, 0xffff0000, v101
	v_pk_add_f32 v[110:111], v[150:151], v[110:111]
	v_pk_add_f32 v[108:109], v[112:113], v[2:3]
	v_mul_f32_e32 v125, v124, v124
	v_mul_f32_e32 v129, v128, v128
	v_mul_f32_e32 v101, v100, v100
	v_mul_f32_e32 v103, v102, v102
	v_pk_add_f32 v[108:109], v[110:111], v[108:109]
	v_pk_add_f32 v[110:111], v[120:121], v[122:123]
	v_pk_add_f32 v[106:107], v[124:125], v[128:129]
	v_pk_add_f32 v[104:105], v[110:111], v[104:105]
	v_pk_add_f32 v[100:101], v[100:101], v[102:103]
	v_pk_add_f32 v[104:105], v[108:109], v[104:105]
	v_pk_add_f32 v[100:101], v[106:107], v[100:101]
	s_nop 0
	v_pk_add_f32 v[100:101], v[104:105], v[100:101]
	ds_bpermute_b32 v102, v181, v100
	ds_bpermute_b32 v103, v181, v101
	s_waitcnt lgkmcnt(0)
	v_pk_add_f32 v[100:101], v[100:101], v[102:103]
	ds_bpermute_b32 v102, v180, v100
	ds_bpermute_b32 v103, v180, v101
	s_and_saveexec_b64 s[0:1], s[40:41]
	s_cbranch_execz .LBB0_2381
	v_lshl_add_u64 v[104:105], s[52:53], 0, v[116:117]
	v_lshl_add_u64 v[104:105], s[68:69], 2, v[104:105]
	s_waitcnt lgkmcnt(0)
	v_pk_add_f32 v[100:101], v[100:101], v[102:103]
	global_store_dwordx2 v[104:105], v[100:101], off
.LBB0_2381:
	s_or_b64 exec, exec, s[0:1]
	v_or_b32_e32 v110, 32, v146
	v_ashrrev_i32_e32 v111, 31, v110
	v_lshlrev_b64 v[100:101], 7, v[110:111]
	v_lshl_add_u64 v[106:107], v[134:135], 0, v[100:101]
	s_waitcnt lgkmcnt(0)
	s_waitcnt vmcnt(21)
	v_mov_b64_e32 v[102:103], v[190:191]
	v_mov_b64_e32 v[104:105], v[192:193]
	global_load_dwordx4 v[190:193], v[248:249], off offset:-4080
	s_nop 0
	s_waitcnt vmcnt(21)
	v_mov_b64_e32 v[106:107], v[194:195]
	v_mov_b64_e32 v[108:109], v[196:197]
	global_load_dwordx4 v[194:197], v[248:249], off offset:-4096
	s_waitcnt lgkmcnt(0)
	v_pk_add_f32 v[102:103], v[102:103], v[104:105]
	s_waitcnt lgkmcnt(0)
	v_pk_add_f32 v[106:107], v[106:107], v[108:109]
	s_nop 0
	v_pk_add_f32 v[102:103], v[106:107], v[102:103]
	ds_bpermute_b32 v104, v181, v102
	ds_bpermute_b32 v105, v181, v103
	s_waitcnt lgkmcnt(0)
	v_pk_add_f32 v[102:103], v[102:103], v[104:105]
	ds_bpermute_b32 v104, v180, v102
	ds_bpermute_b32 v105, v180, v103
	s_waitcnt lgkmcnt(0)
	v_pk_add_f32 v[102:103], v[102:103], v[104:105]
	s_nop 0
	v_pk_mul_f32 v[112:113], v[102:103], s[82:83] op_sel_hi:[1,0]
	v_lshlrev_b64 v[102:103], 11, v[110:111]
	v_lshl_add_u64 v[102:103], s[70:71], 0, v[102:103]
	v_lshl_add_u64 v[108:109], v[144:145], 1, v[102:103]
	v_add_u32_e32 v243, 0x40000, v242
	s_waitcnt vmcnt(21)
	v_mov_b64_e32 v[102:103], v[198:199]
	global_load_dwordx2 v[198:199], v243, s[70:71]
	v_fma_f32 v3, -v112, v112, v113
	v_max_f32_e32 v3, 0, v3
	v_add_f32_e32 v3, 0x3727c5ac, v3
	v_rsq_f32_e32 v114, v3
	s_waitcnt lgkmcnt(0)
	v_lshlrev_b32_e32 v3, 16, v102
	v_and_b32_e32 v102, 0xffff0000, v102
	v_lshlrev_b32_e32 v104, 16, v103
	v_and_b32_e32 v105, 0xffff0000, v103
	v_sub_f32_e32 v103, v102, v112
	v_sub_f32_e32 v102, v3, v112
	v_sub_f32_e32 v105, v105, v112
	v_sub_f32_e32 v104, v104, v112
	v_pk_mul_f32 v[106:107], v[104:105], v[114:115] op_sel_hi:[1,0]
	v_pk_mul_f32 v[110:111], v[102:103], v[114:115] op_sel_hi:[1,0]
	ds_read_b128 v[102:105], v244
	ds_read_b128 v[116:119], v244 offset:256
	s_waitcnt lgkmcnt(0)
	v_pk_fma_f32 v[104:105], v[104:105], v[106:107], v[118:119]
	s_nop 0
	v_pk_fma_f32 v[98:99], v[104:105], s[72:73], v[98:99] op_sel_hi:[1,0,1]
	s_waitcnt vmcnt(21)
	v_mov_b64_e32 v[104:105], v[200:201]
	global_load_dwordx2 v[200:201], v243, s[70:71] offset:32
	v_pk_fma_f32 v[102:103], v[102:103], v[110:111], v[116:117]
	s_waitcnt lgkmcnt(0)
	v_lshlrev_b32_e32 v3, 16, v104
	v_pk_fma_f32 v[96:97], v[102:103], s[72:73], v[96:97] op_sel_hi:[1,0,1]
	v_cvt_pk_bf16_f32 v103, v98, v99
	v_cvt_pk_bf16_f32 v102, v96, v97
	v_and_b32_e32 v97, 0xffff0000, v104
	v_lshlrev_b32_e32 v99, 16, v105
	v_and_b32_e32 v106, 0xffff0000, v105
	global_store_dwordx2 v[108:109], v[102:103], off
	v_sub_f32_e32 v105, v97, v112
	v_sub_f32_e32 v104, v3, v112
	v_sub_f32_e32 v107, v106, v112
	v_sub_f32_e32 v106, v99, v112
	v_pk_mul_f32 v[110:111], v[114:115], v[106:107] op_sel_hi:[0,1]
	v_pk_mul_f32 v[120:121], v[114:115], v[104:105] op_sel_hi:[0,1]
	ds_read_b128 v[104:107], v244 offset:64
	ds_read_b128 v[116:119], v244 offset:320
	v_and_b32_e32 v98, 0xffff0000, v102
	v_lshlrev_b32_e32 v96, 16, v103
	s_waitcnt lgkmcnt(0)
; __device__ __forceinline__ u32x2 pk4(f32x4 v) { u32x2 r; r.x = pk2(v.x, v.y); r.y = pk2(v.z, v.w); return r; }
;     __device__ __forceinline__ void operator()(const f32x4 (&acc)[2][2][4][2], const pg8::Unit& u, int wr, int wc, int fr, int fq) const {
;     ...
;                 for (int bj = 0; bj < 2; ++bj)
; #pragma unroll
;                     for (int n = 0; n < 2; ++n) {
;                         const int col = u.pn * 256 + bj * 128 + wc * 32 + n * 16 + fq * 4;
;                         const u32x2 raw = *(const u32x2*)(src + (size_t)row * DM + col);
;                         f32x4 x = (f32x4){bflo(raw.x), bfhi(raw.x), bflo(raw.y), bfhi(raw.y)};
;                         if (ln) x = (x - mu) * rs * *(const f32x4*)(g + col) + *(const f32x4*)(b + col);
;                         const u32x2 pz = pk4(x * ALPHA + acc[ai][bj][m][n]);
;                         *(u32x2*)(dst + (size_t)row * DM + col) = pz;
;                         const float z0 = bflo(pz.x), z1 = bfhi(pz.x), z2 = bflo(pz.y), z3 = bfhi(pz.y);
;                         s1 += (z0 + z1) + (z2 + z3); s2 += (z0 * z0 + z1 * z1) + (z2 * z2 + z3 * z3);
;                     }
;                 s1 += __shfl_xor(s1, 16); s2 += __shfl_xor(s2, 16); s1 += __shfl_xor(s1, 32); s2 += __shfl_xor(s2, 32);
;                 if (fq == 0) { float* p = stm_n + (size_t)row * 32 + (u.pn * 4 + wc) * 2; p[0] = s1; p[1] = s2; }
	v_pk_fma_f32 v[104:105], v[104:105], v[120:121], v[116:117]
	s_nop 0
	v_pk_fma_f32 v[92:93], v[104:105], s[72:73], v[92:93] op_sel_hi:[1,0,1]
	s_waitcnt vmcnt(21)
	v_mov_b64_e32 v[104:105], v[202:203]
	global_load_dwordx2 v[202:203], v243, s[70:71] offset:256
	v_pk_fma_f32 v[106:107], v[106:107], v[110:111], v[118:119]
	v_cvt_pk_bf16_f32 v110, v92, v93
	v_pk_fma_f32 v[94:95], v[106:107], s[72:73], v[94:95] op_sel_hi:[1,0,1]
	s_waitcnt lgkmcnt(0)
	v_lshlrev_b32_e32 v3, 16, v104
	v_cvt_pk_bf16_f32 v111, v94, v95
	v_lshlrev_b32_e32 v94, 16, v111
	v_and_b32_e32 v95, 0xffff0000, v111
	v_mul_f32_e32 v92, v94, v94
	v_pk_fma_f32 v[92:93], v[94:95], v[94:95], v[92:93] op_sel_hi:[1,1,0]
	v_lshlrev_b32_e32 v97, 16, v105
	v_and_b32_e32 v92, 0xffff0000, v104
	v_and_b32_e32 v99, 0xffff0000, v105
	global_store_dwordx2 v[108:109], v[110:111], off offset:32
	v_sub_f32_e32 v105, v92, v112
	v_sub_f32_e32 v104, v3, v112
	v_sub_f32_e32 v107, v99, v112
	v_sub_f32_e32 v106, v97, v112
	v_pk_mul_f32 v[120:121], v[114:115], v[106:107] op_sel_hi:[0,1]
	v_pk_mul_f32 v[122:123], v[114:115], v[104:105] op_sel_hi:[0,1]
	ds_read_b128 v[104:107], v244 offset:128
	ds_read_b128 v[116:119], v244 offset:384
	v_and_b32_e32 v111, 0xffff0000, v110
	s_waitcnt lgkmcnt(0)
	v_pk_fma_f32 v[104:105], v[104:105], v[122:123], v[116:117]
	s_waitcnt vmcnt(21)
	v_mov_b64_e32 v[116:117], v[204:205]
	global_load_dwordx2 v[204:205], v243, s[70:71] offset:288
	v_pk_fma_f32 v[106:107], v[106:107], v[120:121], v[118:119]
	v_pk_fma_f32 v[88:89], v[104:105], s[72:73], v[88:89] op_sel_hi:[1,0,1]
	v_pk_fma_f32 v[90:91], v[106:107], s[72:73], v[90:91] op_sel_hi:[1,0,1]
	v_cvt_pk_bf16_f32 v88, v88, v89
	v_cvt_pk_bf16_f32 v89, v90, v91
	global_store_dwordx2 v[108:109], v[88:89], off offset:256
	v_lshlrev_b32_e32 v104, 16, v88
	v_and_b32_e32 v106, 0xffff0000, v88
	v_lshlrev_b32_e32 v88, 16, v89
	v_and_b32_e32 v90, 0xffff0000, v89
	v_mul_f32_e32 v105, v104, v104
	v_mul_f32_e32 v107, v106, v106
	v_mul_f32_e32 v89, v88, v88
	v_mul_f32_e32 v91, v90, v90
	v_pk_add_f32 v[88:89], v[88:89], v[90:91]
	s_waitcnt lgkmcnt(0)
	v_lshlrev_b32_e32 v3, 16, v116
	v_and_b32_e32 v92, 0xffff0000, v116
	v_lshlrev_b32_e32 v97, 16, v117
	v_and_b32_e32 v99, 0xffff0000, v117
	v_sub_f32_e32 v117, v92, v112
	v_sub_f32_e32 v116, v3, v112
	v_sub_f32_e32 v113, v99, v112
	v_sub_f32_e32 v112, v97, v112
	v_pk_mul_f32 v[112:113], v[114:115], v[112:113] op_sel_hi:[0,1]
	v_pk_mul_f32 v[114:115], v[114:115], v[116:117] op_sel_hi:[0,1]
	ds_read_b128 v[116:119], v244 offset:192
	ds_read_b128 v[120:123], v244 offset:448
	v_mov_b32_e32 v97, v111
	v_mov_b32_e32 v3, v93
	s_waitcnt lgkmcnt(0)
	v_pk_fma_f32 v[114:115], v[116:117], v[114:115], v[120:121]
	s_nop 0
	v_pk_fma_f32 v[84:85], v[114:115], s[72:73], v[84:85] op_sel_hi:[1,0,1]
	v_lshlrev_b32_e32 v115, 16, v110
	v_lshlrev_b32_e32 v114, 16, v102
	v_mov_b32_e32 v99, v115
	v_pk_fma_f32 v[112:113], v[118:119], v[112:113], v[122:123]
	v_pk_mul_f32 v[116:117], v[114:115], v[114:115]
	v_pk_mul_f32 v[118:119], v[98:99], v[98:99]
	v_and_b32_e32 v110, 0xffff0000, v103
	v_pk_mul_f32 v[102:103], v[96:97], v[96:97]
	v_pk_mul_f32 v[120:121], v[110:111], v[110:111]
	v_pk_mov_b32 v[122:123], v[114:115], v[116:117] op_sel:[1,0]
	v_pk_mov_b32 v[118:119], v[110:111], v[118:119] op_sel:[1,0]
	v_pk_add_f32 v[98:99], v[114:115], v[98:99]
	v_pk_add_f32 v[96:97], v[110:111], v[96:97]
	v_pk_fma_f32 v[86:87], v[112:113], s[72:73], v[86:87] op_sel_hi:[1,0,1]
	v_pk_add_f32 v[118:119], v[122:123], v[118:119]
	v_mov_b32_e32 v122, v94
	v_mov_b32_e32 v123, v102
	v_pk_mov_b32 v[94:95], v[94:95], v[120:121] op_sel:[1,0]
	v_mov_b32_e32 v99, v117
	v_mov_b32_e32 v97, v121
	v_cvt_pk_bf16_f32 v84, v84, v85
	v_cvt_pk_bf16_f32 v85, v86, v87
	v_pk_add_f32 v[94:95], v[122:123], v[94:95]
	v_pk_add_f32 v[96:97], v[98:99], v[96:97]
	global_store_dwordx2 v[108:109], v[84:85], off offset:288
	v_lshlrev_b32_e32 v108, 16, v84
	v_and_b32_e32 v112, 0xffff0000, v84
	v_lshlrev_b32_e32 v84, 16, v85
	v_and_b32_e32 v86, 0xffff0000, v85
	v_pk_add_f32 v[94:95], v[118:119], v[94:95]
	v_pk_add_f32 v[92:93], v[96:97], v[2:3]
	v_mul_f32_e32 v109, v108, v108
	v_mul_f32_e32 v113, v112, v112
	v_mul_f32_e32 v85, v84, v84
	v_mul_f32_e32 v87, v86, v86
	v_pk_add_f32 v[92:93], v[94:95], v[92:93]
	v_pk_add_f32 v[94:95], v[104:105], v[106:107]
	v_pk_add_f32 v[90:91], v[108:109], v[112:113]
	v_pk_add_f32 v[88:89], v[94:95], v[88:89]
	v_pk_add_f32 v[84:85], v[84:85], v[86:87]
	v_pk_add_f32 v[88:89], v[92:93], v[88:89]
	v_pk_add_f32 v[84:85], v[90:91], v[84:85]
	s_nop 0
	v_pk_add_f32 v[84:85], v[88:89], v[84:85]
	ds_bpermute_b32 v86, v181, v84
	ds_bpermute_b32 v87, v181, v85
	s_waitcnt lgkmcnt(0)
	v_pk_add_f32 v[84:85], v[84:85], v[86:87]
	ds_bpermute_b32 v86, v180, v84
	ds_bpermute_b32 v87, v180, v85
	s_and_saveexec_b64 s[0:1], s[40:41]
	s_mov_b32 s78, 0x20000
	s_mov_b32 s76, 0x30000
	s_cbranch_execz .LBB0_2383
	v_lshl_add_u64 v[88:89], s[52:53], 0, v[100:101]
	v_lshl_add_u64 v[88:89], s[68:69], 2, v[88:89]
	s_waitcnt lgkmcnt(0)
	v_pk_add_f32 v[84:85], v[84:85], v[86:87]
	global_store_dwordx2 v[88:89], v[84:85], off
; __device__ __forceinline__ u32x2 pk4(f32x4 v) { u32x2 r; r.x = pk2(v.x, v.y); r.y = pk2(v.z, v.w); return r; }
; __device__ __forceinline__ void stats_main(const float* stm, int row, int fq, float& mu, float& rs) {
;     const f32x4* p = (const f32x4*)(stm + (size_t)row * 32 + fq * 8);
;     const f32x4 a = p[0], b = p[1];
;     float s1 = (a.x + a.z) + (b.x + b.z), s2 = (a.y + a.w) + (b.y + b.w);
;     s1 += __shfl_xor(s1, 16); s2 += __shfl_xor(s2, 16); s1 += __shfl_xor(s1, 32); s2 += __shfl_xor(s2, 32);
;     mu = s1 * (1.f / DM); rs = __builtin_amdgcn_rsqf(fmaxf(s2 * (1.f / DM) - mu * mu, 0.f) + LN_EPS);
;     __device__ __forceinline__ void operator()(const f32x4 (&acc)[2][2][4][2], const pg8::Unit& u, int wr, int wc, int fr, int fq) const {
;     ...
;                 const int row = u.pm * 256 + ai * 128 + wr * 64 + m * 16 + fr;
;                 float mu = 0.f, rs = 1.f; if (ln) stats_main(stm_p, row, fq, mu, rs);
;                 float s1 = 0.f, s2 = 0.f;
; #pragma unroll
;                 for (int bj = 0; bj < 2; ++bj)
; #pragma unroll
;                     for (int n = 0; n < 2; ++n) {
;                         const int col = u.pn * 256 + bj * 128 + wc * 32 + n * 16 + fq * 4;
;                         const u32x2 raw = *(const u32x2*)(src + (size_t)row * DM + col);
;                         f32x4 x = (f32x4){bflo(raw.x), bfhi(raw.x), bflo(raw.y), bfhi(raw.y)};
;                         if (ln) x = (x - mu) * rs * *(const f32x4*)(g + col) + *(const f32x4*)(b + col);
;                         const u32x2 pz = pk4(x * ALPHA + acc[ai][bj][m][n]);
;                         *(u32x2*)(dst + (size_t)row * DM + col) = pz;
;                         const float z0 = bflo(pz.x), z1 = bfhi(pz.x), z2 = bflo(pz.y), z3 = bfhi(pz.y);
;                         s1 += (z0 + z1) + (z2 + z3); s2 += (z0 * z0 + z1 * z1) + (z2 * z2 + z3 * z3);
.LBB0_2383:
	s_or_b64 exec, exec, s[0:1]
	v_or_b32_e32 v94, 48, v146
	v_ashrrev_i32_e32 v95, 31, v94
	v_lshlrev_b64 v[84:85], 7, v[94:95]
	v_lshl_add_u64 v[90:91], v[134:135], 0, v[84:85]
	s_waitcnt lgkmcnt(0)
	s_waitcnt vmcnt(21)
	v_mov_b64_e32 v[86:87], v[206:207]
	v_mov_b64_e32 v[88:89], v[208:209]
	global_load_dwordx4 v[206:209], v[248:249], off offset:-2032
	s_nop 0
	s_waitcnt vmcnt(21)
	v_mov_b64_e32 v[90:91], v[214:215]
	v_mov_b64_e32 v[92:93], v[216:217]
	global_load_dwordx4 v[214:217], v[248:249], off offset:-2048
	s_waitcnt lgkmcnt(0)
	v_pk_add_f32 v[86:87], v[86:87], v[88:89]
	s_waitcnt lgkmcnt(0)
	v_pk_add_f32 v[90:91], v[90:91], v[92:93]
	s_nop 0
	v_pk_add_f32 v[86:87], v[90:91], v[86:87]
	ds_bpermute_b32 v88, v181, v86
	ds_bpermute_b32 v89, v181, v87
	s_waitcnt lgkmcnt(0)
	v_pk_add_f32 v[86:87], v[86:87], v[88:89]
	ds_bpermute_b32 v88, v180, v86
	ds_bpermute_b32 v89, v180, v87
	s_waitcnt lgkmcnt(0)
	v_pk_add_f32 v[86:87], v[86:87], v[88:89]
	s_nop 0
	v_pk_mul_f32 v[96:97], v[86:87], s[82:83] op_sel_hi:[1,0]
	v_lshlrev_b64 v[86:87], 11, v[94:95]
	v_lshl_add_u64 v[86:87], s[70:71], 0, v[86:87]
	v_lshl_add_u64 v[92:93], v[144:145], 1, v[86:87]
	v_add_u32_e32 v243, 0x48000, v242
	s_waitcnt vmcnt(21)
	v_mov_b64_e32 v[86:87], v[234:235]
	global_load_dwordx2 v[234:235], v243, s[70:71]
	v_fma_f32 v3, -v96, v96, v97
	v_max_f32_e32 v3, 0, v3
	v_add_f32_e32 v3, 0x3727c5ac, v3
	v_rsq_f32_e32 v98, v3
	s_waitcnt lgkmcnt(0)
	v_lshlrev_b32_e32 v3, 16, v86
	v_and_b32_e32 v86, 0xffff0000, v86
	v_lshlrev_b32_e32 v88, 16, v87
	v_and_b32_e32 v89, 0xffff0000, v87
	v_sub_f32_e32 v87, v86, v96
	v_sub_f32_e32 v86, v3, v96
	v_sub_f32_e32 v89, v89, v96
	v_sub_f32_e32 v88, v88, v96
	v_pk_mul_f32 v[90:91], v[88:89], v[98:99] op_sel_hi:[1,0]
	v_pk_mul_f32 v[94:95], v[86:87], v[98:99] op_sel_hi:[1,0]
	ds_read_b128 v[86:89], v244
	ds_read_b128 v[100:103], v244 offset:256
	s_waitcnt lgkmcnt(0)
	v_pk_fma_f32 v[88:89], v[88:89], v[90:91], v[102:103]
	s_nop 0
	v_pk_fma_f32 v[82:83], v[88:89], s[72:73], v[82:83] op_sel_hi:[1,0,1]
	s_waitcnt vmcnt(21)
	v_mov_b64_e32 v[88:89], v[236:237]
	global_load_dwordx2 v[236:237], v243, s[70:71] offset:32
	v_pk_fma_f32 v[86:87], v[86:87], v[94:95], v[100:101]
	s_waitcnt lgkmcnt(0)
	v_lshlrev_b32_e32 v3, 16, v88
	v_pk_fma_f32 v[80:81], v[86:87], s[72:73], v[80:81] op_sel_hi:[1,0,1]
	v_cvt_pk_bf16_f32 v87, v82, v83
	v_cvt_pk_bf16_f32 v86, v80, v81
	v_and_b32_e32 v81, 0xffff0000, v88
	v_lshlrev_b32_e32 v83, 16, v89
	v_and_b32_e32 v90, 0xffff0000, v89
	global_store_dwordx2 v[92:93], v[86:87], off
	v_sub_f32_e32 v89, v81, v96
	v_sub_f32_e32 v88, v3, v96
	v_sub_f32_e32 v91, v90, v96
	v_sub_f32_e32 v90, v83, v96
	v_pk_mul_f32 v[94:95], v[98:99], v[90:91] op_sel_hi:[0,1]
	v_pk_mul_f32 v[104:105], v[98:99], v[88:89] op_sel_hi:[0,1]
	ds_read_b128 v[88:91], v244 offset:64
	ds_read_b128 v[100:103], v244 offset:320
	v_and_b32_e32 v82, 0xffff0000, v86
	v_lshlrev_b32_e32 v80, 16, v87
	s_waitcnt lgkmcnt(0)
	v_pk_fma_f32 v[88:89], v[88:89], v[104:105], v[100:101]
	s_nop 0
	v_pk_fma_f32 v[76:77], v[88:89], s[72:73], v[76:77] op_sel_hi:[1,0,1]
	s_waitcnt vmcnt(21)
	v_mov_b64_e32 v[88:89], v[238:239]
	global_load_dwordx2 v[238:239], v243, s[70:71] offset:256
	v_pk_fma_f32 v[90:91], v[90:91], v[94:95], v[102:103]
	v_cvt_pk_bf16_f32 v94, v76, v77
	v_pk_fma_f32 v[78:79], v[90:91], s[72:73], v[78:79] op_sel_hi:[1,0,1]
	s_waitcnt lgkmcnt(0)
	v_lshlrev_b32_e32 v3, 16, v88
	v_cvt_pk_bf16_f32 v95, v78, v79
	v_lshlrev_b32_e32 v78, 16, v95
	v_and_b32_e32 v79, 0xffff0000, v95
	v_mul_f32_e32 v76, v78, v78
	v_pk_fma_f32 v[76:77], v[78:79], v[78:79], v[76:77] op_sel_hi:[1,1,0]
	v_lshlrev_b32_e32 v81, 16, v89
	v_and_b32_e32 v76, 0xffff0000, v88
	v_and_b32_e32 v83, 0xffff0000, v89
	global_store_dwordx2 v[92:93], v[94:95], off offset:32
	v_sub_f32_e32 v89, v76, v96
	v_sub_f32_e32 v88, v3, v96
	v_sub_f32_e32 v91, v83, v96
	v_sub_f32_e32 v90, v81, v96
	v_pk_mul_f32 v[104:105], v[98:99], v[90:91] op_sel_hi:[0,1]
	v_pk_mul_f32 v[106:107], v[98:99], v[88:89] op_sel_hi:[0,1]
	ds_read_b128 v[88:91], v244 offset:128
	ds_read_b128 v[100:103], v244 offset:384
	v_and_b32_e32 v95, 0xffff0000, v94
	s_waitcnt lgkmcnt(0)
	v_pk_fma_f32 v[88:89], v[88:89], v[106:107], v[100:101]
	s_waitcnt vmcnt(21)
	v_mov_b64_e32 v[100:101], v[240:241]
	global_load_dwordx2 v[240:241], v243, s[70:71] offset:288
	v_pk_fma_f32 v[90:91], v[90:91], v[104:105], v[102:103]
	v_pk_fma_f32 v[72:73], v[88:89], s[72:73], v[72:73] op_sel_hi:[1,0,1]
	v_pk_fma_f32 v[74:75], v[90:91], s[72:73], v[74:75] op_sel_hi:[1,0,1]
	v_cvt_pk_bf16_f32 v72, v72, v73
	v_cvt_pk_bf16_f32 v73, v74, v75
	global_store_dwordx2 v[92:93], v[72:73], off offset:256
	v_lshlrev_b32_e32 v88, 16, v72
	v_and_b32_e32 v90, 0xffff0000, v72
	v_lshlrev_b32_e32 v72, 16, v73
	v_and_b32_e32 v74, 0xffff0000, v73
	v_mul_f32_e32 v89, v88, v88
	v_mul_f32_e32 v91, v90, v90
	v_mul_f32_e32 v73, v72, v72
	v_mul_f32_e32 v75, v74, v74
	v_pk_add_f32 v[72:73], v[72:73], v[74:75]
	s_waitcnt lgkmcnt(0)
	v_lshlrev_b32_e32 v3, 16, v100
	v_and_b32_e32 v76, 0xffff0000, v100
	v_lshlrev_b32_e32 v81, 16, v101
	v_and_b32_e32 v83, 0xffff0000, v101
	v_sub_f32_e32 v101, v76, v96
	v_sub_f32_e32 v100, v3, v96
	v_sub_f32_e32 v97, v83, v96
	v_sub_f32_e32 v96, v81, v96
	v_pk_mul_f32 v[96:97], v[98:99], v[96:97] op_sel_hi:[0,1]
	v_pk_mul_f32 v[98:99], v[98:99], v[100:101] op_sel_hi:[0,1]
	ds_read_b128 v[100:103], v244 offset:192
	ds_read_b128 v[104:107], v244 offset:448
	v_mov_b32_e32 v81, v95
	v_mov_b32_e32 v3, v77
	s_waitcnt lgkmcnt(0)
; __device__ __forceinline__ u32x2 pk4(f32x4 v) { u32x2 r; r.x = pk2(v.x, v.y); r.y = pk2(v.z, v.w); return r; }
; __device__ __forceinline__ void stats_main(const float* stm, int row, int fq, float& mu, float& rs) {
;     const f32x4* p = (const f32x4*)(stm + (size_t)row * 32 + fq * 8);
;     const f32x4 a = p[0], b = p[1];
;     float s1 = (a.x + a.z) + (b.x + b.z), s2 = (a.y + a.w) + (b.y + b.w);
;     s1 += __shfl_xor(s1, 16); s2 += __shfl_xor(s2, 16); s1 += __shfl_xor(s1, 32); s2 += __shfl_xor(s2, 32);
;     mu = s1 * (1.f / DM); rs = __builtin_amdgcn_rsqf(fmaxf(s2 * (1.f / DM) - mu * mu, 0.f) + LN_EPS);
;     __device__ __forceinline__ void operator()(const f32x4 (&acc)[2][2][4][2], const pg8::Unit& u, int wr, int wc, int fr, int fq) const {
;     ...
;                 for (int bj = 0; bj < 2; ++bj)
; #pragma unroll
;                     for (int n = 0; n < 2; ++n) {
;                         const int col = u.pn * 256 + bj * 128 + wc * 32 + n * 16 + fq * 4;
;                         const u32x2 raw = *(const u32x2*)(src + (size_t)row * DM + col);
;                         f32x4 x = (f32x4){bflo(raw.x), bfhi(raw.x), bflo(raw.y), bfhi(raw.y)};
;                         if (ln) x = (x - mu) * rs * *(const f32x4*)(g + col) + *(const f32x4*)(b + col);
;                         const u32x2 pz = pk4(x * ALPHA + acc[ai][bj][m][n]);
;                         *(u32x2*)(dst + (size_t)row * DM + col) = pz;
;                         const float z0 = bflo(pz.x), z1 = bfhi(pz.x), z2 = bflo(pz.y), z3 = bfhi(pz.y);
;                         s1 += (z0 + z1) + (z2 + z3); s2 += (z0 * z0 + z1 * z1) + (z2 * z2 + z3 * z3);
;                     }
;                 s1 += __shfl_xor(s1, 16); s2 += __shfl_xor(s2, 16); s1 += __shfl_xor(s1, 32); s2 += __shfl_xor(s2, 32);
;                 if (fq == 0) { float* p = stm_n + (size_t)row * 32 + (u.pn * 4 + wc) * 2; p[0] = s1; p[1] = s2; }
	v_pk_fma_f32 v[98:99], v[100:101], v[98:99], v[104:105]
	s_nop 0
	v_pk_fma_f32 v[68:69], v[98:99], s[72:73], v[68:69] op_sel_hi:[1,0,1]
	v_lshlrev_b32_e32 v99, 16, v94
	v_lshlrev_b32_e32 v98, 16, v86
	v_mov_b32_e32 v83, v99
	v_pk_fma_f32 v[96:97], v[102:103], v[96:97], v[106:107]
	v_pk_mul_f32 v[100:101], v[98:99], v[98:99]
	v_pk_mul_f32 v[102:103], v[82:83], v[82:83]
	v_and_b32_e32 v94, 0xffff0000, v87
	v_pk_mul_f32 v[86:87], v[80:81], v[80:81]
	v_pk_mul_f32 v[104:105], v[94:95], v[94:95]
	v_pk_mov_b32 v[106:107], v[98:99], v[100:101] op_sel:[1,0]
	v_pk_mov_b32 v[102:103], v[94:95], v[102:103] op_sel:[1,0]
	v_pk_add_f32 v[82:83], v[98:99], v[82:83]
	v_pk_add_f32 v[80:81], v[94:95], v[80:81]
	v_pk_fma_f32 v[70:71], v[96:97], s[72:73], v[70:71] op_sel_hi:[1,0,1]
	v_pk_add_f32 v[102:103], v[106:107], v[102:103]
	v_mov_b32_e32 v106, v78
	v_mov_b32_e32 v107, v86
	v_pk_mov_b32 v[78:79], v[78:79], v[104:105] op_sel:[1,0]
	v_mov_b32_e32 v83, v101
	v_mov_b32_e32 v81, v105
	v_cvt_pk_bf16_f32 v68, v68, v69
	v_cvt_pk_bf16_f32 v69, v70, v71
	v_pk_add_f32 v[78:79], v[106:107], v[78:79]
	v_pk_add_f32 v[80:81], v[82:83], v[80:81]
	global_store_dwordx2 v[92:93], v[68:69], off offset:288
	v_lshlrev_b32_e32 v92, 16, v68
	v_and_b32_e32 v96, 0xffff0000, v68
	v_lshlrev_b32_e32 v68, 16, v69
	v_and_b32_e32 v70, 0xffff0000, v69
	v_pk_add_f32 v[78:79], v[102:103], v[78:79]
	v_pk_add_f32 v[76:77], v[80:81], v[2:3]
	v_mul_f32_e32 v93, v92, v92
	v_mul_f32_e32 v97, v96, v96
	v_mul_f32_e32 v69, v68, v68
	v_mul_f32_e32 v71, v70, v70
	v_pk_add_f32 v[76:77], v[78:79], v[76:77]
	v_pk_add_f32 v[78:79], v[88:89], v[90:91]
	v_pk_add_f32 v[74:75], v[92:93], v[96:97]
	v_pk_add_f32 v[72:73], v[78:79], v[72:73]
	v_pk_add_f32 v[68:69], v[68:69], v[70:71]
	v_pk_add_f32 v[72:73], v[76:77], v[72:73]
	v_pk_add_f32 v[68:69], v[74:75], v[68:69]
	s_nop 0
	v_pk_add_f32 v[68:69], v[72:73], v[68:69]
	ds_bpermute_b32 v70, v181, v68
	ds_bpermute_b32 v71, v181, v69
	s_waitcnt lgkmcnt(0)
	v_pk_add_f32 v[68:69], v[68:69], v[70:71]
	ds_bpermute_b32 v70, v180, v68
	ds_bpermute_b32 v71, v180, v69
	s_and_saveexec_b64 s[0:1], s[40:41]
	s_cbranch_execz .LBB0_2385
	v_lshl_add_u64 v[72:73], s[52:53], 0, v[84:85]
	v_lshl_add_u64 v[72:73], s[68:69], 2, v[72:73]
	s_waitcnt lgkmcnt(0)
	v_pk_add_f32 v[68:69], v[68:69], v[70:71]
	global_store_dwordx2 v[72:73], v[68:69], off
.LBB0_2385:
	s_or_b64 exec, exec, s[0:1]
	v_add_u32_e32 v78, 0x80, v146
	v_ashrrev_i32_e32 v79, 31, v78
	v_lshlrev_b64 v[68:69], 7, v[78:79]
	v_lshl_add_u64 v[74:75], v[134:135], 0, v[68:69]
	s_waitcnt lgkmcnt(0)
	s_waitcnt vmcnt(21)
	v_mov_b64_e32 v[70:71], v[190:191]
	v_mov_b64_e32 v[72:73], v[192:193]
	global_load_dwordx4 v[190:193], v[248:249], off offset:16
	s_nop 0
	s_waitcnt vmcnt(21)
	v_mov_b64_e32 v[74:75], v[194:195]
	v_mov_b64_e32 v[76:77], v[196:197]
	global_load_dwordx4 v[194:197], v[248:249], off
	s_waitcnt lgkmcnt(0)
	v_pk_add_f32 v[70:71], v[70:71], v[72:73]
	s_waitcnt lgkmcnt(0)
	v_pk_add_f32 v[74:75], v[74:75], v[76:77]
	s_nop 0
	v_pk_add_f32 v[70:71], v[74:75], v[70:71]
	ds_bpermute_b32 v72, v181, v70
	ds_bpermute_b32 v73, v181, v71
	s_waitcnt lgkmcnt(0)
	v_pk_add_f32 v[70:71], v[70:71], v[72:73]
	ds_bpermute_b32 v72, v180, v70
	ds_bpermute_b32 v73, v180, v71
	s_waitcnt lgkmcnt(0)
	v_pk_add_f32 v[70:71], v[70:71], v[72:73]
	s_nop 0
	v_pk_mul_f32 v[80:81], v[70:71], s[82:83] op_sel_hi:[1,0]
	v_lshlrev_b64 v[70:71], 11, v[78:79]
	v_lshl_add_u64 v[70:71], s[70:71], 0, v[70:71]
	v_lshl_add_u64 v[76:77], v[144:145], 1, v[70:71]
	v_add_u32_e32 v243, 0x50000, v242
	s_waitcnt vmcnt(21)
	v_mov_b64_e32 v[70:71], v[198:199]
	global_load_dwordx2 v[198:199], v243, s[70:71]
	v_fma_f32 v3, -v80, v80, v81
	v_max_f32_e32 v3, 0, v3
	v_add_f32_e32 v3, 0x3727c5ac, v3
	v_rsq_f32_e32 v82, v3
	s_waitcnt lgkmcnt(0)
	v_lshlrev_b32_e32 v3, 16, v70
	v_and_b32_e32 v70, 0xffff0000, v70
	v_lshlrev_b32_e32 v72, 16, v71
	v_and_b32_e32 v73, 0xffff0000, v71
	v_sub_f32_e32 v71, v70, v80
	v_sub_f32_e32 v70, v3, v80
	v_sub_f32_e32 v73, v73, v80
	v_sub_f32_e32 v72, v72, v80
	v_pk_mul_f32 v[74:75], v[72:73], v[82:83] op_sel_hi:[1,0]
	v_pk_mul_f32 v[78:79], v[70:71], v[82:83] op_sel_hi:[1,0]
	ds_read_b128 v[70:73], v244
	ds_read_b128 v[84:87], v244 offset:256
	s_waitcnt lgkmcnt(0)
	v_pk_fma_f32 v[72:73], v[72:73], v[74:75], v[86:87]
	s_nop 0
	v_pk_fma_f32 v[66:67], v[72:73], s[72:73], v[66:67] op_sel_hi:[1,0,1]
	s_waitcnt vmcnt(21)
	v_mov_b64_e32 v[72:73], v[200:201]
	global_load_dwordx2 v[200:201], v243, s[70:71] offset:32
	v_pk_fma_f32 v[70:71], v[70:71], v[78:79], v[84:85]
	s_waitcnt lgkmcnt(0)
	v_lshlrev_b32_e32 v3, 16, v72
	v_pk_fma_f32 v[64:65], v[70:71], s[72:73], v[64:65] op_sel_hi:[1,0,1]
	v_cvt_pk_bf16_f32 v71, v66, v67
	v_cvt_pk_bf16_f32 v70, v64, v65
	v_and_b32_e32 v65, 0xffff0000, v72
	v_lshlrev_b32_e32 v67, 16, v73
	v_and_b32_e32 v74, 0xffff0000, v73
	global_store_dwordx2 v[76:77], v[70:71], off
	v_sub_f32_e32 v73, v65, v80
	v_sub_f32_e32 v72, v3, v80
	v_sub_f32_e32 v75, v74, v80
	v_sub_f32_e32 v74, v67, v80
	v_pk_mul_f32 v[78:79], v[82:83], v[74:75] op_sel_hi:[0,1]
	v_pk_mul_f32 v[88:89], v[82:83], v[72:73] op_sel_hi:[0,1]
	ds_read_b128 v[72:75], v244 offset:64
	ds_read_b128 v[84:87], v244 offset:320
	v_and_b32_e32 v66, 0xffff0000, v70
	v_lshlrev_b32_e32 v64, 16, v71
	s_waitcnt lgkmcnt(0)
	v_pk_fma_f32 v[72:73], v[72:73], v[88:89], v[84:85]
	s_nop 0
	v_pk_fma_f32 v[60:61], v[72:73], s[72:73], v[60:61] op_sel_hi:[1,0,1]
	s_waitcnt vmcnt(21)
	v_mov_b64_e32 v[72:73], v[202:203]
	global_load_dwordx2 v[202:203], v243, s[70:71] offset:256
	v_pk_fma_f32 v[74:75], v[74:75], v[78:79], v[86:87]
	v_cvt_pk_bf16_f32 v78, v60, v61
	v_pk_fma_f32 v[62:63], v[74:75], s[72:73], v[62:63] op_sel_hi:[1,0,1]
	s_waitcnt lgkmcnt(0)
; __device__ __forceinline__ u32x2 pk4(f32x4 v) { u32x2 r; r.x = pk2(v.x, v.y); r.y = pk2(v.z, v.w); return r; }
;     __device__ __forceinline__ void operator()(const f32x4 (&acc)[2][2][4][2], const pg8::Unit& u, int wr, int wc, int fr, int fq) const {
;     ...
;                 for (int bj = 0; bj < 2; ++bj)
; #pragma unroll
;                     for (int n = 0; n < 2; ++n) {
;                         const int col = u.pn * 256 + bj * 128 + wc * 32 + n * 16 + fq * 4;
;                         const u32x2 raw = *(const u32x2*)(src + (size_t)row * DM + col);
;                         f32x4 x = (f32x4){bflo(raw.x), bfhi(raw.x), bflo(raw.y), bfhi(raw.y)};
;                         if (ln) x = (x - mu) * rs * *(const f32x4*)(g + col) + *(const f32x4*)(b + col);
;                         const u32x2 pz = pk4(x * ALPHA + acc[ai][bj][m][n]);
;                         *(u32x2*)(dst + (size_t)row * DM + col) = pz;
;                         const float z0 = bflo(pz.x), z1 = bfhi(pz.x), z2 = bflo(pz.y), z3 = bfhi(pz.y);
;                         s1 += (z0 + z1) + (z2 + z3); s2 += (z0 * z0 + z1 * z1) + (z2 * z2 + z3 * z3);
;                     }
;                 s1 += __shfl_xor(s1, 16); s2 += __shfl_xor(s2, 16); s1 += __shfl_xor(s1, 32); s2 += __shfl_xor(s2, 32);
;                 if (fq == 0) { float* p = stm_n + (size_t)row * 32 + (u.pn * 4 + wc) * 2; p[0] = s1; p[1] = s2; }
	v_lshlrev_b32_e32 v3, 16, v72
	v_cvt_pk_bf16_f32 v79, v62, v63
	v_lshlrev_b32_e32 v62, 16, v79
	v_and_b32_e32 v63, 0xffff0000, v79
	v_mul_f32_e32 v60, v62, v62
	v_pk_fma_f32 v[60:61], v[62:63], v[62:63], v[60:61] op_sel_hi:[1,1,0]
	v_lshlrev_b32_e32 v65, 16, v73
	v_and_b32_e32 v60, 0xffff0000, v72
	v_and_b32_e32 v67, 0xffff0000, v73
	global_store_dwordx2 v[76:77], v[78:79], off offset:32
	v_sub_f32_e32 v73, v60, v80
	v_sub_f32_e32 v72, v3, v80
	v_sub_f32_e32 v75, v67, v80
	v_sub_f32_e32 v74, v65, v80
	v_pk_mul_f32 v[88:89], v[82:83], v[74:75] op_sel_hi:[0,1]
	v_pk_mul_f32 v[90:91], v[82:83], v[72:73] op_sel_hi:[0,1]
	ds_read_b128 v[72:75], v244 offset:128
	ds_read_b128 v[84:87], v244 offset:384
	v_and_b32_e32 v79, 0xffff0000, v78
	s_waitcnt lgkmcnt(0)
	v_pk_fma_f32 v[72:73], v[72:73], v[90:91], v[84:85]
	s_waitcnt vmcnt(21)
	v_mov_b64_e32 v[84:85], v[204:205]
	global_load_dwordx2 v[204:205], v243, s[70:71] offset:288
	v_pk_fma_f32 v[74:75], v[74:75], v[88:89], v[86:87]
	v_pk_fma_f32 v[56:57], v[72:73], s[72:73], v[56:57] op_sel_hi:[1,0,1]
	v_pk_fma_f32 v[58:59], v[74:75], s[72:73], v[58:59] op_sel_hi:[1,0,1]
	v_cvt_pk_bf16_f32 v56, v56, v57
	v_cvt_pk_bf16_f32 v57, v58, v59
	global_store_dwordx2 v[76:77], v[56:57], off offset:256
	v_lshlrev_b32_e32 v72, 16, v56
	v_and_b32_e32 v74, 0xffff0000, v56
	v_lshlrev_b32_e32 v56, 16, v57
	v_and_b32_e32 v58, 0xffff0000, v57
	v_mul_f32_e32 v73, v72, v72
	v_mul_f32_e32 v75, v74, v74
	v_mul_f32_e32 v57, v56, v56
	v_mul_f32_e32 v59, v58, v58
	v_pk_add_f32 v[56:57], v[56:57], v[58:59]
	s_waitcnt lgkmcnt(0)
	v_lshlrev_b32_e32 v3, 16, v84
	v_and_b32_e32 v60, 0xffff0000, v84
	v_lshlrev_b32_e32 v65, 16, v85
	v_and_b32_e32 v67, 0xffff0000, v85
	v_sub_f32_e32 v85, v60, v80
	v_sub_f32_e32 v84, v3, v80
	v_sub_f32_e32 v81, v67, v80
	v_sub_f32_e32 v80, v65, v80
	v_pk_mul_f32 v[80:81], v[82:83], v[80:81] op_sel_hi:[0,1]
	v_pk_mul_f32 v[82:83], v[82:83], v[84:85] op_sel_hi:[0,1]
	ds_read_b128 v[84:87], v244 offset:192
	ds_read_b128 v[88:91], v244 offset:448
	v_mov_b32_e32 v65, v79
	v_mov_b32_e32 v3, v61
	s_waitcnt lgkmcnt(0)
	v_pk_fma_f32 v[82:83], v[84:85], v[82:83], v[88:89]
	s_nop 0
	v_pk_fma_f32 v[52:53], v[82:83], s[72:73], v[52:53] op_sel_hi:[1,0,1]
	v_lshlrev_b32_e32 v83, 16, v78
	v_lshlrev_b32_e32 v82, 16, v70
	v_mov_b32_e32 v67, v83
	v_pk_fma_f32 v[80:81], v[86:87], v[80:81], v[90:91]
	v_pk_mul_f32 v[84:85], v[82:83], v[82:83]
	v_pk_mul_f32 v[86:87], v[66:67], v[66:67]
	v_and_b32_e32 v78, 0xffff0000, v71
	v_pk_mul_f32 v[70:71], v[64:65], v[64:65]
	v_pk_mul_f32 v[88:89], v[78:79], v[78:79]
	v_pk_mov_b32 v[90:91], v[82:83], v[84:85] op_sel:[1,0]
	v_pk_mov_b32 v[86:87], v[78:79], v[86:87] op_sel:[1,0]
	v_pk_add_f32 v[66:67], v[82:83], v[66:67]
	v_pk_add_f32 v[64:65], v[78:79], v[64:65]
	v_pk_fma_f32 v[54:55], v[80:81], s[72:73], v[54:55] op_sel_hi:[1,0,1]
	v_pk_add_f32 v[86:87], v[90:91], v[86:87]
	v_mov_b32_e32 v90, v62
	v_mov_b32_e32 v91, v70
	v_pk_mov_b32 v[62:63], v[62:63], v[88:89] op_sel:[1,0]
	v_mov_b32_e32 v67, v85
	v_mov_b32_e32 v65, v89
	v_cvt_pk_bf16_f32 v52, v52, v53
	v_cvt_pk_bf16_f32 v53, v54, v55
	v_pk_add_f32 v[62:63], v[90:91], v[62:63]
	v_pk_add_f32 v[64:65], v[66:67], v[64:65]
	global_store_dwordx2 v[76:77], v[52:53], off offset:288
	v_lshlrev_b32_e32 v76, 16, v52
	v_and_b32_e32 v80, 0xffff0000, v52
	v_lshlrev_b32_e32 v52, 16, v53
	v_and_b32_e32 v54, 0xffff0000, v53
	v_pk_add_f32 v[62:63], v[86:87], v[62:63]
	v_pk_add_f32 v[60:61], v[64:65], v[2:3]
	v_mul_f32_e32 v77, v76, v76
	v_mul_f32_e32 v81, v80, v80
	v_mul_f32_e32 v53, v52, v52
	v_mul_f32_e32 v55, v54, v54
	v_pk_add_f32 v[60:61], v[62:63], v[60:61]
	v_pk_add_f32 v[62:63], v[72:73], v[74:75]
	v_pk_add_f32 v[58:59], v[76:77], v[80:81]
	v_pk_add_f32 v[56:57], v[62:63], v[56:57]
	v_pk_add_f32 v[52:53], v[52:53], v[54:55]
	v_pk_add_f32 v[56:57], v[60:61], v[56:57]
	v_pk_add_f32 v[52:53], v[58:59], v[52:53]
	s_nop 0
	v_pk_add_f32 v[52:53], v[56:57], v[52:53]
	ds_bpermute_b32 v54, v181, v52
	ds_bpermute_b32 v55, v181, v53
	s_waitcnt lgkmcnt(0)
	v_pk_add_f32 v[52:53], v[52:53], v[54:55]
	ds_bpermute_b32 v54, v180, v52
	ds_bpermute_b32 v55, v180, v53
	s_and_saveexec_b64 s[0:1], s[40:41]
	s_cbranch_execz .LBB0_2387
	v_lshl_add_u64 v[56:57], s[52:53], 0, v[68:69]
	v_lshl_add_u64 v[56:57], s[68:69], 2, v[56:57]
	s_waitcnt lgkmcnt(0)
	v_pk_add_f32 v[52:53], v[52:53], v[54:55]
	global_store_dwordx2 v[56:57], v[52:53], off
; __device__ __forceinline__ u32x2 pk4(f32x4 v) { u32x2 r; r.x = pk2(v.x, v.y); r.y = pk2(v.z, v.w); return r; }
; __device__ __forceinline__ void stats_main(const float* stm, int row, int fq, float& mu, float& rs) {
;     const f32x4* p = (const f32x4*)(stm + (size_t)row * 32 + fq * 8);
;     const f32x4 a = p[0], b = p[1];
;     float s1 = (a.x + a.z) + (b.x + b.z), s2 = (a.y + a.w) + (b.y + b.w);
;     s1 += __shfl_xor(s1, 16); s2 += __shfl_xor(s2, 16); s1 += __shfl_xor(s1, 32); s2 += __shfl_xor(s2, 32);
;     mu = s1 * (1.f / DM); rs = __builtin_amdgcn_rsqf(fmaxf(s2 * (1.f / DM) - mu * mu, 0.f) + LN_EPS);
;     __device__ __forceinline__ void operator()(const f32x4 (&acc)[2][2][4][2], const pg8::Unit& u, int wr, int wc, int fr, int fq) const {
;     ...
;                 const int row = u.pm * 256 + ai * 128 + wr * 64 + m * 16 + fr;
;                 float mu = 0.f, rs = 1.f; if (ln) stats_main(stm_p, row, fq, mu, rs);
;                 float s1 = 0.f, s2 = 0.f;
; #pragma unroll
;                 for (int bj = 0; bj < 2; ++bj)
; #pragma unroll
;                     for (int n = 0; n < 2; ++n) {
;                         const int col = u.pn * 256 + bj * 128 + wc * 32 + n * 16 + fq * 4;
;                         const u32x2 raw = *(const u32x2*)(src + (size_t)row * DM + col);
;                         f32x4 x = (f32x4){bflo(raw.x), bfhi(raw.x), bflo(raw.y), bfhi(raw.y)};
;                         if (ln) x = (x - mu) * rs * *(const f32x4*)(g + col) + *(const f32x4*)(b + col);
;                         const u32x2 pz = pk4(x * ALPHA + acc[ai][bj][m][n]);
;                         *(u32x2*)(dst + (size_t)row * DM + col) = pz;
;                         const float z0 = bflo(pz.x), z1 = bfhi(pz.x), z2 = bflo(pz.y), z3 = bfhi(pz.y);
;                         s1 += (z0 + z1) + (z2 + z3); s2 += (z0 * z0 + z1 * z1) + (z2 * z2 + z3 * z3);
.LBB0_2387:
	s_or_b64 exec, exec, s[0:1]
	v_add_u32_e32 v62, 0x90, v146
	v_ashrrev_i32_e32 v63, 31, v62
	v_lshlrev_b64 v[52:53], 7, v[62:63]
	v_lshl_add_u64 v[58:59], v[134:135], 0, v[52:53]
	s_waitcnt lgkmcnt(0)
	s_waitcnt vmcnt(21)
	v_mov_b64_e32 v[54:55], v[206:207]
	v_mov_b64_e32 v[56:57], v[208:209]
	global_load_dwordx4 v[206:209], v[248:249], off offset:2064
	s_nop 0
	s_waitcnt vmcnt(21)
	v_mov_b64_e32 v[58:59], v[214:215]
	v_mov_b64_e32 v[60:61], v[216:217]
	global_load_dwordx4 v[214:217], v[248:249], off offset:2048
	s_waitcnt lgkmcnt(0)
	v_pk_add_f32 v[54:55], v[54:55], v[56:57]
	s_waitcnt lgkmcnt(0)
	v_pk_add_f32 v[58:59], v[58:59], v[60:61]
	s_nop 0
	v_pk_add_f32 v[54:55], v[58:59], v[54:55]
	ds_bpermute_b32 v56, v181, v54
	ds_bpermute_b32 v57, v181, v55
	s_waitcnt lgkmcnt(0)
	v_pk_add_f32 v[54:55], v[54:55], v[56:57]
	ds_bpermute_b32 v56, v180, v54
	ds_bpermute_b32 v57, v180, v55
	s_waitcnt lgkmcnt(0)
	v_pk_add_f32 v[54:55], v[54:55], v[56:57]
	s_nop 0
	v_pk_mul_f32 v[64:65], v[54:55], s[82:83] op_sel_hi:[1,0]
	v_lshlrev_b64 v[54:55], 11, v[62:63]
	v_lshl_add_u64 v[54:55], s[70:71], 0, v[54:55]
	v_lshl_add_u64 v[60:61], v[144:145], 1, v[54:55]
	v_add_u32_e32 v243, 0x58000, v242
	s_waitcnt vmcnt(21)
	v_mov_b64_e32 v[54:55], v[234:235]
	global_load_dwordx2 v[234:235], v243, s[70:71]
	v_fma_f32 v3, -v64, v64, v65
	v_max_f32_e32 v3, 0, v3
	v_add_f32_e32 v3, 0x3727c5ac, v3
	v_rsq_f32_e32 v66, v3
	s_waitcnt lgkmcnt(0)
	v_lshlrev_b32_e32 v3, 16, v54
	v_and_b32_e32 v54, 0xffff0000, v54
	v_lshlrev_b32_e32 v56, 16, v55
	v_and_b32_e32 v57, 0xffff0000, v55
	v_sub_f32_e32 v55, v54, v64
	v_sub_f32_e32 v54, v3, v64
	v_sub_f32_e32 v57, v57, v64
	v_sub_f32_e32 v56, v56, v64
	v_pk_mul_f32 v[58:59], v[56:57], v[66:67] op_sel_hi:[1,0]
	v_pk_mul_f32 v[62:63], v[54:55], v[66:67] op_sel_hi:[1,0]
	ds_read_b128 v[54:57], v244
	ds_read_b128 v[68:71], v244 offset:256
	s_waitcnt lgkmcnt(0)
	v_pk_fma_f32 v[56:57], v[56:57], v[58:59], v[70:71]
	s_nop 0
	v_pk_fma_f32 v[50:51], v[56:57], s[72:73], v[50:51] op_sel_hi:[1,0,1]
	s_waitcnt vmcnt(21)
	v_mov_b64_e32 v[56:57], v[236:237]
	global_load_dwordx2 v[236:237], v243, s[70:71] offset:32
	v_pk_fma_f32 v[54:55], v[54:55], v[62:63], v[68:69]
	s_waitcnt lgkmcnt(0)
	v_lshlrev_b32_e32 v3, 16, v56
	v_pk_fma_f32 v[48:49], v[54:55], s[72:73], v[48:49] op_sel_hi:[1,0,1]
	v_cvt_pk_bf16_f32 v55, v50, v51
	v_cvt_pk_bf16_f32 v54, v48, v49
	v_and_b32_e32 v49, 0xffff0000, v56
	v_lshlrev_b32_e32 v51, 16, v57
	v_and_b32_e32 v58, 0xffff0000, v57
	global_store_dwordx2 v[60:61], v[54:55], off
	v_sub_f32_e32 v57, v49, v64
	v_sub_f32_e32 v56, v3, v64
	v_sub_f32_e32 v59, v58, v64
	v_sub_f32_e32 v58, v51, v64
	v_pk_mul_f32 v[62:63], v[66:67], v[58:59] op_sel_hi:[0,1]
	v_pk_mul_f32 v[72:73], v[66:67], v[56:57] op_sel_hi:[0,1]
	ds_read_b128 v[56:59], v244 offset:64
	ds_read_b128 v[68:71], v244 offset:320
	v_and_b32_e32 v50, 0xffff0000, v54
	v_lshlrev_b32_e32 v48, 16, v55
	s_waitcnt lgkmcnt(0)
	v_pk_fma_f32 v[56:57], v[56:57], v[72:73], v[68:69]
	s_nop 0
	v_pk_fma_f32 v[44:45], v[56:57], s[72:73], v[44:45] op_sel_hi:[1,0,1]
	s_waitcnt vmcnt(21)
	v_mov_b64_e32 v[56:57], v[238:239]
	global_load_dwordx2 v[238:239], v243, s[70:71] offset:256
	v_pk_fma_f32 v[58:59], v[58:59], v[62:63], v[70:71]
	v_cvt_pk_bf16_f32 v62, v44, v45
	v_pk_fma_f32 v[46:47], v[58:59], s[72:73], v[46:47] op_sel_hi:[1,0,1]
	s_waitcnt lgkmcnt(0)
	v_lshlrev_b32_e32 v3, 16, v56
	v_cvt_pk_bf16_f32 v63, v46, v47
	v_lshlrev_b32_e32 v46, 16, v63
	v_and_b32_e32 v47, 0xffff0000, v63
	v_mul_f32_e32 v44, v46, v46
	v_pk_fma_f32 v[44:45], v[46:47], v[46:47], v[44:45] op_sel_hi:[1,1,0]
	v_lshlrev_b32_e32 v49, 16, v57
	v_and_b32_e32 v44, 0xffff0000, v56
	v_and_b32_e32 v51, 0xffff0000, v57
	global_store_dwordx2 v[60:61], v[62:63], off offset:32
	v_sub_f32_e32 v57, v44, v64
	v_sub_f32_e32 v56, v3, v64
	v_sub_f32_e32 v59, v51, v64
	v_sub_f32_e32 v58, v49, v64
	v_pk_mul_f32 v[72:73], v[66:67], v[58:59] op_sel_hi:[0,1]
	v_pk_mul_f32 v[74:75], v[66:67], v[56:57] op_sel_hi:[0,1]
	ds_read_b128 v[56:59], v244 offset:128
	ds_read_b128 v[68:71], v244 offset:384
	v_and_b32_e32 v63, 0xffff0000, v62
	s_waitcnt lgkmcnt(0)
	v_pk_fma_f32 v[56:57], v[56:57], v[74:75], v[68:69]
	s_waitcnt vmcnt(21)
	v_mov_b64_e32 v[68:69], v[240:241]
	global_load_dwordx2 v[240:241], v243, s[70:71] offset:288
	v_pk_fma_f32 v[58:59], v[58:59], v[72:73], v[70:71]
	v_pk_fma_f32 v[40:41], v[56:57], s[72:73], v[40:41] op_sel_hi:[1,0,1]
	v_pk_fma_f32 v[42:43], v[58:59], s[72:73], v[42:43] op_sel_hi:[1,0,1]
	v_cvt_pk_bf16_f32 v40, v40, v41
	v_cvt_pk_bf16_f32 v41, v42, v43
	global_store_dwordx2 v[60:61], v[40:41], off offset:256
	v_lshlrev_b32_e32 v56, 16, v40
	v_and_b32_e32 v58, 0xffff0000, v40
	v_lshlrev_b32_e32 v40, 16, v41
	v_and_b32_e32 v42, 0xffff0000, v41
	v_mul_f32_e32 v57, v56, v56
	v_mul_f32_e32 v59, v58, v58
	v_mul_f32_e32 v41, v40, v40
	v_mul_f32_e32 v43, v42, v42
	v_pk_add_f32 v[40:41], v[40:41], v[42:43]
	s_waitcnt lgkmcnt(0)
	v_lshlrev_b32_e32 v3, 16, v68
	v_and_b32_e32 v44, 0xffff0000, v68
	v_lshlrev_b32_e32 v49, 16, v69
	v_and_b32_e32 v51, 0xffff0000, v69
	v_sub_f32_e32 v69, v44, v64
	v_sub_f32_e32 v68, v3, v64
	v_sub_f32_e32 v65, v51, v64
	v_sub_f32_e32 v64, v49, v64
	v_pk_mul_f32 v[64:65], v[66:67], v[64:65] op_sel_hi:[0,1]
	v_pk_mul_f32 v[66:67], v[66:67], v[68:69] op_sel_hi:[0,1]
	ds_read_b128 v[68:71], v244 offset:192
	ds_read_b128 v[72:75], v244 offset:448
	v_mov_b32_e32 v49, v63
	v_mov_b32_e32 v3, v45
	s_waitcnt lgkmcnt(0)
; __device__ __forceinline__ u32x2 pk4(f32x4 v) { u32x2 r; r.x = pk2(v.x, v.y); r.y = pk2(v.z, v.w); return r; }
; __device__ __forceinline__ void stats_main(const float* stm, int row, int fq, float& mu, float& rs) {
;     const f32x4* p = (const f32x4*)(stm + (size_t)row * 32 + fq * 8);
;     const f32x4 a = p[0], b = p[1];
;     float s1 = (a.x + a.z) + (b.x + b.z), s2 = (a.y + a.w) + (b.y + b.w);
;     s1 += __shfl_xor(s1, 16); s2 += __shfl_xor(s2, 16); s1 += __shfl_xor(s1, 32); s2 += __shfl_xor(s2, 32);
;     mu = s1 * (1.f / DM); rs = __builtin_amdgcn_rsqf(fmaxf(s2 * (1.f / DM) - mu * mu, 0.f) + LN_EPS);
;     __device__ __forceinline__ void operator()(const f32x4 (&acc)[2][2][4][2], const pg8::Unit& u, int wr, int wc, int fr, int fq) const {
;     ...
;                 for (int bj = 0; bj < 2; ++bj)
; #pragma unroll
;                     for (int n = 0; n < 2; ++n) {
;                         const int col = u.pn * 256 + bj * 128 + wc * 32 + n * 16 + fq * 4;
;                         const u32x2 raw = *(const u32x2*)(src + (size_t)row * DM + col);
;                         f32x4 x = (f32x4){bflo(raw.x), bfhi(raw.x), bflo(raw.y), bfhi(raw.y)};
;                         if (ln) x = (x - mu) * rs * *(const f32x4*)(g + col) + *(const f32x4*)(b + col);
;                         const u32x2 pz = pk4(x * ALPHA + acc[ai][bj][m][n]);
;                         *(u32x2*)(dst + (size_t)row * DM + col) = pz;
;                         const float z0 = bflo(pz.x), z1 = bfhi(pz.x), z2 = bflo(pz.y), z3 = bfhi(pz.y);
;                         s1 += (z0 + z1) + (z2 + z3); s2 += (z0 * z0 + z1 * z1) + (z2 * z2 + z3 * z3);
;                     }
;                 s1 += __shfl_xor(s1, 16); s2 += __shfl_xor(s2, 16); s1 += __shfl_xor(s1, 32); s2 += __shfl_xor(s2, 32);
;                 if (fq == 0) { float* p = stm_n + (size_t)row * 32 + (u.pn * 4 + wc) * 2; p[0] = s1; p[1] = s2; }
	v_pk_fma_f32 v[66:67], v[68:69], v[66:67], v[72:73]
	s_nop 0
	v_pk_fma_f32 v[36:37], v[66:67], s[72:73], v[36:37] op_sel_hi:[1,0,1]
	v_lshlrev_b32_e32 v67, 16, v62
	v_lshlrev_b32_e32 v66, 16, v54
	v_mov_b32_e32 v51, v67
	v_pk_fma_f32 v[64:65], v[70:71], v[64:65], v[74:75]
	v_pk_mul_f32 v[68:69], v[66:67], v[66:67]
	v_pk_mul_f32 v[70:71], v[50:51], v[50:51]
	v_and_b32_e32 v62, 0xffff0000, v55
	v_pk_mul_f32 v[54:55], v[48:49], v[48:49]
	v_pk_mul_f32 v[72:73], v[62:63], v[62:63]
	v_pk_mov_b32 v[74:75], v[66:67], v[68:69] op_sel:[1,0]
	v_pk_mov_b32 v[70:71], v[62:63], v[70:71] op_sel:[1,0]
	v_pk_add_f32 v[50:51], v[66:67], v[50:51]
	v_pk_add_f32 v[48:49], v[62:63], v[48:49]
	v_pk_fma_f32 v[38:39], v[64:65], s[72:73], v[38:39] op_sel_hi:[1,0,1]
	v_pk_add_f32 v[70:71], v[74:75], v[70:71]
	v_mov_b32_e32 v74, v46
	v_mov_b32_e32 v75, v54
	v_pk_mov_b32 v[46:47], v[46:47], v[72:73] op_sel:[1,0]
	v_mov_b32_e32 v51, v69
	v_mov_b32_e32 v49, v73
	v_cvt_pk_bf16_f32 v36, v36, v37
	v_cvt_pk_bf16_f32 v37, v38, v39
	v_pk_add_f32 v[46:47], v[74:75], v[46:47]
	v_pk_add_f32 v[48:49], v[50:51], v[48:49]
	global_store_dwordx2 v[60:61], v[36:37], off offset:288
	v_lshlrev_b32_e32 v60, 16, v36
	v_and_b32_e32 v64, 0xffff0000, v36
	v_lshlrev_b32_e32 v36, 16, v37
	v_and_b32_e32 v38, 0xffff0000, v37
	v_pk_add_f32 v[46:47], v[70:71], v[46:47]
	v_pk_add_f32 v[44:45], v[48:49], v[2:3]
	v_mul_f32_e32 v61, v60, v60
	v_mul_f32_e32 v65, v64, v64
	v_mul_f32_e32 v37, v36, v36
	v_mul_f32_e32 v39, v38, v38
	v_pk_add_f32 v[44:45], v[46:47], v[44:45]
	v_pk_add_f32 v[46:47], v[56:57], v[58:59]
	v_pk_add_f32 v[42:43], v[60:61], v[64:65]
	v_pk_add_f32 v[40:41], v[46:47], v[40:41]
	v_pk_add_f32 v[36:37], v[36:37], v[38:39]
	v_pk_add_f32 v[40:41], v[44:45], v[40:41]
	v_pk_add_f32 v[36:37], v[42:43], v[36:37]
	s_nop 0
	v_pk_add_f32 v[36:37], v[40:41], v[36:37]
	ds_bpermute_b32 v38, v181, v36
	ds_bpermute_b32 v39, v181, v37
	s_waitcnt lgkmcnt(0)
	v_pk_add_f32 v[36:37], v[36:37], v[38:39]
	ds_bpermute_b32 v38, v180, v36
	ds_bpermute_b32 v39, v180, v37
	s_and_saveexec_b64 s[0:1], s[40:41]
	s_cbranch_execz .LBB0_2389
	v_lshl_add_u64 v[40:41], s[52:53], 0, v[52:53]
	v_lshl_add_u64 v[40:41], s[68:69], 2, v[40:41]
	s_waitcnt lgkmcnt(0)
	v_pk_add_f32 v[36:37], v[36:37], v[38:39]
	global_store_dwordx2 v[40:41], v[36:37], off
.LBB0_2389:
	s_or_b64 exec, exec, s[0:1]
	v_add_u32_e32 v46, 0xa0, v146
	v_ashrrev_i32_e32 v47, 31, v46
	v_lshlrev_b64 v[36:37], 7, v[46:47]
	v_lshl_add_u64 v[42:43], v[134:135], 0, v[36:37]
	s_waitcnt lgkmcnt(0)
	s_waitcnt vmcnt(21)
	v_mov_b64_e32 v[38:39], v[190:191]
	v_mov_b64_e32 v[40:41], v[192:193]
	s_nop 0
	s_waitcnt vmcnt(20)
	v_mov_b64_e32 v[42:43], v[194:195]
	v_mov_b64_e32 v[44:45], v[196:197]
	s_waitcnt lgkmcnt(0)
	v_pk_add_f32 v[38:39], v[38:39], v[40:41]
	s_waitcnt lgkmcnt(0)
	v_pk_add_f32 v[42:43], v[42:43], v[44:45]
	s_nop 0
	v_pk_add_f32 v[38:39], v[42:43], v[38:39]
	ds_bpermute_b32 v40, v181, v38
	ds_bpermute_b32 v41, v181, v39
	s_waitcnt lgkmcnt(0)
	v_pk_add_f32 v[38:39], v[38:39], v[40:41]
	ds_bpermute_b32 v40, v180, v38
	ds_bpermute_b32 v41, v180, v39
	s_waitcnt lgkmcnt(0)
	v_pk_add_f32 v[38:39], v[38:39], v[40:41]
	s_nop 0
	v_pk_mul_f32 v[48:49], v[38:39], s[82:83] op_sel_hi:[1,0]
	v_lshlrev_b64 v[38:39], 11, v[46:47]
	v_lshl_add_u64 v[38:39], s[70:71], 0, v[38:39]
	v_lshl_add_u64 v[44:45], v[144:145], 1, v[38:39]
	s_waitcnt vmcnt(19)
	v_mov_b64_e32 v[38:39], v[198:199]
	v_fma_f32 v3, -v48, v48, v49
	v_max_f32_e32 v3, 0, v3
	v_add_f32_e32 v3, 0x3727c5ac, v3
	v_rsq_f32_e32 v50, v3
	s_waitcnt lgkmcnt(0)
	v_lshlrev_b32_e32 v3, 16, v38
	v_and_b32_e32 v38, 0xffff0000, v38
	v_lshlrev_b32_e32 v40, 16, v39
	v_and_b32_e32 v41, 0xffff0000, v39
	v_sub_f32_e32 v39, v38, v48
	v_sub_f32_e32 v38, v3, v48
	v_sub_f32_e32 v41, v41, v48
	v_sub_f32_e32 v40, v40, v48
	v_pk_mul_f32 v[42:43], v[40:41], v[50:51] op_sel_hi:[1,0]
	v_pk_mul_f32 v[46:47], v[38:39], v[50:51] op_sel_hi:[1,0]
	ds_read_b128 v[38:41], v244
	ds_read_b128 v[52:55], v244 offset:256
	s_waitcnt lgkmcnt(0)
	v_pk_fma_f32 v[40:41], v[40:41], v[42:43], v[54:55]
	s_nop 0
	v_pk_fma_f32 v[34:35], v[40:41], s[72:73], v[34:35] op_sel_hi:[1,0,1]
	s_waitcnt vmcnt(18)
	v_mov_b64_e32 v[40:41], v[200:201]
	v_pk_fma_f32 v[38:39], v[38:39], v[46:47], v[52:53]
	s_waitcnt lgkmcnt(0)
	v_lshlrev_b32_e32 v3, 16, v40
	v_pk_fma_f32 v[32:33], v[38:39], s[72:73], v[32:33] op_sel_hi:[1,0,1]
	v_cvt_pk_bf16_f32 v39, v34, v35
	v_cvt_pk_bf16_f32 v38, v32, v33
	v_and_b32_e32 v33, 0xffff0000, v40
	v_lshlrev_b32_e32 v35, 16, v41
	v_and_b32_e32 v42, 0xffff0000, v41
	global_store_dwordx2 v[44:45], v[38:39], off
	v_sub_f32_e32 v41, v33, v48
	v_sub_f32_e32 v40, v3, v48
	v_sub_f32_e32 v43, v42, v48
	v_sub_f32_e32 v42, v35, v48
	v_pk_mul_f32 v[46:47], v[50:51], v[42:43] op_sel_hi:[0,1]
	v_pk_mul_f32 v[56:57], v[50:51], v[40:41] op_sel_hi:[0,1]
	ds_read_b128 v[40:43], v244 offset:64
	ds_read_b128 v[52:55], v244 offset:320
	v_and_b32_e32 v34, 0xffff0000, v38
	v_lshlrev_b32_e32 v32, 16, v39
	s_waitcnt lgkmcnt(0)
	v_pk_fma_f32 v[40:41], v[40:41], v[56:57], v[52:53]
	s_nop 0
	v_pk_fma_f32 v[28:29], v[40:41], s[72:73], v[28:29] op_sel_hi:[1,0,1]
	s_waitcnt vmcnt(17)
	v_mov_b64_e32 v[40:41], v[202:203]
	v_pk_fma_f32 v[42:43], v[42:43], v[46:47], v[54:55]
	v_cvt_pk_bf16_f32 v46, v28, v29
	v_pk_fma_f32 v[30:31], v[42:43], s[72:73], v[30:31] op_sel_hi:[1,0,1]
	s_waitcnt lgkmcnt(0)
; __device__ __forceinline__ u32x2 pk4(f32x4 v) { u32x2 r; r.x = pk2(v.x, v.y); r.y = pk2(v.z, v.w); return r; }
;     __device__ __forceinline__ void operator()(const f32x4 (&acc)[2][2][4][2], const pg8::Unit& u, int wr, int wc, int fr, int fq) const {
;     ...
;                 for (int bj = 0; bj < 2; ++bj)
; #pragma unroll
;                     for (int n = 0; n < 2; ++n) {
;                         const int col = u.pn * 256 + bj * 128 + wc * 32 + n * 16 + fq * 4;
;                         const u32x2 raw = *(const u32x2*)(src + (size_t)row * DM + col);
;                         f32x4 x = (f32x4){bflo(raw.x), bfhi(raw.x), bflo(raw.y), bfhi(raw.y)};
;                         if (ln) x = (x - mu) * rs * *(const f32x4*)(g + col) + *(const f32x4*)(b + col);
;                         const u32x2 pz = pk4(x * ALPHA + acc[ai][bj][m][n]);
;                         *(u32x2*)(dst + (size_t)row * DM + col) = pz;
;                         const float z0 = bflo(pz.x), z1 = bfhi(pz.x), z2 = bflo(pz.y), z3 = bfhi(pz.y);
;                         s1 += (z0 + z1) + (z2 + z3); s2 += (z0 * z0 + z1 * z1) + (z2 * z2 + z3 * z3);
;                     }
;                 s1 += __shfl_xor(s1, 16); s2 += __shfl_xor(s2, 16); s1 += __shfl_xor(s1, 32); s2 += __shfl_xor(s2, 32);
;                 if (fq == 0) { float* p = stm_n + (size_t)row * 32 + (u.pn * 4 + wc) * 2; p[0] = s1; p[1] = s2; }
	v_lshlrev_b32_e32 v3, 16, v40
	v_cvt_pk_bf16_f32 v47, v30, v31
	v_lshlrev_b32_e32 v30, 16, v47
	v_and_b32_e32 v31, 0xffff0000, v47
	v_mul_f32_e32 v28, v30, v30
	v_pk_fma_f32 v[28:29], v[30:31], v[30:31], v[28:29] op_sel_hi:[1,1,0]
	v_lshlrev_b32_e32 v33, 16, v41
	v_and_b32_e32 v28, 0xffff0000, v40
	v_and_b32_e32 v35, 0xffff0000, v41
	global_store_dwordx2 v[44:45], v[46:47], off offset:32
	v_sub_f32_e32 v41, v28, v48
	v_sub_f32_e32 v40, v3, v48
	v_sub_f32_e32 v43, v35, v48
	v_sub_f32_e32 v42, v33, v48
	v_pk_mul_f32 v[56:57], v[50:51], v[42:43] op_sel_hi:[0,1]
	v_pk_mul_f32 v[58:59], v[50:51], v[40:41] op_sel_hi:[0,1]
	ds_read_b128 v[40:43], v244 offset:128
	ds_read_b128 v[52:55], v244 offset:384
	v_and_b32_e32 v47, 0xffff0000, v46
	s_waitcnt lgkmcnt(0)
	v_pk_fma_f32 v[40:41], v[40:41], v[58:59], v[52:53]
	s_waitcnt vmcnt(16)
	v_mov_b64_e32 v[52:53], v[204:205]
	v_pk_fma_f32 v[42:43], v[42:43], v[56:57], v[54:55]
	v_pk_fma_f32 v[24:25], v[40:41], s[72:73], v[24:25] op_sel_hi:[1,0,1]
	v_pk_fma_f32 v[26:27], v[42:43], s[72:73], v[26:27] op_sel_hi:[1,0,1]
	v_cvt_pk_bf16_f32 v24, v24, v25
	v_cvt_pk_bf16_f32 v25, v26, v27
	global_store_dwordx2 v[44:45], v[24:25], off offset:256
	v_lshlrev_b32_e32 v40, 16, v24
	v_and_b32_e32 v42, 0xffff0000, v24
	v_lshlrev_b32_e32 v24, 16, v25
	v_and_b32_e32 v26, 0xffff0000, v25
	v_mul_f32_e32 v41, v40, v40
	v_mul_f32_e32 v43, v42, v42
	v_mul_f32_e32 v25, v24, v24
	v_mul_f32_e32 v27, v26, v26
	v_pk_add_f32 v[24:25], v[24:25], v[26:27]
	s_waitcnt lgkmcnt(0)
	v_lshlrev_b32_e32 v3, 16, v52
	v_and_b32_e32 v28, 0xffff0000, v52
	v_lshlrev_b32_e32 v33, 16, v53
	v_and_b32_e32 v35, 0xffff0000, v53
	v_sub_f32_e32 v53, v28, v48
	v_sub_f32_e32 v52, v3, v48
	v_sub_f32_e32 v49, v35, v48
	v_sub_f32_e32 v48, v33, v48
	v_pk_mul_f32 v[48:49], v[50:51], v[48:49] op_sel_hi:[0,1]
	v_pk_mul_f32 v[50:51], v[50:51], v[52:53] op_sel_hi:[0,1]
	ds_read_b128 v[52:55], v244 offset:192
	ds_read_b128 v[56:59], v244 offset:448
	v_mov_b32_e32 v33, v47
	v_mov_b32_e32 v3, v29
	s_waitcnt lgkmcnt(0)
	v_pk_fma_f32 v[50:51], v[52:53], v[50:51], v[56:57]
	s_nop 0
	v_pk_fma_f32 v[20:21], v[50:51], s[72:73], v[20:21] op_sel_hi:[1,0,1]
	v_lshlrev_b32_e32 v51, 16, v46
	v_lshlrev_b32_e32 v50, 16, v38
	v_mov_b32_e32 v35, v51
	v_pk_fma_f32 v[48:49], v[54:55], v[48:49], v[58:59]
	v_pk_mul_f32 v[52:53], v[50:51], v[50:51]
	v_pk_mul_f32 v[54:55], v[34:35], v[34:35]
	v_and_b32_e32 v46, 0xffff0000, v39
	v_pk_mul_f32 v[38:39], v[32:33], v[32:33]
	v_pk_mul_f32 v[56:57], v[46:47], v[46:47]
	v_pk_mov_b32 v[58:59], v[50:51], v[52:53] op_sel:[1,0]
	v_pk_mov_b32 v[54:55], v[46:47], v[54:55] op_sel:[1,0]
	v_pk_add_f32 v[34:35], v[50:51], v[34:35]
	v_pk_add_f32 v[32:33], v[46:47], v[32:33]
	v_pk_fma_f32 v[22:23], v[48:49], s[72:73], v[22:23] op_sel_hi:[1,0,1]
	v_pk_add_f32 v[54:55], v[58:59], v[54:55]
	v_mov_b32_e32 v58, v30
	v_mov_b32_e32 v59, v38
	v_pk_mov_b32 v[30:31], v[30:31], v[56:57] op_sel:[1,0]
	v_mov_b32_e32 v35, v53
	v_mov_b32_e32 v33, v57
	v_cvt_pk_bf16_f32 v20, v20, v21
	v_cvt_pk_bf16_f32 v21, v22, v23
	v_pk_add_f32 v[30:31], v[58:59], v[30:31]
	v_pk_add_f32 v[32:33], v[34:35], v[32:33]
	global_store_dwordx2 v[44:45], v[20:21], off offset:288
	v_lshlrev_b32_e32 v44, 16, v20
	v_and_b32_e32 v48, 0xffff0000, v20
	v_lshlrev_b32_e32 v20, 16, v21
	v_and_b32_e32 v22, 0xffff0000, v21
	v_pk_add_f32 v[30:31], v[54:55], v[30:31]
	v_pk_add_f32 v[28:29], v[32:33], v[2:3]
	v_mul_f32_e32 v45, v44, v44
	v_mul_f32_e32 v49, v48, v48
	v_mul_f32_e32 v21, v20, v20
	v_mul_f32_e32 v23, v22, v22
	v_pk_add_f32 v[28:29], v[30:31], v[28:29]
	v_pk_add_f32 v[30:31], v[40:41], v[42:43]
	v_pk_add_f32 v[26:27], v[44:45], v[48:49]
	v_pk_add_f32 v[24:25], v[30:31], v[24:25]
	v_pk_add_f32 v[20:21], v[20:21], v[22:23]
	v_pk_add_f32 v[24:25], v[28:29], v[24:25]
	v_pk_add_f32 v[20:21], v[26:27], v[20:21]
	s_nop 0
	v_pk_add_f32 v[20:21], v[24:25], v[20:21]
	ds_bpermute_b32 v22, v181, v20
	ds_bpermute_b32 v23, v181, v21
	s_waitcnt lgkmcnt(0)
	v_pk_add_f32 v[20:21], v[20:21], v[22:23]
	ds_bpermute_b32 v22, v180, v20
	ds_bpermute_b32 v23, v180, v21
	s_and_saveexec_b64 s[0:1], s[40:41]
	s_cbranch_execz .LBB0_2391
	v_lshl_add_u64 v[24:25], s[52:53], 0, v[36:37]
	v_lshl_add_u64 v[24:25], s[68:69], 2, v[24:25]
	s_waitcnt lgkmcnt(0)
	v_pk_add_f32 v[20:21], v[20:21], v[22:23]
	global_store_dwordx2 v[24:25], v[20:21], off
; __device__ __forceinline__ u32x2 pk4(f32x4 v) { u32x2 r; r.x = pk2(v.x, v.y); r.y = pk2(v.z, v.w); return r; }
; __device__ __forceinline__ void stats_main(const float* stm, int row, int fq, float& mu, float& rs) {
;     const f32x4* p = (const f32x4*)(stm + (size_t)row * 32 + fq * 8);
;     const f32x4 a = p[0], b = p[1];
;     float s1 = (a.x + a.z) + (b.x + b.z), s2 = (a.y + a.w) + (b.y + b.w);
;     s1 += __shfl_xor(s1, 16); s2 += __shfl_xor(s2, 16); s1 += __shfl_xor(s1, 32); s2 += __shfl_xor(s2, 32);
;     mu = s1 * (1.f / DM); rs = __builtin_amdgcn_rsqf(fmaxf(s2 * (1.f / DM) - mu * mu, 0.f) + LN_EPS);
;     __device__ __forceinline__ void operator()(const f32x4 (&acc)[2][2][4][2], const pg8::Unit& u, int wr, int wc, int fr, int fq) const {
;     ...
;                 const int row = u.pm * 256 + ai * 128 + wr * 64 + m * 16 + fr;
;                 float mu = 0.f, rs = 1.f; if (ln) stats_main(stm_p, row, fq, mu, rs);
;                 float s1 = 0.f, s2 = 0.f;
; #pragma unroll
;                 for (int bj = 0; bj < 2; ++bj)
; #pragma unroll
;                     for (int n = 0; n < 2; ++n) {
;                         const int col = u.pn * 256 + bj * 128 + wc * 32 + n * 16 + fq * 4;
;                         const u32x2 raw = *(const u32x2*)(src + (size_t)row * DM + col);
;                         f32x4 x = (f32x4){bflo(raw.x), bfhi(raw.x), bflo(raw.y), bfhi(raw.y)};
;                         if (ln) x = (x - mu) * rs * *(const f32x4*)(g + col) + *(const f32x4*)(b + col);
;                         const u32x2 pz = pk4(x * ALPHA + acc[ai][bj][m][n]);
;                         *(u32x2*)(dst + (size_t)row * DM + col) = pz;
;                         const float z0 = bflo(pz.x), z1 = bfhi(pz.x), z2 = bflo(pz.y), z3 = bfhi(pz.y);
;                         s1 += (z0 + z1) + (z2 + z3); s2 += (z0 * z0 + z1 * z1) + (z2 * z2 + z3 * z3);
.LBB0_2391:
	s_or_b64 exec, exec, s[0:1]
	v_add_u32_e32 v30, 0xb0, v146
	v_ashrrev_i32_e32 v31, 31, v30
	v_lshlrev_b64 v[20:21], 7, v[30:31]
	v_lshl_add_u64 v[26:27], v[134:135], 0, v[20:21]
	s_waitcnt lgkmcnt(0)
	s_waitcnt vmcnt(15)
	v_mov_b64_e32 v[22:23], v[206:207]
	v_mov_b64_e32 v[24:25], v[208:209]
	s_nop 0
	s_waitcnt vmcnt(14)
	v_mov_b64_e32 v[26:27], v[214:215]
	v_mov_b64_e32 v[28:29], v[216:217]
	s_waitcnt lgkmcnt(0)
	v_pk_add_f32 v[22:23], v[22:23], v[24:25]
	s_waitcnt lgkmcnt(0)
	v_pk_add_f32 v[26:27], v[26:27], v[28:29]
	s_nop 0
	v_pk_add_f32 v[22:23], v[26:27], v[22:23]
	ds_bpermute_b32 v24, v181, v22
	ds_bpermute_b32 v25, v181, v23
	s_waitcnt lgkmcnt(0)
	v_pk_add_f32 v[22:23], v[22:23], v[24:25]
	ds_bpermute_b32 v24, v180, v22
	ds_bpermute_b32 v25, v180, v23
	s_waitcnt lgkmcnt(0)
	v_pk_add_f32 v[22:23], v[22:23], v[24:25]
	s_nop 0
	v_pk_mul_f32 v[32:33], v[22:23], s[82:83] op_sel_hi:[1,0]
	v_lshlrev_b64 v[22:23], 11, v[30:31]
	v_lshl_add_u64 v[22:23], s[70:71], 0, v[22:23]
	v_lshl_add_u64 v[28:29], v[144:145], 1, v[22:23]
	s_waitcnt vmcnt(13)
	v_mov_b64_e32 v[22:23], v[234:235]
	v_fma_f32 v3, -v32, v32, v33
	v_max_f32_e32 v3, 0, v3
	v_add_f32_e32 v3, 0x3727c5ac, v3
	v_rsq_f32_e32 v34, v3
	s_waitcnt lgkmcnt(0)
	v_lshlrev_b32_e32 v3, 16, v22
	v_and_b32_e32 v22, 0xffff0000, v22
	v_lshlrev_b32_e32 v24, 16, v23
	v_and_b32_e32 v25, 0xffff0000, v23
	v_sub_f32_e32 v23, v22, v32
	v_sub_f32_e32 v22, v3, v32
	v_sub_f32_e32 v25, v25, v32
	v_sub_f32_e32 v24, v24, v32
	v_pk_mul_f32 v[26:27], v[24:25], v[34:35] op_sel_hi:[1,0]
	v_pk_mul_f32 v[30:31], v[22:23], v[34:35] op_sel_hi:[1,0]
	ds_read_b128 v[22:25], v244
	ds_read_b128 v[36:39], v244 offset:256
	s_waitcnt lgkmcnt(0)
	v_pk_fma_f32 v[24:25], v[24:25], v[26:27], v[38:39]
	s_nop 0
	v_pk_fma_f32 v[18:19], v[24:25], s[72:73], v[18:19] op_sel_hi:[1,0,1]
	s_waitcnt vmcnt(12)
	v_mov_b64_e32 v[24:25], v[236:237]
	v_pk_fma_f32 v[22:23], v[22:23], v[30:31], v[36:37]
	s_waitcnt lgkmcnt(0)
	v_lshlrev_b32_e32 v3, 16, v24
	v_pk_fma_f32 v[16:17], v[22:23], s[72:73], v[16:17] op_sel_hi:[1,0,1]
	v_cvt_pk_bf16_f32 v23, v18, v19
	v_cvt_pk_bf16_f32 v22, v16, v17
	v_and_b32_e32 v17, 0xffff0000, v24
	v_lshlrev_b32_e32 v19, 16, v25
	v_and_b32_e32 v26, 0xffff0000, v25
	global_store_dwordx2 v[28:29], v[22:23], off
	v_sub_f32_e32 v25, v17, v32
	v_sub_f32_e32 v24, v3, v32
	v_sub_f32_e32 v27, v26, v32
	v_sub_f32_e32 v26, v19, v32
	v_pk_mul_f32 v[30:31], v[34:35], v[26:27] op_sel_hi:[0,1]
	v_pk_mul_f32 v[40:41], v[34:35], v[24:25] op_sel_hi:[0,1]
	ds_read_b128 v[24:27], v244 offset:64
	ds_read_b128 v[36:39], v244 offset:320
	v_and_b32_e32 v18, 0xffff0000, v22
	v_lshlrev_b32_e32 v16, 16, v23
	s_waitcnt lgkmcnt(0)
	v_pk_fma_f32 v[24:25], v[24:25], v[40:41], v[36:37]
	s_nop 0
	v_pk_fma_f32 v[12:13], v[24:25], s[72:73], v[12:13] op_sel_hi:[1,0,1]
	s_waitcnt vmcnt(11)
	v_mov_b64_e32 v[24:25], v[238:239]
	v_pk_fma_f32 v[26:27], v[26:27], v[30:31], v[38:39]
	v_cvt_pk_bf16_f32 v30, v12, v13
	v_pk_fma_f32 v[14:15], v[26:27], s[72:73], v[14:15] op_sel_hi:[1,0,1]
	s_waitcnt lgkmcnt(0)
	v_lshlrev_b32_e32 v3, 16, v24
	v_cvt_pk_bf16_f32 v31, v14, v15
	v_lshlrev_b32_e32 v14, 16, v31
	v_and_b32_e32 v15, 0xffff0000, v31
	v_mul_f32_e32 v12, v14, v14
	v_pk_fma_f32 v[12:13], v[14:15], v[14:15], v[12:13] op_sel_hi:[1,1,0]
	v_lshlrev_b32_e32 v17, 16, v25
	v_and_b32_e32 v12, 0xffff0000, v24
	v_and_b32_e32 v19, 0xffff0000, v25
	global_store_dwordx2 v[28:29], v[30:31], off offset:32
	v_sub_f32_e32 v25, v12, v32
	v_sub_f32_e32 v24, v3, v32
	v_sub_f32_e32 v27, v19, v32
	v_sub_f32_e32 v26, v17, v32
	v_pk_mul_f32 v[40:41], v[34:35], v[26:27] op_sel_hi:[0,1]
	v_pk_mul_f32 v[42:43], v[34:35], v[24:25] op_sel_hi:[0,1]
	ds_read_b128 v[24:27], v244 offset:128
	ds_read_b128 v[36:39], v244 offset:384
	v_and_b32_e32 v31, 0xffff0000, v30
	s_waitcnt lgkmcnt(0)
; __device__ __forceinline__ u32x2 pk4(f32x4 v) { u32x2 r; r.x = pk2(v.x, v.y); r.y = pk2(v.z, v.w); return r; }
;     __device__ __forceinline__ void operator()(const f32x4 (&acc)[2][2][4][2], const pg8::Unit& u, int wr, int wc, int fr, int fq) const {
;     ...
;                 for (int bj = 0; bj < 2; ++bj)
; #pragma unroll
;                     for (int n = 0; n < 2; ++n) {
;                         const int col = u.pn * 256 + bj * 128 + wc * 32 + n * 16 + fq * 4;
;                         const u32x2 raw = *(const u32x2*)(src + (size_t)row * DM + col);
;                         f32x4 x = (f32x4){bflo(raw.x), bfhi(raw.x), bflo(raw.y), bfhi(raw.y)};
;                         if (ln) x = (x - mu) * rs * *(const f32x4*)(g + col) + *(const f32x4*)(b + col);
;                         const u32x2 pz = pk4(x * ALPHA + acc[ai][bj][m][n]);
;                         *(u32x2*)(dst + (size_t)row * DM + col) = pz;
;                         const float z0 = bflo(pz.x), z1 = bfhi(pz.x), z2 = bflo(pz.y), z3 = bfhi(pz.y);
;                         s1 += (z0 + z1) + (z2 + z3); s2 += (z0 * z0 + z1 * z1) + (z2 * z2 + z3 * z3);
;                     }
;                 s1 += __shfl_xor(s1, 16); s2 += __shfl_xor(s2, 16); s1 += __shfl_xor(s1, 32); s2 += __shfl_xor(s2, 32);
;                 if (fq == 0) { float* p = stm_n + (size_t)row * 32 + (u.pn * 4 + wc) * 2; p[0] = s1; p[1] = s2; }
	v_pk_fma_f32 v[24:25], v[24:25], v[42:43], v[36:37]
	s_waitcnt vmcnt(10)
	v_mov_b64_e32 v[36:37], v[240:241]
	v_pk_fma_f32 v[26:27], v[26:27], v[40:41], v[38:39]
	v_pk_fma_f32 v[8:9], v[24:25], s[72:73], v[8:9] op_sel_hi:[1,0,1]
	v_pk_fma_f32 v[10:11], v[26:27], s[72:73], v[10:11] op_sel_hi:[1,0,1]
	v_cvt_pk_bf16_f32 v8, v8, v9
	v_cvt_pk_bf16_f32 v9, v10, v11
	global_store_dwordx2 v[28:29], v[8:9], off offset:256
	v_lshlrev_b32_e32 v24, 16, v8
	v_and_b32_e32 v26, 0xffff0000, v8
	v_lshlrev_b32_e32 v8, 16, v9
	v_and_b32_e32 v10, 0xffff0000, v9
	v_mul_f32_e32 v25, v24, v24
	v_mul_f32_e32 v27, v26, v26
	v_mul_f32_e32 v9, v8, v8
	v_mul_f32_e32 v11, v10, v10
	v_pk_add_f32 v[8:9], v[8:9], v[10:11]
	s_waitcnt lgkmcnt(0)
	v_lshlrev_b32_e32 v3, 16, v36
	v_and_b32_e32 v12, 0xffff0000, v36
	v_lshlrev_b32_e32 v17, 16, v37
	v_and_b32_e32 v19, 0xffff0000, v37
	v_sub_f32_e32 v37, v12, v32
	v_sub_f32_e32 v36, v3, v32
	v_sub_f32_e32 v33, v19, v32
	v_sub_f32_e32 v32, v17, v32
	v_pk_mul_f32 v[32:33], v[34:35], v[32:33] op_sel_hi:[0,1]
	v_pk_mul_f32 v[34:35], v[34:35], v[36:37] op_sel_hi:[0,1]
	ds_read_b128 v[36:39], v244 offset:192
	ds_read_b128 v[40:43], v244 offset:448
	v_mov_b32_e32 v17, v31
	v_mov_b32_e32 v3, v13
	s_waitcnt lgkmcnt(0)
	v_pk_fma_f32 v[34:35], v[36:37], v[34:35], v[40:41]
	s_nop 0
	v_pk_fma_f32 v[4:5], v[34:35], s[72:73], v[4:5] op_sel_hi:[1,0,1]
	v_lshlrev_b32_e32 v35, 16, v30
	v_lshlrev_b32_e32 v34, 16, v22
	v_mov_b32_e32 v19, v35
	v_pk_fma_f32 v[32:33], v[38:39], v[32:33], v[42:43]
	v_pk_mul_f32 v[36:37], v[34:35], v[34:35]
	v_pk_mul_f32 v[38:39], v[18:19], v[18:19]
	v_and_b32_e32 v30, 0xffff0000, v23
	v_pk_mul_f32 v[22:23], v[16:17], v[16:17]
	v_pk_mul_f32 v[40:41], v[30:31], v[30:31]
	v_pk_mov_b32 v[42:43], v[34:35], v[36:37] op_sel:[1,0]
	v_pk_mov_b32 v[38:39], v[30:31], v[38:39] op_sel:[1,0]
	v_pk_add_f32 v[18:19], v[34:35], v[18:19]
	v_pk_add_f32 v[16:17], v[30:31], v[16:17]
	v_pk_fma_f32 v[6:7], v[32:33], s[72:73], v[6:7] op_sel_hi:[1,0,1]
	v_pk_add_f32 v[38:39], v[42:43], v[38:39]
	v_mov_b32_e32 v42, v14
	v_mov_b32_e32 v43, v22
	v_pk_mov_b32 v[14:15], v[14:15], v[40:41] op_sel:[1,0]
	v_mov_b32_e32 v19, v37
	v_mov_b32_e32 v17, v41
	v_cvt_pk_bf16_f32 v4, v4, v5
	v_cvt_pk_bf16_f32 v5, v6, v7
	v_pk_add_f32 v[14:15], v[42:43], v[14:15]
	v_pk_add_f32 v[16:17], v[18:19], v[16:17]
	global_store_dwordx2 v[28:29], v[4:5], off offset:288
	v_lshlrev_b32_e32 v28, 16, v4
	v_and_b32_e32 v32, 0xffff0000, v4
	v_lshlrev_b32_e32 v4, 16, v5
	v_and_b32_e32 v6, 0xffff0000, v5
	v_pk_add_f32 v[14:15], v[38:39], v[14:15]
	v_pk_add_f32 v[12:13], v[16:17], v[2:3]
	v_mul_f32_e32 v29, v28, v28
	v_mul_f32_e32 v33, v32, v32
	v_mul_f32_e32 v5, v4, v4
	v_mul_f32_e32 v7, v6, v6
	v_pk_add_f32 v[12:13], v[14:15], v[12:13]
	v_pk_add_f32 v[14:15], v[24:25], v[26:27]
	v_pk_add_f32 v[10:11], v[28:29], v[32:33]
	v_pk_add_f32 v[8:9], v[14:15], v[8:9]
	v_pk_add_f32 v[4:5], v[4:5], v[6:7]
	v_pk_add_f32 v[8:9], v[12:13], v[8:9]
	v_pk_add_f32 v[4:5], v[10:11], v[4:5]
	s_nop 0
	v_pk_add_f32 v[4:5], v[8:9], v[4:5]
	ds_bpermute_b32 v6, v181, v4
	ds_bpermute_b32 v7, v181, v5
	s_waitcnt lgkmcnt(0)
	v_pk_add_f32 v[4:5], v[4:5], v[6:7]
	ds_bpermute_b32 v6, v180, v4
	ds_bpermute_b32 v7, v180, v5
	s_and_saveexec_b64 s[0:1], s[40:41]
	s_cbranch_execz .LBB0_2393
	v_lshl_add_u64 v[8:9], s[52:53], 0, v[20:21]
	v_lshl_add_u64 v[8:9], s[68:69], 2, v[8:9]
	s_waitcnt lgkmcnt(0)
	v_pk_add_f32 v[4:5], v[4:5], v[6:7]
	global_store_dwordx2 v[8:9], v[4:5], off
